# staging wave found critical: row-value transposition moved back to scan waves (4x ds_read_u16), staging wave writes one b64; drop load-offset copies
# speedup vs baseline: 1.0248x; 1.0056x over previous
.LBB0_182:
	s_min_u32 s4, s37, 0x1030
	s_lshl_b32 s4, s4, 2
	s_cmp_gt_u32 s37, 48
	s_cselect_b32 s5, 0xffffff3c, 60
	s_cselect_b32 s23, s10, s33
	s_cselect_b32 s37, s46, 0xfc
	s_add_i32 s44, s4, s5
	s_sub_i32 s37, s37, s44
	s_waitcnt vmcnt(46)
	v_cvt_f32_f16_sdwa v123, v90 dst_sel:DWORD dst_unused:UNUSED_PAD src0_sel:WORD_1
	v_cvt_f32_f16_sdwa v125, v91 dst_sel:DWORD dst_unused:UNUSED_PAD src0_sel:WORD_1
	v_cvt_f32_f16_e32 v122, v90
	v_cvt_f32_f16_e32 v124, v91
	s_and_b64 s[4:5], s[42:43], exec
	s_waitcnt vmcnt(44)
	v_cvt_f32_f16_sdwa v127, v102 dst_sel:DWORD dst_unused:UNUSED_PAD src0_sel:WORD_1
	v_cvt_f32_f16_sdwa v133, v103 dst_sel:DWORD dst_unused:UNUSED_PAD src0_sel:WORD_1
	v_cvt_f32_f16_e32 v126, v102
	v_cvt_f32_f16_e32 v132, v103
	s_cselect_b32 s4, s44, s37
	s_add_i32 s4, s4, s23
	s_ashr_i32 s5, s4, 31
	v_pk_fma_f32 v[102:103], v[2:3], v[124:125], v[92:93]
	v_pk_fma_f32 v[122:123], v[0:1], v[122:123], v[94:95]
	s_lshl_b64 s[4:5], s[4:5], 11
	v_pk_mul_f32 v[102:103], v[102:103], v[132:133]
	v_pk_mul_f32 v[126:127], v[122:123], v[126:127]
	s_add_u32 s44, s87, s4
	v_pk_mul_f16 v123, v91, v35
	v_pk_mul_f16 v122, v90, v34
	v_cvt_pk_f16_f32 v125, v102, v103
	v_cvt_pk_f16_f32 v124, v126, v127
	ds_write_b128 v120, v[32:35] offset:21504
	ds_write_b128 v120, v[122:125] offset:22528
	s_waitcnt vmcnt(42)
	v_add_u32_e32 v185, v121, v186
	ds_write_b64 v185, v[100:101] offset:23552
	ds_write_b64 v121, v[104:105] offset:24064
	v_mov_b32_e32 v32, s22
	s_addc_u32 s45, s35, s5
	s_waitcnt lgkmcnt(0)
	ds_write_b32 v161, v32 offset:49152
	global_load_dwordx2 v[32:33], v119, s[44:45]
	s_add_u32 s44, s85, s4
	s_addc_u32 s45, s86, s5
	global_load_dwordx2 v[90:91], v119, s[44:45]
	s_add_u32 s44, s8, s4
	s_addc_u32 s45, s84, s5
	global_load_dwordx2 v[34:35], v119, s[44:45]
	s_add_u32 s44, s97, s4
	s_addc_u32 s45, s99, s5
	global_load_dwordx2 v[102:103], v119, s[44:45]
	s_add_u32 s44, s94, s4
	s_addc_u32 s45, s95, s5
	s_add_u32 s4, s0, s4
	s_addc_u32 s5, s1, s5
	global_load_dwordx2 v[100:101], v119, s[44:45]
	s_nop 0
	global_load_dwordx2 v[104:105], v119, s[4:5]
	s_andn2_b64 vcc, exec, s[90:91]
	s_mov_b32 s37, s22
	s_cbranch_vccz .LBB0_242

.LBB0_185:
	s_waitcnt vmcnt(46)
	v_cvt_f32_f16_sdwa v121, v36 dst_sel:DWORD dst_unused:UNUSED_PAD src0_sel:WORD_1
	v_cvt_f32_f16_e32 v120, v36
	s_waitcnt vmcnt(44)
	v_cvt_f32_f16_sdwa v125, v44 dst_sel:DWORD dst_unused:UNUSED_PAD src0_sel:WORD_1
	v_cvt_f32_f16_e32 v124, v44
	s_and_b32 s4, s37, 8
	v_cvt_f32_f16_sdwa v123, v37 dst_sel:DWORD dst_unused:UNUSED_PAD src0_sel:WORD_1
	v_cvt_f32_f16_e32 v122, v37
	s_mulk_i32 s4, 0xc00
	s_add_i32 s4, s4, 16
	v_pk_fma_f32 v[120:121], v[0:1], v[120:121], v[94:95]
	s_or_b32 s23, s37, 1
	s_add_i32 s22, s37, 8
	v_pk_mul_f32 v[120:121], v[120:121], v[124:125]
	s_cmpk_gt_u32 s37, 0x1037
	v_cvt_f32_f16_sdwa v127, v45 dst_sel:DWORD dst_unused:UNUSED_PAD src0_sel:WORD_1
	v_cvt_f32_f16_e32 v126, v45
	v_pk_fma_f32 v[44:45], v[2:3], v[122:123], v[92:93]
	v_pk_mul_f16 v122, v36, v6
	v_cvt_pk_f16_f32 v124, v120, v121
	v_add_u32_e32 v36, s4, v113
	v_add_u32_e32 v121, s4, v111
	s_cselect_b64 s[90:91], -1, 0
	s_lshl_b32 s4, s22, 2
	s_cmpk_lt_u32 s37, 0x1038
	s_cselect_b32 s4, s4, 0x40fc
	s_add_i32 s5, s4, 0xffffff00
	s_min_u32 s44, s5, s4
	s_cmpk_gt_u32 s4, 0xff
	s_movk_i32 s4, 0x3fff
	s_cselect_b32 s4, s4, 0xff
	s_cselect_b32 s45, s10, s33
	s_sub_i32 s4, s4, s44
	s_add_i32 vcc_lo, s4, -3
	s_and_b64 s[4:5], s[42:43], exec
	s_cselect_b32 s4, s44, vcc_lo
	s_add_i32 s4, s4, s45
	s_ashr_i32 s5, s4, 31
	s_lshl_b64 s[4:5], s[4:5], 11
	v_pk_mul_f32 v[44:45], v[44:45], v[126:127]
	v_add_u32_e32 v120, v36, v128
	s_add_u32 s44, s87, s4
	v_pk_mul_f16 v123, v37, v7
	v_cvt_pk_f16_f32 v125, v44, v45
	ds_write_b128 v120, v[4:7]
	ds_write_b128 v120, v[122:125] offset:1024
	s_waitcnt vmcnt(42)
	v_add_u32_e32 v185, v121, v186
	ds_write_b64 v185, v[38:39] offset:2048
	ds_write_b64 v121, v[42:43] offset:2560
	v_mov_b32_e32 v4, s23
	s_addc_u32 s45, s35, s5
	s_waitcnt lgkmcnt(0)
	ds_write_b32 v161, v4 offset:49152
	global_load_dwordx2 v[4:5], v119, s[44:45]
	s_add_u32 s44, s85, s4
	s_addc_u32 s45, s86, s5
	global_load_dwordx2 v[36:37], v119, s[44:45]
	s_add_u32 s44, s8, s4
	s_addc_u32 s45, s84, s5
	global_load_dwordx2 v[6:7], v119, s[44:45]
	s_add_u32 s44, s97, s4
	s_addc_u32 s45, s99, s5
	global_load_dwordx2 v[44:45], v119, s[44:45]
	s_add_u32 s44, s94, s4
	s_addc_u32 s45, s95, s5
	s_add_u32 s4, s0, s4
	s_addc_u32 s5, s1, s5
	global_load_dwordx2 v[38:39], v119, s[44:45]
	s_nop 0
	global_load_dwordx2 v[42:43], v119, s[4:5]
	v_cndmask_b32_e64 v122, 0, 1, s[92:93]
	v_cmp_ne_u32_e64 s[44:45], 1, v122
	s_andn2_b64 vcc, exec, s[92:93]
	s_cbranch_vccnz .LBB0_187
	s_add_i32 s4, s37, -14
	s_cmp_ge_i32 s36, s4
	s_cbranch_scc0 .LBB0_203
.LBB0_187:
	s_waitcnt vmcnt(46)
	v_cvt_f32_f16_sdwa v123, v40 dst_sel:DWORD dst_unused:UNUSED_PAD src0_sel:WORD_1
	v_cvt_f32_f16_sdwa v125, v41 dst_sel:DWORD dst_unused:UNUSED_PAD src0_sel:WORD_1
	v_cvt_f32_f16_e32 v122, v40
	v_cvt_f32_f16_e32 v124, v41
	s_waitcnt vmcnt(44)
	v_cvt_f32_f16_sdwa v127, v52 dst_sel:DWORD dst_unused:UNUSED_PAD src0_sel:WORD_1
	v_cvt_f32_f16_sdwa v133, v53 dst_sel:DWORD dst_unused:UNUSED_PAD src0_sel:WORD_1
	v_cvt_f32_f16_e32 v126, v52
	v_cvt_f32_f16_e32 v132, v53
	s_and_b32 s4, s23, 9
	s_mulk_i32 s4, 0xc00
	s_add_i32 s4, s4, 16
	v_pk_fma_f32 v[52:53], v[2:3], v[124:125], v[92:93]
	v_pk_fma_f32 v[122:123], v[0:1], v[122:123], v[94:95]
	v_pk_mul_f32 v[52:53], v[52:53], v[132:133]
	v_pk_mul_f32 v[126:127], v[122:123], v[126:127]
	v_pk_mul_f16 v122, v40, v10
	v_add3_u32 v40, s4, v113, v128
	v_pk_mul_f16 v123, v41, v11
	v_cvt_pk_f16_f32 v125, v52, v53
	v_cvt_pk_f16_f32 v124, v126, v127
	ds_write_b128 v40, v[8:11]
	ds_write_b128 v40, v[122:125] offset:1024
	v_add_u32_e32 v8, s4, v111
	s_or_b32 s4, s37, 2
	s_waitcnt vmcnt(42)
	v_add_u32_e32 v185, v8, v186
	ds_write_b64 v185, v[46:47] offset:2048
	ds_write_b64 v8, v[50:51] offset:2560
	v_mov_b32_e32 v8, s4
	s_min_u32 s4, s37, 0x1036
	s_lshl_b32 s4, s4, 2
	s_cmp_gt_u32 s37, 54
	s_cselect_b32 s5, 0xffffff24, 36
	s_cselect_b32 s23, s10, s33
	s_cselect_b32 s92, s46, 0xfc
	s_add_i32 s93, s4, s5
	s_sub_i32 s92, s92, s93
	s_and_b64 s[4:5], s[42:43], exec
	s_cselect_b32 s4, s93, s92
	s_add_i32 s4, s4, s23
	s_ashr_i32 s5, s4, 31
	s_lshl_b64 s[4:5], s[4:5], 11
	s_add_u32 s92, s87, s4
	s_addc_u32 s93, s35, s5
	s_waitcnt lgkmcnt(0)
	ds_write_b32 v161, v8 offset:49152
	global_load_dwordx2 v[8:9], v119, s[92:93]
	s_add_u32 s92, s85, s4
	s_addc_u32 s93, s86, s5
	global_load_dwordx2 v[40:41], v119, s[92:93]
	s_add_u32 s92, s8, s4
	s_addc_u32 s93, s84, s5
	global_load_dwordx2 v[10:11], v119, s[92:93]
	s_add_u32 s92, s97, s4
	s_addc_u32 s93, s99, s5
	global_load_dwordx2 v[52:53], v119, s[92:93]
	s_add_u32 s92, s94, s4
	s_addc_u32 s93, s95, s5
	s_add_u32 s4, s0, s4
	s_addc_u32 s5, s1, s5
	global_load_dwordx2 v[46:47], v119, s[92:93]
	s_nop 0
	global_load_dwordx2 v[50:51], v119, s[4:5]
	s_and_b64 vcc, exec, s[44:45]
	s_cbranch_vccnz .LBB0_189
	s_add_i32 s4, s37, -13
	s_cmp_ge_i32 s36, s4
	s_cbranch_scc0 .LBB0_206
.LBB0_189:
	s_waitcnt vmcnt(46)
	v_cvt_f32_f16_sdwa v123, v48 dst_sel:DWORD dst_unused:UNUSED_PAD src0_sel:WORD_1
	v_cvt_f32_f16_sdwa v125, v49 dst_sel:DWORD dst_unused:UNUSED_PAD src0_sel:WORD_1
	v_cvt_f32_f16_e32 v122, v48
	v_cvt_f32_f16_e32 v124, v49
	s_waitcnt vmcnt(44)
	v_cvt_f32_f16_sdwa v127, v60 dst_sel:DWORD dst_unused:UNUSED_PAD src0_sel:WORD_1
	v_cvt_f32_f16_sdwa v133, v61 dst_sel:DWORD dst_unused:UNUSED_PAD src0_sel:WORD_1
	v_cvt_f32_f16_e32 v126, v60
	v_cvt_f32_f16_e32 v132, v61
	v_pk_fma_f32 v[60:61], v[2:3], v[124:125], v[92:93]
	v_pk_fma_f32 v[122:123], v[0:1], v[122:123], v[94:95]
	s_or_b32 s4, s37, 3
	v_pk_mul_f32 v[60:61], v[60:61], v[132:133]
	v_pk_mul_f32 v[126:127], v[122:123], v[126:127]
	v_pk_mul_f16 v123, v49, v15
	v_pk_mul_f16 v122, v48, v14
	v_cvt_pk_f16_f32 v125, v60, v61
	v_cvt_pk_f16_f32 v124, v126, v127
	ds_write_b128 v120, v[12:15] offset:6144
	ds_write_b128 v120, v[122:125] offset:7168
	s_waitcnt vmcnt(42)
	v_add_u32_e32 v185, v121, v186
	ds_write_b64 v185, v[54:55] offset:8192
	ds_write_b64 v121, v[58:59] offset:8704
	v_mov_b32_e32 v12, s4
	s_min_u32 s4, s37, 0x1035
	s_lshl_b32 s4, s4, 2
	s_cmp_gt_u32 s37, 53
	s_cselect_b32 s5, 0xffffff28, 40
	s_cselect_b32 s23, s10, s33
	s_cselect_b32 s92, s46, 0xfc
	s_add_i32 s93, s4, s5
	s_sub_i32 s92, s92, s93
	s_and_b64 s[4:5], s[42:43], exec
	s_cselect_b32 s4, s93, s92
	s_add_i32 s4, s4, s23
	s_ashr_i32 s5, s4, 31
	s_lshl_b64 s[4:5], s[4:5], 11
	s_add_u32 s92, s87, s4
	s_addc_u32 s93, s35, s5
	s_waitcnt lgkmcnt(0)
	ds_write_b32 v161, v12 offset:49152
	global_load_dwordx2 v[12:13], v119, s[92:93]
	s_add_u32 s92, s85, s4
	s_addc_u32 s93, s86, s5
	global_load_dwordx2 v[48:49], v119, s[92:93]
	s_add_u32 s92, s8, s4
	s_addc_u32 s93, s84, s5
	global_load_dwordx2 v[14:15], v119, s[92:93]
	s_add_u32 s92, s97, s4
	s_addc_u32 s93, s99, s5
	global_load_dwordx2 v[60:61], v119, s[92:93]
	s_add_u32 s92, s94, s4
	s_addc_u32 s93, s95, s5
	s_add_u32 s4, s0, s4
	s_addc_u32 s5, s1, s5
	global_load_dwordx2 v[54:55], v119, s[92:93]
	s_nop 0
	global_load_dwordx2 v[58:59], v119, s[4:5]
	s_and_b64 vcc, exec, s[44:45]
	s_cbranch_vccnz .LBB0_191
	s_add_i32 s4, s37, -12
	s_cmp_ge_i32 s36, s4
	s_cbranch_scc0 .LBB0_209
.LBB0_191:
	s_waitcnt vmcnt(46)
	v_cvt_f32_f16_sdwa v123, v56 dst_sel:DWORD dst_unused:UNUSED_PAD src0_sel:WORD_1
	v_cvt_f32_f16_sdwa v125, v57 dst_sel:DWORD dst_unused:UNUSED_PAD src0_sel:WORD_1
	v_cvt_f32_f16_e32 v122, v56
	v_cvt_f32_f16_e32 v124, v57
	s_waitcnt vmcnt(44)
	v_cvt_f32_f16_sdwa v127, v66 dst_sel:DWORD dst_unused:UNUSED_PAD src0_sel:WORD_1
	v_cvt_f32_f16_sdwa v133, v67 dst_sel:DWORD dst_unused:UNUSED_PAD src0_sel:WORD_1
	v_cvt_f32_f16_e32 v126, v66
	v_cvt_f32_f16_e32 v132, v67
	v_pk_fma_f32 v[66:67], v[2:3], v[124:125], v[92:93]
	v_pk_fma_f32 v[122:123], v[0:1], v[122:123], v[94:95]
	s_or_b32 s4, s37, 4
	v_pk_mul_f32 v[66:67], v[66:67], v[132:133]
	v_pk_mul_f32 v[126:127], v[122:123], v[126:127]
	v_pk_mul_f16 v123, v57, v19
	v_pk_mul_f16 v122, v56, v18
	v_cvt_pk_f16_f32 v125, v66, v67
	v_cvt_pk_f16_f32 v124, v126, v127
	ds_write_b128 v120, v[16:19] offset:9216
	ds_write_b128 v120, v[122:125] offset:10240
	s_waitcnt vmcnt(42)
	v_add_u32_e32 v185, v121, v186
	ds_write_b64 v185, v[62:63] offset:11264
	ds_write_b64 v121, v[68:69] offset:11776
	v_mov_b32_e32 v16, s4
	s_min_u32 s4, s37, 0x1034
	s_lshl_b32 s4, s4, 2
	s_cmp_gt_u32 s37, 52
	s_cselect_b32 s5, 0xffffff2c, 44
	s_cselect_b32 s23, s10, s33
	s_cselect_b32 s92, s46, 0xfc
	s_add_i32 s93, s4, s5
	s_sub_i32 s92, s92, s93
	s_and_b64 s[4:5], s[42:43], exec
	s_cselect_b32 s4, s93, s92
	s_add_i32 s4, s4, s23
	s_ashr_i32 s5, s4, 31
	s_lshl_b64 s[4:5], s[4:5], 11
	s_add_u32 s92, s87, s4
	s_addc_u32 s93, s35, s5
	s_waitcnt lgkmcnt(0)
	ds_write_b32 v161, v16 offset:49152
	global_load_dwordx2 v[16:17], v119, s[92:93]
	s_add_u32 s92, s85, s4
	s_addc_u32 s93, s86, s5
	global_load_dwordx2 v[56:57], v119, s[92:93]
	s_add_u32 s92, s8, s4
	s_addc_u32 s93, s84, s5
	global_load_dwordx2 v[18:19], v119, s[92:93]
	s_add_u32 s92, s97, s4
	s_addc_u32 s93, s99, s5
	global_load_dwordx2 v[66:67], v119, s[92:93]
	s_add_u32 s92, s94, s4
	s_addc_u32 s93, s95, s5
	s_add_u32 s4, s0, s4
	s_addc_u32 s5, s1, s5
	global_load_dwordx2 v[62:63], v119, s[92:93]
	s_nop 0
	global_load_dwordx2 v[68:69], v119, s[4:5]
	s_and_b64 vcc, exec, s[44:45]
	s_cbranch_vccnz .LBB0_193
	s_add_i32 s4, s37, -11
	s_cmp_ge_i32 s36, s4
	s_cbranch_scc0 .LBB0_212
.LBB0_193:
	s_waitcnt vmcnt(46)
	v_cvt_f32_f16_sdwa v123, v64 dst_sel:DWORD dst_unused:UNUSED_PAD src0_sel:WORD_1
	v_cvt_f32_f16_sdwa v125, v65 dst_sel:DWORD dst_unused:UNUSED_PAD src0_sel:WORD_1
	v_cvt_f32_f16_e32 v122, v64
	v_cvt_f32_f16_e32 v124, v65
	s_waitcnt vmcnt(44)
	v_cvt_f32_f16_sdwa v127, v76 dst_sel:DWORD dst_unused:UNUSED_PAD src0_sel:WORD_1
	v_cvt_f32_f16_sdwa v133, v77 dst_sel:DWORD dst_unused:UNUSED_PAD src0_sel:WORD_1
	v_cvt_f32_f16_e32 v126, v76
	v_cvt_f32_f16_e32 v132, v77
	v_pk_fma_f32 v[76:77], v[2:3], v[124:125], v[92:93]
	v_pk_fma_f32 v[122:123], v[0:1], v[122:123], v[94:95]
	s_or_b32 s4, s37, 5
	v_pk_mul_f32 v[76:77], v[76:77], v[132:133]
	v_pk_mul_f32 v[126:127], v[122:123], v[126:127]
	v_pk_mul_f16 v123, v65, v23
	v_pk_mul_f16 v122, v64, v22
	v_cvt_pk_f16_f32 v125, v76, v77
	v_cvt_pk_f16_f32 v124, v126, v127
	ds_write_b128 v120, v[20:23] offset:12288
	ds_write_b128 v120, v[122:125] offset:13312
	s_waitcnt vmcnt(42)
	v_add_u32_e32 v185, v121, v186
	ds_write_b64 v185, v[70:71] offset:14336
	ds_write_b64 v121, v[74:75] offset:14848
	v_mov_b32_e32 v20, s4
	s_min_u32 s4, s37, 0x1033
	s_lshl_b32 s4, s4, 2
	s_cmp_gt_u32 s37, 51
	s_cselect_b32 s5, 0xffffff30, 48
	s_cselect_b32 s23, s10, s33
	s_cselect_b32 s92, s46, 0xfc
	s_add_i32 s93, s4, s5
	s_sub_i32 s92, s92, s93
	s_and_b64 s[4:5], s[42:43], exec
	s_cselect_b32 s4, s93, s92
	s_add_i32 s4, s4, s23
	s_ashr_i32 s5, s4, 31
	s_lshl_b64 s[4:5], s[4:5], 11
	s_add_u32 s92, s87, s4
	s_addc_u32 s93, s35, s5
	s_waitcnt lgkmcnt(0)
	ds_write_b32 v161, v20 offset:49152
	global_load_dwordx2 v[20:21], v119, s[92:93]
	s_add_u32 s92, s85, s4
	s_addc_u32 s93, s86, s5
	global_load_dwordx2 v[64:65], v119, s[92:93]
	s_add_u32 s92, s8, s4
	s_addc_u32 s93, s84, s5
	global_load_dwordx2 v[22:23], v119, s[92:93]
	s_add_u32 s92, s97, s4
	s_addc_u32 s93, s99, s5
	global_load_dwordx2 v[76:77], v119, s[92:93]
	s_add_u32 s92, s94, s4
	s_addc_u32 s93, s95, s5
	s_add_u32 s4, s0, s4
	s_addc_u32 s5, s1, s5
	global_load_dwordx2 v[70:71], v119, s[92:93]
	s_nop 0
	global_load_dwordx2 v[74:75], v119, s[4:5]
	s_and_b64 vcc, exec, s[44:45]
	s_cbranch_vccnz .LBB0_195
	s_add_i32 s4, s37, -10
	s_cmp_ge_i32 s36, s4
	s_cbranch_scc0 .LBB0_215
.LBB0_195:
	s_waitcnt vmcnt(46)
	v_cvt_f32_f16_sdwa v123, v72 dst_sel:DWORD dst_unused:UNUSED_PAD src0_sel:WORD_1
	v_cvt_f32_f16_sdwa v125, v73 dst_sel:DWORD dst_unused:UNUSED_PAD src0_sel:WORD_1
	v_cvt_f32_f16_e32 v122, v72
	v_cvt_f32_f16_e32 v124, v73
	s_waitcnt vmcnt(44)
	v_cvt_f32_f16_sdwa v127, v84 dst_sel:DWORD dst_unused:UNUSED_PAD src0_sel:WORD_1
	v_cvt_f32_f16_sdwa v133, v85 dst_sel:DWORD dst_unused:UNUSED_PAD src0_sel:WORD_1
	v_cvt_f32_f16_e32 v126, v84
	v_cvt_f32_f16_e32 v132, v85
	v_pk_fma_f32 v[84:85], v[2:3], v[124:125], v[92:93]
	v_pk_fma_f32 v[122:123], v[0:1], v[122:123], v[94:95]
	s_or_b32 s4, s37, 6
	v_pk_mul_f32 v[84:85], v[84:85], v[132:133]
	v_pk_mul_f32 v[126:127], v[122:123], v[126:127]
	v_pk_mul_f16 v123, v73, v27
	v_pk_mul_f16 v122, v72, v26
	v_cvt_pk_f16_f32 v125, v84, v85
	v_cvt_pk_f16_f32 v124, v126, v127
	ds_write_b128 v120, v[24:27] offset:15360
	ds_write_b128 v120, v[122:125] offset:16384
	s_waitcnt vmcnt(42)
	v_add_u32_e32 v185, v121, v186
	ds_write_b64 v185, v[78:79] offset:17408
	ds_write_b64 v121, v[86:87] offset:17920
	v_mov_b32_e32 v24, s4
	s_min_u32 s4, s37, 0x1032
	s_lshl_b32 s4, s4, 2
	s_cmp_gt_u32 s37, 50
	s_cselect_b32 s5, 0xffffff34, 52
	s_cselect_b32 s23, s10, s33
	s_cselect_b32 s92, s46, 0xfc
	s_add_i32 s93, s4, s5
	s_sub_i32 s92, s92, s93
	s_and_b64 s[4:5], s[42:43], exec
	s_cselect_b32 s4, s93, s92
	s_add_i32 s4, s4, s23
	s_ashr_i32 s5, s4, 31
	s_lshl_b64 s[4:5], s[4:5], 11
	s_add_u32 s92, s87, s4
	s_addc_u32 s93, s35, s5
	s_waitcnt lgkmcnt(0)
	ds_write_b32 v161, v24 offset:49152
	global_load_dwordx2 v[24:25], v119, s[92:93]
	s_add_u32 s92, s85, s4
	s_addc_u32 s93, s86, s5
	global_load_dwordx2 v[72:73], v119, s[92:93]
	s_add_u32 s92, s8, s4
	s_addc_u32 s93, s84, s5
	global_load_dwordx2 v[26:27], v119, s[92:93]
	s_add_u32 s92, s97, s4
	s_addc_u32 s93, s99, s5
	global_load_dwordx2 v[84:85], v119, s[92:93]
	s_add_u32 s92, s94, s4
	s_addc_u32 s93, s95, s5
	s_add_u32 s4, s0, s4
	s_addc_u32 s5, s1, s5
	global_load_dwordx2 v[78:79], v119, s[92:93]
	s_nop 0
	global_load_dwordx2 v[86:87], v119, s[4:5]
	s_and_b64 vcc, exec, s[44:45]
	s_cbranch_vccnz .LBB0_197
	s_add_i32 s4, s37, -9
	s_cmp_ge_i32 s36, s4
	s_cbranch_scc0 .LBB0_218
.LBB0_197:
	s_waitcnt vmcnt(46)
	v_cvt_f32_f16_sdwa v123, v82 dst_sel:DWORD dst_unused:UNUSED_PAD src0_sel:WORD_1
	v_cvt_f32_f16_sdwa v125, v83 dst_sel:DWORD dst_unused:UNUSED_PAD src0_sel:WORD_1
	v_cvt_f32_f16_e32 v122, v82
	v_cvt_f32_f16_e32 v124, v83
	s_waitcnt vmcnt(44)
	v_cvt_f32_f16_sdwa v127, v98 dst_sel:DWORD dst_unused:UNUSED_PAD src0_sel:WORD_1
	v_cvt_f32_f16_sdwa v133, v99 dst_sel:DWORD dst_unused:UNUSED_PAD src0_sel:WORD_1
	v_cvt_f32_f16_e32 v126, v98
	v_cvt_f32_f16_e32 v132, v99
	v_pk_fma_f32 v[98:99], v[2:3], v[124:125], v[92:93]
	v_pk_fma_f32 v[122:123], v[0:1], v[122:123], v[94:95]
	s_or_b32 s4, s37, 7
	v_pk_mul_f32 v[98:99], v[98:99], v[132:133]
	v_pk_mul_f32 v[126:127], v[122:123], v[126:127]
	v_pk_mul_f16 v123, v83, v31
	v_pk_mul_f16 v122, v82, v30
	v_cvt_pk_f16_f32 v125, v98, v99
	v_cvt_pk_f16_f32 v124, v126, v127
	ds_write_b128 v120, v[28:31] offset:18432
	ds_write_b128 v120, v[122:125] offset:19456
	s_waitcnt vmcnt(42)
	v_add_u32_e32 v185, v121, v186
	ds_write_b64 v185, v[88:89] offset:20480
	ds_write_b64 v121, v[96:97] offset:20992
	v_mov_b32_e32 v28, s4
	s_min_u32 s4, s37, 0x1031
	s_lshl_b32 s4, s4, 2
	s_cmp_gt_u32 s37, 49
	s_cselect_b32 s5, 0xffffff38, 56
	s_cselect_b32 s23, s10, s33
	s_cselect_b32 s92, s46, 0xfc
	s_add_i32 s93, s4, s5
	s_sub_i32 s92, s92, s93
	s_and_b64 s[4:5], s[42:43], exec
	s_cselect_b32 s4, s93, s92
	s_add_i32 s4, s4, s23
	s_ashr_i32 s5, s4, 31
	s_lshl_b64 s[4:5], s[4:5], 11
	s_add_u32 s92, s87, s4
	s_addc_u32 s93, s35, s5
	s_waitcnt lgkmcnt(0)
	ds_write_b32 v161, v28 offset:49152
	global_load_dwordx2 v[28:29], v119, s[92:93]
	s_add_u32 s92, s85, s4
	s_addc_u32 s93, s86, s5
	global_load_dwordx2 v[82:83], v119, s[92:93]
	s_add_u32 s92, s8, s4
	s_addc_u32 s93, s84, s5
	global_load_dwordx2 v[30:31], v119, s[92:93]
	s_add_u32 s92, s97, s4
	s_addc_u32 s93, s99, s5
	global_load_dwordx2 v[98:99], v119, s[92:93]
	s_add_u32 s92, s94, s4
	s_addc_u32 s93, s95, s5
	s_add_u32 s4, s0, s4
	s_addc_u32 s5, s1, s5
	global_load_dwordx2 v[88:89], v119, s[92:93]
	s_nop 0
	global_load_dwordx2 v[96:97], v119, s[4:5]
	s_and_b64 vcc, exec, s[44:45]
	s_cbranch_vccnz .LBB0_182
	s_add_i32 s4, s37, -8
	s_cmp_ge_i32 s36, s4
	s_cbranch_scc0 .LBB0_221
	s_branch .LBB0_182

; #define LAS3 __attribute__((address_space(3)))
; DEV void rwkv_consumer(const Params& p, const Ctx& cx, int l, int task, int lane, const char* ring, int widx) {
;   const int unit = task >> 4, d = unit & 1, h = (unit >> 1) & 15, b = unit >> 5;
;   const int j = lane >> 4, s = lane & 15;
;   const int myrow = (task & 15) * 4 + j;
;   char* pO = (char*)((h16*)(p.ws + OFF_REG2) + (size_t)d * ARR + h * 64);
;   const int sm = d ? 3 - (s & 3) : (s & 3);
;   const unsigned vov0 = (unsigned)(sm * 2048 + myrow * 2);
;   const unsigned rofs = (unsigned)(s * 8);
;   const unsigned vrofs = (unsigned)(2560 + myrow * 2);
;   LAS3 volatile int* pflag = (LAS3 volatile int*)(ring + RW_FLAGS);
;   LAS3 volatile int* cflag = (LAS3 volatile int*)(ring + RW_FLAGS + 64) + widx;
;   float S0 = 0.f, S1 = 0.f, S2 = 0.f, S3 = 0.f;
;   int pseen = 0;
;   struct GD { u2v w[4], kk[4], kka[4], kd[4], r[4]; unsigned v[4]; };
;   GD A, B;
.LBB0_229:
	s_ashr_i32 s4, s31, 4
	s_lshl_b32 s1, s34, 4
	s_and_b32 s4, s4, -4
	s_or_b32 s1, s1, s4
	s_or_b32 s4, s1, s50
	s_lshl_b32 s1, s4, 2
	v_and_or_b32 v0, s1, 60, v107
	s_waitcnt vmcnt(0)
	v_lshlrev_b32_e32 v82, 1, v0
	v_lshlrev_b32_e32 v184, 3, v0
	v_add_u32_e32 v0, 16, v116
	v_add_u32_e32 v36, 16, v117
	v_add_u32_e32 v20, 0x800, v0
	v_add_u32_e32 v41, 16, v82
	ds_read_b128 v[0:3], v36 offset:2048
	ds_read_b128 v[4:7], v36
	ds_read_b128 v[8:11], v36 offset:256
	ds_read_b128 v[12:15], v36 offset:1024
	ds_read_b128 v[16:19], v36 offset:1280
	ds_read_b128 v[20:23], v36 offset:2304
	ds_read_b128 v[24:27], v36 offset:512
	s_waitcnt vmcnt(9)
	ds_read_b128 v[28:31], v36 offset:768
	s_waitcnt vmcnt(3)
	ds_read_b128 v[32:35], v36 offset:1536
	ds_read_b128 v[36:39], v36 offset:1792
	ds_read_u16 v88, v41 offset:2560
	ds_read_u16 v89, v41 offset:2688
	ds_read_u16 v90, v41 offset:2816
	ds_read_u16 v91, v41 offset:2944
	s_bfe_u32 s5, s4, 0x10004
	s_mul_i32 s8, s5, 0x4100000
	s_add_u32 s8, s20, s8
	s_addc_u32 s10, s21, 0
	s_and_b32 s1, s1, 0x780
	s_add_u32 s1, s8, s1
	s_addc_u32 s8, s10, 0
	s_cmp_eq_u32 s5, 0
	s_cselect_b64 s[42:43], -1, 0
	s_ashr_i32 s4, s4, 9
	v_cndmask_b32_e64 v40, v115, v114, s[42:43]
	s_lshl_b32 s22, s4, 8
	s_mov_b32 s33, 0
	v_or_b32_e32 v83, v40, v82
	s_lshl_b32 s10, s4, 14
	s_add_i32 s22, s22, 0x8000
	v_mov_b32_e32 v84, 0
	v_mov_b32_e32 v85, 0
	v_mov_b32_e32 v86, 0
	v_mov_b32_e32 v87, 0
	s_waitcnt vmcnt(0)
	s_and_b64 s[4:5], s[42:43], exec
	s_cselect_b32 s4, 0, 0xfc
	s_add_i32 s4, s22, s4
	s_lshl_b32 s4, s4, 11
	s_add_u32 s36, s1, s4
	s_addc_u32 s37, s8, 0
	s_and_b64 s[4:5], s[42:43], exec
	s_cselect_b32 s4, 0, 0x3ffc
	s_add_i32 s4, s10, s4
	s_lshl_b32 s4, s4, 11
	s_add_u32 s88, s1, s4
	s_addc_u32 s89, s8, 0
	s_and_b64 s[4:5], s[42:43], exec
	s_mov_b32 s44, 0xffffe000
	s_and_b64 s[4:5], s[42:43], exec
	s_cselect_b32 s44, 0x2000, s44
	s_cselect_b32 s45, 0, -1
	v_mov_b32_e32 v172, s9
	v_add_u32_e32 v194, 16, v117
	v_add_u32_e32 v195, 16, v184
	v_add_u32_e32 v196, 16, v82
	v_mov_b32_e32 v193, 0

.Lc_init_ld:
	ds_read_b128 v[56:59], v194 offset:5120
	ds_read_b128 v[72:75], v194 offset:3072
	ds_read_b128 v[64:67], v194 offset:3328
	ds_read_b128 v[76:79], v194 offset:4096
	ds_read_b128 v[68:71], v194 offset:4352
	ds_read_b128 v[40:43], v194 offset:5376
	ds_read_b128 v[52:55], v194 offset:3584
	ds_read_b128 v[44:47], v194 offset:3840
	ds_read_b128 v[60:63], v194 offset:4608
	ds_read_b128 v[48:51], v194 offset:4864
	ds_read_u16 v92, v196 offset:5632
	ds_read_u16 v93, v196 offset:5760
	ds_read_u16 v94, v196 offset:5888
	ds_read_u16 v95, v196 offset:6016
	s_mov_b32 s35, s0
	s_waitcnt lgkmcnt(0)
	v_fma_mix_f32 v98, v84, v6, 0 op_sel:[0,0,0] op_sel_hi:[0,1,0]
	v_fma_mix_f32 v98, v85, v6, v98 op_sel:[0,1,0] op_sel_hi:[0,1,0]
	v_fma_mix_f32 v98, v86, v7, v98 op_sel:[0,0,0] op_sel_hi:[0,1,0]
	v_fma_mix_f32 v98, v87, v7, v98 op_sel:[0,1,0] op_sel_hi:[0,1,0]
	v_fma_mix_f32 v100, v88, v14, 0 op_sel:[0,0,0] op_sel_hi:[1,1,0]
	v_fma_mix_f32 v101, v88, v14, 0 op_sel:[0,1,0] op_sel_hi:[1,1,0]
	v_add_f32_dpp v98, v98, v98 quad_perm:[1,0,3,2] row_mask:0xf bank_mask:0xf bound_ctrl:1
	v_fma_mix_f32 v102, v88, v15, 0 op_sel:[0,0,0] op_sel_hi:[1,1,0]
	v_fma_mix_f32 v103, v88, v15, 0 op_sel:[0,1,0] op_sel_hi:[1,1,0]
	v_add_f32_dpp v98, v98, v98 quad_perm:[2,3,0,1] row_mask:0xf bank_mask:0xf bound_ctrl:1
	s_branch .Lc_top
.Lc_top:
	v_fma_mix_f32 v84, v84, v4, v100 op_sel:[0,0,0] op_sel_hi:[0,1,0]
	v_fma_mix_f32 v85, v85, v4, v101 op_sel:[0,1,0] op_sel_hi:[0,1,0]
	v_add_f32_dpp v98, v98, v98 row_half_mirror row_mask:0xf bank_mask:0xf bound_ctrl:1
	v_fma_mix_f32 v86, v86, v5, v102 op_sel:[0,0,0] op_sel_hi:[0,1,0]
	v_fma_mix_f32 v87, v87, v5, v103 op_sel:[0,1,0] op_sel_hi:[0,1,0]
	v_add_f32_dpp v98, v98, v98 row_mirror row_mask:0xf bank_mask:0xf bound_ctrl:1
	v_fma_mix_f32 v84, -v98, v12, v84 op_sel:[0,0,0] op_sel_hi:[0,1,0]
	v_fma_mix_f32 v85, -v98, v12, v85 op_sel:[0,1,0] op_sel_hi:[0,1,0]
	v_fma_mix_f32 v86, -v98, v13, v86 op_sel:[0,0,0] op_sel_hi:[0,1,0]
	v_fma_mix_f32 v87, -v98, v13, v87 op_sel:[0,1,0] op_sel_hi:[0,1,0]
	v_fma_mix_f32 v99, v84, v10, 0 op_sel:[0,0,0] op_sel_hi:[0,1,0]
	v_fma_mix_f32 v96, v84, v0, 0 op_sel:[0,0,0] op_sel_hi:[0,1,0]
	v_fma_mix_f32 v99, v85, v10, v99 op_sel:[0,1,0] op_sel_hi:[0,1,0]
	v_fma_mix_f32 v96, v85, v0, v96 op_sel:[0,1,0] op_sel_hi:[0,1,0]
	v_fma_mix_f32 v99, v86, v11, v99 op_sel:[0,0,0] op_sel_hi:[0,1,0]
	v_fma_mix_f32 v96, v86, v1, v96 op_sel:[0,0,0] op_sel_hi:[0,1,0]
	v_fma_mix_f32 v99, v87, v11, v99 op_sel:[0,1,0] op_sel_hi:[0,1,0]
	v_fma_mix_f32 v96, v87, v1, v96 op_sel:[0,1,0] op_sel_hi:[0,1,0]
	v_fma_mix_f32 v101, v89, v18, 0 op_sel:[0,0,0] op_sel_hi:[1,1,0]
	v_fma_mix_f32 v102, v89, v18, 0 op_sel:[0,1,0] op_sel_hi:[1,1,0]
	v_add_f32_dpp v99, v99, v99 quad_perm:[1,0,3,2] row_mask:0xf bank_mask:0xf bound_ctrl:1
	v_fma_mix_f32 v103, v89, v19, 0 op_sel:[0,0,0] op_sel_hi:[1,1,0]
	v_fma_mix_f32 v104, v89, v19, 0 op_sel:[0,1,0] op_sel_hi:[1,1,0]
	v_add_f32_dpp v99, v99, v99 quad_perm:[2,3,0,1] row_mask:0xf bank_mask:0xf bound_ctrl:1
	v_fma_mix_f32 v84, v84, v8, v101 op_sel:[0,0,0] op_sel_hi:[0,1,0]
	v_fma_mix_f32 v85, v85, v8, v102 op_sel:[0,1,0] op_sel_hi:[0,1,0]
	v_add_f32_dpp v99, v99, v99 row_half_mirror row_mask:0xf bank_mask:0xf bound_ctrl:1
	v_fma_mix_f32 v86, v86, v9, v103 op_sel:[0,0,0] op_sel_hi:[0,1,0]
	v_fma_mix_f32 v87, v87, v9, v104 op_sel:[0,1,0] op_sel_hi:[0,1,0]
	v_add_f32_dpp v99, v99, v99 row_mirror row_mask:0xf bank_mask:0xf bound_ctrl:1
	v_fma_mix_f32 v84, -v99, v16, v84 op_sel:[0,0,0] op_sel_hi:[0,1,0]
	v_fma_mix_f32 v85, -v99, v16, v85 op_sel:[0,1,0] op_sel_hi:[0,1,0]
	v_fma_mix_f32 v86, -v99, v17, v86 op_sel:[0,0,0] op_sel_hi:[0,1,0]
	v_fma_mix_f32 v87, -v99, v17, v87 op_sel:[0,1,0] op_sel_hi:[0,1,0]
	v_fma_mix_f32 v100, v84, v26, 0 op_sel:[0,0,0] op_sel_hi:[0,1,0]
	v_fma_mix_f32 v97, v84, v2, 0 op_sel:[0,0,0] op_sel_hi:[0,1,0]
	v_fma_mix_f32 v100, v85, v26, v100 op_sel:[0,1,0] op_sel_hi:[0,1,0]
	v_fma_mix_f32 v97, v85, v2, v97 op_sel:[0,1,0] op_sel_hi:[0,1,0]
	v_fma_mix_f32 v100, v86, v27, v100 op_sel:[0,0,0] op_sel_hi:[0,1,0]
	v_fma_mix_f32 v97, v86, v3, v97 op_sel:[0,0,0] op_sel_hi:[0,1,0]
	v_fma_mix_f32 v100, v87, v27, v100 op_sel:[0,1,0] op_sel_hi:[0,1,0]
	v_fma_mix_f32 v97, v87, v3, v97 op_sel:[0,1,0] op_sel_hi:[0,1,0]
	v_fma_mix_f32 v102, v90, v34, 0 op_sel:[0,0,0] op_sel_hi:[1,1,0]
	v_fma_mix_f32 v103, v90, v34, 0 op_sel:[0,1,0] op_sel_hi:[1,1,0]
	v_add_f32_dpp v100, v100, v100 quad_perm:[1,0,3,2] row_mask:0xf bank_mask:0xf bound_ctrl:1
	v_fma_mix_f32 v104, v90, v35, 0 op_sel:[0,0,0] op_sel_hi:[1,1,0]
	v_fma_mix_f32 v105, v90, v35, 0 op_sel:[0,1,0] op_sel_hi:[1,1,0]
	v_add_f32_dpp v100, v100, v100 quad_perm:[2,3,0,1] row_mask:0xf bank_mask:0xf bound_ctrl:1
	v_fma_mix_f32 v84, v84, v24, v102 op_sel:[0,0,0] op_sel_hi:[0,1,0]
	v_fma_mix_f32 v85, v85, v24, v103 op_sel:[0,1,0] op_sel_hi:[0,1,0]
	v_add_f32_dpp v100, v100, v100 row_half_mirror row_mask:0xf bank_mask:0xf bound_ctrl:1
	v_fma_mix_f32 v86, v86, v25, v104 op_sel:[0,0,0] op_sel_hi:[0,1,0]
	v_fma_mix_f32 v87, v87, v25, v105 op_sel:[0,1,0] op_sel_hi:[0,1,0]
	v_add_f32_dpp v100, v100, v100 row_mirror row_mask:0xf bank_mask:0xf bound_ctrl:1
	v_fma_mix_f32 v84, -v100, v32, v84 op_sel:[0,0,0] op_sel_hi:[0,1,0]
	v_fma_mix_f32 v85, -v100, v32, v85 op_sel:[0,1,0] op_sel_hi:[0,1,0]
	v_fma_mix_f32 v86, -v100, v33, v86 op_sel:[0,0,0] op_sel_hi:[0,1,0]
	v_fma_mix_f32 v87, -v100, v33, v87 op_sel:[0,1,0] op_sel_hi:[0,1,0]
	v_fma_mix_f32 v101, v84, v30, 0 op_sel:[0,0,0] op_sel_hi:[0,1,0]
	v_fma_mix_f32 v98, v84, v20, 0 op_sel:[0,0,0] op_sel_hi:[0,1,0]
	v_fma_mix_f32 v101, v85, v30, v101 op_sel:[0,1,0] op_sel_hi:[0,1,0]
	v_fma_mix_f32 v98, v85, v20, v98 op_sel:[0,1,0] op_sel_hi:[0,1,0]
	v_fma_mix_f32 v101, v86, v31, v101 op_sel:[0,0,0] op_sel_hi:[0,1,0]
	v_fma_mix_f32 v98, v86, v21, v98 op_sel:[0,0,0] op_sel_hi:[0,1,0]
	v_fma_mix_f32 v101, v87, v31, v101 op_sel:[0,1,0] op_sel_hi:[0,1,0]
	v_fma_mix_f32 v98, v87, v21, v98 op_sel:[0,1,0] op_sel_hi:[0,1,0]
	v_fma_mix_f32 v103, v91, v38, 0 op_sel:[0,0,0] op_sel_hi:[1,1,0]
	v_fma_mix_f32 v104, v91, v38, 0 op_sel:[0,1,0] op_sel_hi:[1,1,0]
	v_add_f32_dpp v101, v101, v101 quad_perm:[1,0,3,2] row_mask:0xf bank_mask:0xf bound_ctrl:1
	v_fma_mix_f32 v105, v91, v39, 0 op_sel:[0,0,0] op_sel_hi:[1,1,0]
	v_fma_mix_f32 v119, v91, v39, 0 op_sel:[0,1,0] op_sel_hi:[1,1,0]
	v_add_f32_dpp v101, v101, v101 quad_perm:[2,3,0,1] row_mask:0xf bank_mask:0xf bound_ctrl:1
	v_fma_mix_f32 v84, v84, v28, v103 op_sel:[0,0,0] op_sel_hi:[0,1,0]
	v_fma_mix_f32 v85, v85, v28, v104 op_sel:[0,1,0] op_sel_hi:[0,1,0]
	v_add_f32_dpp v101, v101, v101 row_half_mirror row_mask:0xf bank_mask:0xf bound_ctrl:1
	v_fma_mix_f32 v86, v86, v29, v105 op_sel:[0,0,0] op_sel_hi:[0,1,0]
	v_fma_mix_f32 v87, v87, v29, v119 op_sel:[0,1,0] op_sel_hi:[0,1,0]
	v_add_f32_dpp v101, v101, v101 row_mirror row_mask:0xf bank_mask:0xf bound_ctrl:1
	v_fma_mix_f32 v84, -v101, v36, v84 op_sel:[0,0,0] op_sel_hi:[0,1,0]
	v_fma_mix_f32 v85, -v101, v36, v85 op_sel:[0,1,0] op_sel_hi:[0,1,0]
	v_fma_mix_f32 v86, -v101, v37, v86 op_sel:[0,0,0] op_sel_hi:[0,1,0]
	v_fma_mix_f32 v87, -v101, v37, v87 op_sel:[0,1,0] op_sel_hi:[0,1,0]
	v_fma_mix_f32 v99, v84, v22, 0 op_sel:[0,0,0] op_sel_hi:[0,1,0]
	v_cndmask_b32_e64 v187, v97, v96, s[38:39]
	v_fma_mix_f32 v99, v85, v22, v99 op_sel:[0,1,0] op_sel_hi:[0,1,0]
	v_cndmask_b32_e64 v188, v96, v97, s[38:39]
	v_fma_mix_f32 v99, v86, v23, v99 op_sel:[0,0,0] op_sel_hi:[0,1,0]
	v_fma_mix_f32 v99, v87, v23, v99 op_sel:[0,1,0] op_sel_hi:[0,1,0]
	v_cndmask_b32_e64 v189, v99, v98, s[38:39]
	v_cndmask_b32_e64 v190, v98, v99, s[38:39]
	s_waitcnt lgkmcnt(0)
	v_fma_mix_f32 v98, v84, v74, 0 op_sel:[0,0,0] op_sel_hi:[0,1,0]
	v_fma_mix_f32 v98, v85, v74, v98 op_sel:[0,1,0] op_sel_hi:[0,1,0]
	v_add_f32_dpp v188, v188, v187 quad_perm:[1,0,3,2] row_mask:0xf bank_mask:0xf bound_ctrl:1
	v_add_f32_dpp v189, v190, v189 quad_perm:[1,0,3,2] row_mask:0xf bank_mask:0xf bound_ctrl:1
	v_fma_mix_f32 v98, v86, v75, v98 op_sel:[0,0,0] op_sel_hi:[0,1,0]
	v_fma_mix_f32 v98, v87, v75, v98 op_sel:[0,1,0] op_sel_hi:[0,1,0]
	v_cndmask_b32_e64 v191, v189, v188, s[40:41]
	v_cndmask_b32_e64 v192, v188, v189, s[40:41]
	v_fma_mix_f32 v100, v92, v78, 0 op_sel:[0,0,0] op_sel_hi:[1,1,0]
	v_fma_mix_f32 v101, v92, v78, 0 op_sel:[0,1,0] op_sel_hi:[1,1,0]
	v_add_f32_dpp v192, v192, v191 quad_perm:[2,3,0,1] row_mask:0xf bank_mask:0xf bound_ctrl:1
	v_add_f32_dpp v98, v98, v98 quad_perm:[1,0,3,2] row_mask:0xf bank_mask:0xf bound_ctrl:1
	v_fma_mix_f32 v102, v92, v79, 0 op_sel:[0,0,0] op_sel_hi:[1,1,0]
	v_add_f32_dpp v192, v192, v192 row_ror:4 row_mask:0xf bank_mask:0xf bound_ctrl:1
	v_fma_mix_f32 v103, v92, v79, 0 op_sel:[0,1,0] op_sel_hi:[1,1,0]
	v_add_f32_dpp v98, v98, v98 quad_perm:[2,3,0,1] row_mask:0xf bank_mask:0xf bound_ctrl:1
	v_add_f32_dpp v192, v192, v192 row_ror:8 row_mask:0xf bank_mask:0xf bound_ctrl:1
	v_cvt_f16_f32_e32 v192, v192
	global_store_short v83, v192, s[36:37]
	s_add_u32 s36, s36, s44
	s_addc_u32 s37, s37, s45
	s_cmp_gt_i32 s35, 3
	s_cbranch_scc0 .Lc_poll_A0
.Lc_ret_A0:
	ds_read_b128 v[0:3], v194 offset:8192
	ds_read_b128 v[4:7], v194 offset:6144
	ds_read_b128 v[8:11], v194 offset:6400
	ds_read_b128 v[12:15], v194 offset:7168
	ds_read_b128 v[16:19], v194 offset:7424
	ds_read_b128 v[20:23], v194 offset:8448
	ds_read_b128 v[24:27], v194 offset:6656
	ds_read_b128 v[28:31], v194 offset:6912
	ds_read_b128 v[32:35], v194 offset:7680
	ds_read_b128 v[36:39], v194 offset:7936
	ds_read_u16 v88, v196 offset:8704
	ds_read_u16 v89, v196 offset:8832
	ds_read_u16 v90, v196 offset:8960
	ds_read_u16 v91, v196 offset:9088
	v_fma_mix_f32 v84, v84, v72, v100 op_sel:[0,0,0] op_sel_hi:[0,1,0]
	v_fma_mix_f32 v85, v85, v72, v101 op_sel:[0,1,0] op_sel_hi:[0,1,0]
	v_add_f32_dpp v98, v98, v98 row_half_mirror row_mask:0xf bank_mask:0xf bound_ctrl:1
	v_fma_mix_f32 v86, v86, v73, v102 op_sel:[0,0,0] op_sel_hi:[0,1,0]
	v_fma_mix_f32 v87, v87, v73, v103 op_sel:[0,1,0] op_sel_hi:[0,1,0]
	v_add_f32_dpp v98, v98, v98 row_mirror row_mask:0xf bank_mask:0xf bound_ctrl:1
	v_fma_mix_f32 v84, -v98, v76, v84 op_sel:[0,0,0] op_sel_hi:[0,1,0]
	v_fma_mix_f32 v85, -v98, v76, v85 op_sel:[0,1,0] op_sel_hi:[0,1,0]
	v_fma_mix_f32 v86, -v98, v77, v86 op_sel:[0,0,0] op_sel_hi:[0,1,0]
	v_fma_mix_f32 v87, -v98, v77, v87 op_sel:[0,1,0] op_sel_hi:[0,1,0]
	v_fma_mix_f32 v73, v84, v66, 0 op_sel:[0,0,0] op_sel_hi:[0,1,0]
	v_fma_mix_f32 v97, v84, v56, 0 op_sel:[0,0,0] op_sel_hi:[0,1,0]
	v_fma_mix_f32 v73, v85, v66, v73 op_sel:[0,1,0] op_sel_hi:[0,1,0]
	v_fma_mix_f32 v56, v85, v56, v97 op_sel:[0,1,0] op_sel_hi:[0,1,0]
	v_fma_mix_f32 v73, v86, v67, v73 op_sel:[0,0,0] op_sel_hi:[0,1,0]
	v_fma_mix_f32 v56, v86, v57, v56 op_sel:[0,0,0] op_sel_hi:[0,1,0]
	v_fma_mix_f32 v73, v87, v67, v73 op_sel:[0,1,0] op_sel_hi:[0,1,0]
	v_fma_mix_f32 v56, v87, v57, v56 op_sel:[0,1,0] op_sel_hi:[0,1,0]
	v_fma_mix_f32 v75, v93, v70, 0 op_sel:[0,0,0] op_sel_hi:[1,1,0]
	v_fma_mix_f32 v76, v93, v70, 0 op_sel:[0,1,0] op_sel_hi:[1,1,0]
	v_add_f32_dpp v73, v73, v73 quad_perm:[1,0,3,2] row_mask:0xf bank_mask:0xf bound_ctrl:1
	v_fma_mix_f32 v77, v93, v71, 0 op_sel:[0,0,0] op_sel_hi:[1,1,0]
	v_fma_mix_f32 v78, v93, v71, 0 op_sel:[0,1,0] op_sel_hi:[1,1,0]
	v_add_f32_dpp v73, v73, v73 quad_perm:[2,3,0,1] row_mask:0xf bank_mask:0xf bound_ctrl:1
	v_fma_mix_f32 v84, v84, v64, v75 op_sel:[0,0,0] op_sel_hi:[0,1,0]
	v_fma_mix_f32 v85, v85, v64, v76 op_sel:[0,1,0] op_sel_hi:[0,1,0]
	v_add_f32_dpp v73, v73, v73 row_half_mirror row_mask:0xf bank_mask:0xf bound_ctrl:1
	v_fma_mix_f32 v86, v86, v65, v77 op_sel:[0,0,0] op_sel_hi:[0,1,0]
	v_fma_mix_f32 v87, v87, v65, v78 op_sel:[0,1,0] op_sel_hi:[0,1,0]
	v_add_f32_dpp v73, v73, v73 row_mirror row_mask:0xf bank_mask:0xf bound_ctrl:1
	v_fma_mix_f32 v84, -v73, v68, v84 op_sel:[0,0,0] op_sel_hi:[0,1,0]
	v_fma_mix_f32 v85, -v73, v68, v85 op_sel:[0,1,0] op_sel_hi:[0,1,0]
	v_fma_mix_f32 v86, -v73, v69, v86 op_sel:[0,0,0] op_sel_hi:[0,1,0]
	v_fma_mix_f32 v87, -v73, v69, v87 op_sel:[0,1,0] op_sel_hi:[0,1,0]
	v_fma_mix_f32 v64, v84, v54, 0 op_sel:[0,0,0] op_sel_hi:[0,1,0]
	v_fma_mix_f32 v57, v84, v58, 0 op_sel:[0,0,0] op_sel_hi:[0,1,0]
	v_fma_mix_f32 v64, v85, v54, v64 op_sel:[0,1,0] op_sel_hi:[0,1,0]
	v_fma_mix_f32 v57, v85, v58, v57 op_sel:[0,1,0] op_sel_hi:[0,1,0]
	v_fma_mix_f32 v64, v86, v55, v64 op_sel:[0,0,0] op_sel_hi:[0,1,0]
	v_fma_mix_f32 v57, v86, v59, v57 op_sel:[0,0,0] op_sel_hi:[0,1,0]
	v_fma_mix_f32 v64, v87, v55, v64 op_sel:[0,1,0] op_sel_hi:[0,1,0]
	v_fma_mix_f32 v57, v87, v59, v57 op_sel:[0,1,0] op_sel_hi:[0,1,0]
	v_fma_mix_f32 v66, v94, v62, 0 op_sel:[0,0,0] op_sel_hi:[1,1,0]
	v_fma_mix_f32 v67, v94, v62, 0 op_sel:[0,1,0] op_sel_hi:[1,1,0]
	v_add_f32_dpp v64, v64, v64 quad_perm:[1,0,3,2] row_mask:0xf bank_mask:0xf bound_ctrl:1
	v_fma_mix_f32 v68, v94, v63, 0 op_sel:[0,0,0] op_sel_hi:[1,1,0]
	v_fma_mix_f32 v69, v94, v63, 0 op_sel:[0,1,0] op_sel_hi:[1,1,0]
	v_add_f32_dpp v64, v64, v64 quad_perm:[2,3,0,1] row_mask:0xf bank_mask:0xf bound_ctrl:1
	v_fma_mix_f32 v84, v84, v52, v66 op_sel:[0,0,0] op_sel_hi:[0,1,0]
	v_fma_mix_f32 v85, v85, v52, v67 op_sel:[0,1,0] op_sel_hi:[0,1,0]
	v_add_f32_dpp v64, v64, v64 row_half_mirror row_mask:0xf bank_mask:0xf bound_ctrl:1
	v_fma_mix_f32 v86, v86, v53, v68 op_sel:[0,0,0] op_sel_hi:[0,1,0]
	v_fma_mix_f32 v87, v87, v53, v69 op_sel:[0,1,0] op_sel_hi:[0,1,0]
	v_add_f32_dpp v64, v64, v64 row_mirror row_mask:0xf bank_mask:0xf bound_ctrl:1
	v_fma_mix_f32 v84, -v64, v60, v84 op_sel:[0,0,0] op_sel_hi:[0,1,0]
	v_fma_mix_f32 v85, -v64, v60, v85 op_sel:[0,1,0] op_sel_hi:[0,1,0]
	v_fma_mix_f32 v86, -v64, v61, v86 op_sel:[0,0,0] op_sel_hi:[0,1,0]
	v_fma_mix_f32 v87, -v64, v61, v87 op_sel:[0,1,0] op_sel_hi:[0,1,0]
	v_fma_mix_f32 v53, v84, v46, 0 op_sel:[0,0,0] op_sel_hi:[0,1,0]
	v_fma_mix_f32 v59, v84, v40, 0 op_sel:[0,0,0] op_sel_hi:[0,1,0]
	v_fma_mix_f32 v53, v85, v46, v53 op_sel:[0,1,0] op_sel_hi:[0,1,0]
	v_fma_mix_f32 v40, v85, v40, v59 op_sel:[0,1,0] op_sel_hi:[0,1,0]
	v_fma_mix_f32 v53, v86, v47, v53 op_sel:[0,0,0] op_sel_hi:[0,1,0]
	v_fma_mix_f32 v40, v86, v41, v40 op_sel:[0,0,0] op_sel_hi:[0,1,0]
	v_fma_mix_f32 v53, v87, v47, v53 op_sel:[0,1,0] op_sel_hi:[0,1,0]
	v_fma_mix_f32 v40, v87, v41, v40 op_sel:[0,1,0] op_sel_hi:[0,1,0]
	v_fma_mix_f32 v55, v95, v50, 0 op_sel:[0,0,0] op_sel_hi:[1,1,0]
	v_fma_mix_f32 v58, v95, v50, 0 op_sel:[0,1,0] op_sel_hi:[1,1,0]
	v_add_f32_dpp v53, v53, v53 quad_perm:[1,0,3,2] row_mask:0xf bank_mask:0xf bound_ctrl:1
	v_fma_mix_f32 v59, v95, v51, 0 op_sel:[0,0,0] op_sel_hi:[1,1,0]
	v_fma_mix_f32 v60, v95, v51, 0 op_sel:[0,1,0] op_sel_hi:[1,1,0]
	v_add_f32_dpp v53, v53, v53 quad_perm:[2,3,0,1] row_mask:0xf bank_mask:0xf bound_ctrl:1
	v_fma_mix_f32 v84, v84, v44, v55 op_sel:[0,0,0] op_sel_hi:[0,1,0]
	v_fma_mix_f32 v85, v85, v44, v58 op_sel:[0,1,0] op_sel_hi:[0,1,0]
	v_add_f32_dpp v53, v53, v53 row_half_mirror row_mask:0xf bank_mask:0xf bound_ctrl:1
	v_fma_mix_f32 v86, v86, v45, v59 op_sel:[0,0,0] op_sel_hi:[0,1,0]
	v_fma_mix_f32 v87, v87, v45, v60 op_sel:[0,1,0] op_sel_hi:[0,1,0]
	v_add_f32_dpp v53, v53, v53 row_mirror row_mask:0xf bank_mask:0xf bound_ctrl:1
	v_fma_mix_f32 v84, -v53, v48, v84 op_sel:[0,0,0] op_sel_hi:[0,1,0]
	v_fma_mix_f32 v85, -v53, v48, v85 op_sel:[0,1,0] op_sel_hi:[0,1,0]
	v_fma_mix_f32 v86, -v53, v49, v86 op_sel:[0,0,0] op_sel_hi:[0,1,0]
	v_fma_mix_f32 v87, -v53, v49, v87 op_sel:[0,1,0] op_sel_hi:[0,1,0]
	v_fma_mix_f32 v41, v84, v42, 0 op_sel:[0,0,0] op_sel_hi:[0,1,0]
	v_cndmask_b32_e64 v187, v57, v56, s[38:39]
	v_fma_mix_f32 v41, v85, v42, v41 op_sel:[0,1,0] op_sel_hi:[0,1,0]
	v_cndmask_b32_e64 v188, v56, v57, s[38:39]
	v_fma_mix_f32 v41, v86, v43, v41 op_sel:[0,0,0] op_sel_hi:[0,1,0]
	v_fma_mix_f32 v41, v87, v43, v41 op_sel:[0,1,0] op_sel_hi:[0,1,0]
	v_cndmask_b32_e64 v189, v41, v40, s[38:39]
	v_cndmask_b32_e64 v190, v40, v41, s[38:39]
	s_waitcnt lgkmcnt(0)
	v_fma_mix_f32 v98, v84, v6, 0 op_sel:[0,0,0] op_sel_hi:[0,1,0]
	v_fma_mix_f32 v98, v85, v6, v98 op_sel:[0,1,0] op_sel_hi:[0,1,0]
	v_add_f32_dpp v188, v188, v187 quad_perm:[1,0,3,2] row_mask:0xf bank_mask:0xf bound_ctrl:1
	v_add_f32_dpp v189, v190, v189 quad_perm:[1,0,3,2] row_mask:0xf bank_mask:0xf bound_ctrl:1
	v_fma_mix_f32 v98, v86, v7, v98 op_sel:[0,0,0] op_sel_hi:[0,1,0]
	v_fma_mix_f32 v98, v87, v7, v98 op_sel:[0,1,0] op_sel_hi:[0,1,0]
	v_cndmask_b32_e64 v191, v189, v188, s[40:41]
	v_cndmask_b32_e64 v192, v188, v189, s[40:41]
	v_fma_mix_f32 v100, v88, v14, 0 op_sel:[0,0,0] op_sel_hi:[1,1,0]
	v_fma_mix_f32 v101, v88, v14, 0 op_sel:[0,1,0] op_sel_hi:[1,1,0]
	v_add_f32_dpp v192, v192, v191 quad_perm:[2,3,0,1] row_mask:0xf bank_mask:0xf bound_ctrl:1
	v_add_f32_dpp v98, v98, v98 quad_perm:[1,0,3,2] row_mask:0xf bank_mask:0xf bound_ctrl:1
	v_fma_mix_f32 v102, v88, v15, 0 op_sel:[0,0,0] op_sel_hi:[1,1,0]
	v_add_f32_dpp v192, v192, v192 row_ror:4 row_mask:0xf bank_mask:0xf bound_ctrl:1
	v_fma_mix_f32 v103, v88, v15, 0 op_sel:[0,1,0] op_sel_hi:[1,1,0]
	v_add_f32_dpp v98, v98, v98 quad_perm:[2,3,0,1] row_mask:0xf bank_mask:0xf bound_ctrl:1
	v_add_f32_dpp v192, v192, v192 row_ror:8 row_mask:0xf bank_mask:0xf bound_ctrl:1
	v_cvt_f16_f32_e32 v192, v192
	global_store_short v83, v192, s[36:37]
	s_add_u32 s36, s36, s44
	s_addc_u32 s37, s37, s45
	ds_read_b128 v[56:59], v194 offset:11264
	ds_read_b128 v[72:75], v194 offset:9216
	ds_read_b128 v[64:67], v194 offset:9472
	ds_read_b128 v[76:79], v194 offset:10240
	ds_read_b128 v[68:71], v194 offset:10496
	ds_read_b128 v[40:43], v194 offset:11520
	ds_read_b128 v[52:55], v194 offset:9728
	ds_read_b128 v[44:47], v194 offset:9984
	ds_read_b128 v[60:63], v194 offset:10752
	ds_read_b128 v[48:51], v194 offset:11008
	ds_read_u16 v92, v196 offset:11776
	ds_read_u16 v93, v196 offset:11904
	ds_read_u16 v94, v196 offset:12032
	ds_read_u16 v95, v196 offset:12160
	v_fma_mix_f32 v84, v84, v4, v100 op_sel:[0,0,0] op_sel_hi:[0,1,0]
	v_fma_mix_f32 v85, v85, v4, v101 op_sel:[0,1,0] op_sel_hi:[0,1,0]
	v_add_f32_dpp v98, v98, v98 row_half_mirror row_mask:0xf bank_mask:0xf bound_ctrl:1
	v_fma_mix_f32 v86, v86, v5, v102 op_sel:[0,0,0] op_sel_hi:[0,1,0]
	v_fma_mix_f32 v87, v87, v5, v103 op_sel:[0,1,0] op_sel_hi:[0,1,0]
	v_add_f32_dpp v98, v98, v98 row_mirror row_mask:0xf bank_mask:0xf bound_ctrl:1
	v_fma_mix_f32 v84, -v98, v12, v84 op_sel:[0,0,0] op_sel_hi:[0,1,0]
	v_fma_mix_f32 v85, -v98, v12, v85 op_sel:[0,1,0] op_sel_hi:[0,1,0]
	v_fma_mix_f32 v86, -v98, v13, v86 op_sel:[0,0,0] op_sel_hi:[0,1,0]
	v_fma_mix_f32 v87, -v98, v13, v87 op_sel:[0,1,0] op_sel_hi:[0,1,0]
	v_fma_mix_f32 v99, v84, v10, 0 op_sel:[0,0,0] op_sel_hi:[0,1,0]
	v_fma_mix_f32 v96, v84, v0, 0 op_sel:[0,0,0] op_sel_hi:[0,1,0]
	v_fma_mix_f32 v99, v85, v10, v99 op_sel:[0,1,0] op_sel_hi:[0,1,0]
	v_fma_mix_f32 v96, v85, v0, v96 op_sel:[0,1,0] op_sel_hi:[0,1,0]
	v_fma_mix_f32 v99, v86, v11, v99 op_sel:[0,0,0] op_sel_hi:[0,1,0]
	v_fma_mix_f32 v96, v86, v1, v96 op_sel:[0,0,0] op_sel_hi:[0,1,0]
	v_fma_mix_f32 v99, v87, v11, v99 op_sel:[0,1,0] op_sel_hi:[0,1,0]
	v_fma_mix_f32 v96, v87, v1, v96 op_sel:[0,1,0] op_sel_hi:[0,1,0]
	v_fma_mix_f32 v101, v89, v18, 0 op_sel:[0,0,0] op_sel_hi:[1,1,0]
	v_fma_mix_f32 v102, v89, v18, 0 op_sel:[0,1,0] op_sel_hi:[1,1,0]
	v_add_f32_dpp v99, v99, v99 quad_perm:[1,0,3,2] row_mask:0xf bank_mask:0xf bound_ctrl:1
	v_fma_mix_f32 v103, v89, v19, 0 op_sel:[0,0,0] op_sel_hi:[1,1,0]
	v_fma_mix_f32 v104, v89, v19, 0 op_sel:[0,1,0] op_sel_hi:[1,1,0]
	v_add_f32_dpp v99, v99, v99 quad_perm:[2,3,0,1] row_mask:0xf bank_mask:0xf bound_ctrl:1
	v_fma_mix_f32 v84, v84, v8, v101 op_sel:[0,0,0] op_sel_hi:[0,1,0]
	v_fma_mix_f32 v85, v85, v8, v102 op_sel:[0,1,0] op_sel_hi:[0,1,0]
	v_add_f32_dpp v99, v99, v99 row_half_mirror row_mask:0xf bank_mask:0xf bound_ctrl:1
	v_fma_mix_f32 v86, v86, v9, v103 op_sel:[0,0,0] op_sel_hi:[0,1,0]
	v_fma_mix_f32 v87, v87, v9, v104 op_sel:[0,1,0] op_sel_hi:[0,1,0]
	v_add_f32_dpp v99, v99, v99 row_mirror row_mask:0xf bank_mask:0xf bound_ctrl:1
	v_fma_mix_f32 v84, -v99, v16, v84 op_sel:[0,0,0] op_sel_hi:[0,1,0]
	v_fma_mix_f32 v85, -v99, v16, v85 op_sel:[0,1,0] op_sel_hi:[0,1,0]
	v_fma_mix_f32 v86, -v99, v17, v86 op_sel:[0,0,0] op_sel_hi:[0,1,0]
	v_fma_mix_f32 v87, -v99, v17, v87 op_sel:[0,1,0] op_sel_hi:[0,1,0]
	v_fma_mix_f32 v100, v84, v26, 0 op_sel:[0,0,0] op_sel_hi:[0,1,0]
	v_fma_mix_f32 v97, v84, v2, 0 op_sel:[0,0,0] op_sel_hi:[0,1,0]
	v_fma_mix_f32 v100, v85, v26, v100 op_sel:[0,1,0] op_sel_hi:[0,1,0]
	v_fma_mix_f32 v97, v85, v2, v97 op_sel:[0,1,0] op_sel_hi:[0,1,0]
	v_fma_mix_f32 v100, v86, v27, v100 op_sel:[0,0,0] op_sel_hi:[0,1,0]
	v_fma_mix_f32 v97, v86, v3, v97 op_sel:[0,0,0] op_sel_hi:[0,1,0]
	v_fma_mix_f32 v100, v87, v27, v100 op_sel:[0,1,0] op_sel_hi:[0,1,0]
	v_fma_mix_f32 v97, v87, v3, v97 op_sel:[0,1,0] op_sel_hi:[0,1,0]
	v_fma_mix_f32 v102, v90, v34, 0 op_sel:[0,0,0] op_sel_hi:[1,1,0]
	v_fma_mix_f32 v103, v90, v34, 0 op_sel:[0,1,0] op_sel_hi:[1,1,0]
	v_add_f32_dpp v100, v100, v100 quad_perm:[1,0,3,2] row_mask:0xf bank_mask:0xf bound_ctrl:1
	v_fma_mix_f32 v104, v90, v35, 0 op_sel:[0,0,0] op_sel_hi:[1,1,0]
	v_fma_mix_f32 v105, v90, v35, 0 op_sel:[0,1,0] op_sel_hi:[1,1,0]
	v_add_f32_dpp v100, v100, v100 quad_perm:[2,3,0,1] row_mask:0xf bank_mask:0xf bound_ctrl:1
	v_fma_mix_f32 v84, v84, v24, v102 op_sel:[0,0,0] op_sel_hi:[0,1,0]
	v_fma_mix_f32 v85, v85, v24, v103 op_sel:[0,1,0] op_sel_hi:[0,1,0]
	v_add_f32_dpp v100, v100, v100 row_half_mirror row_mask:0xf bank_mask:0xf bound_ctrl:1
	v_fma_mix_f32 v86, v86, v25, v104 op_sel:[0,0,0] op_sel_hi:[0,1,0]
	v_fma_mix_f32 v87, v87, v25, v105 op_sel:[0,1,0] op_sel_hi:[0,1,0]
	v_add_f32_dpp v100, v100, v100 row_mirror row_mask:0xf bank_mask:0xf bound_ctrl:1
	v_fma_mix_f32 v84, -v100, v32, v84 op_sel:[0,0,0] op_sel_hi:[0,1,0]
	v_fma_mix_f32 v85, -v100, v32, v85 op_sel:[0,1,0] op_sel_hi:[0,1,0]
	v_fma_mix_f32 v86, -v100, v33, v86 op_sel:[0,0,0] op_sel_hi:[0,1,0]
	v_fma_mix_f32 v87, -v100, v33, v87 op_sel:[0,1,0] op_sel_hi:[0,1,0]
	v_fma_mix_f32 v101, v84, v30, 0 op_sel:[0,0,0] op_sel_hi:[0,1,0]
	v_fma_mix_f32 v98, v84, v20, 0 op_sel:[0,0,0] op_sel_hi:[0,1,0]
	v_fma_mix_f32 v101, v85, v30, v101 op_sel:[0,1,0] op_sel_hi:[0,1,0]
	v_fma_mix_f32 v98, v85, v20, v98 op_sel:[0,1,0] op_sel_hi:[0,1,0]
	v_fma_mix_f32 v101, v86, v31, v101 op_sel:[0,0,0] op_sel_hi:[0,1,0]
	v_fma_mix_f32 v98, v86, v21, v98 op_sel:[0,0,0] op_sel_hi:[0,1,0]
	v_fma_mix_f32 v101, v87, v31, v101 op_sel:[0,1,0] op_sel_hi:[0,1,0]
	v_fma_mix_f32 v98, v87, v21, v98 op_sel:[0,1,0] op_sel_hi:[0,1,0]
	v_fma_mix_f32 v103, v91, v38, 0 op_sel:[0,0,0] op_sel_hi:[1,1,0]
	v_fma_mix_f32 v104, v91, v38, 0 op_sel:[0,1,0] op_sel_hi:[1,1,0]
	v_add_f32_dpp v101, v101, v101 quad_perm:[1,0,3,2] row_mask:0xf bank_mask:0xf bound_ctrl:1
	v_fma_mix_f32 v105, v91, v39, 0 op_sel:[0,0,0] op_sel_hi:[1,1,0]
	v_fma_mix_f32 v119, v91, v39, 0 op_sel:[0,1,0] op_sel_hi:[1,1,0]
	v_add_f32_dpp v101, v101, v101 quad_perm:[2,3,0,1] row_mask:0xf bank_mask:0xf bound_ctrl:1
	v_fma_mix_f32 v84, v84, v28, v103 op_sel:[0,0,0] op_sel_hi:[0,1,0]
	v_fma_mix_f32 v85, v85, v28, v104 op_sel:[0,1,0] op_sel_hi:[0,1,0]
	v_add_f32_dpp v101, v101, v101 row_half_mirror row_mask:0xf bank_mask:0xf bound_ctrl:1
	v_fma_mix_f32 v86, v86, v29, v105 op_sel:[0,0,0] op_sel_hi:[0,1,0]
	v_fma_mix_f32 v87, v87, v29, v119 op_sel:[0,1,0] op_sel_hi:[0,1,0]
	v_add_f32_dpp v101, v101, v101 row_mirror row_mask:0xf bank_mask:0xf bound_ctrl:1
	v_fma_mix_f32 v84, -v101, v36, v84 op_sel:[0,0,0] op_sel_hi:[0,1,0]
	v_fma_mix_f32 v85, -v101, v36, v85 op_sel:[0,1,0] op_sel_hi:[0,1,0]
	v_fma_mix_f32 v86, -v101, v37, v86 op_sel:[0,0,0] op_sel_hi:[0,1,0]
	v_fma_mix_f32 v87, -v101, v37, v87 op_sel:[0,1,0] op_sel_hi:[0,1,0]
	v_fma_mix_f32 v99, v84, v22, 0 op_sel:[0,0,0] op_sel_hi:[0,1,0]
	v_cndmask_b32_e64 v187, v97, v96, s[38:39]
	v_fma_mix_f32 v99, v85, v22, v99 op_sel:[0,1,0] op_sel_hi:[0,1,0]
	v_cndmask_b32_e64 v188, v96, v97, s[38:39]
	v_fma_mix_f32 v99, v86, v23, v99 op_sel:[0,0,0] op_sel_hi:[0,1,0]
	v_fma_mix_f32 v99, v87, v23, v99 op_sel:[0,1,0] op_sel_hi:[0,1,0]
	v_cndmask_b32_e64 v189, v99, v98, s[38:39]
	v_cndmask_b32_e64 v190, v98, v99, s[38:39]
	s_waitcnt lgkmcnt(0)
	v_fma_mix_f32 v98, v84, v74, 0 op_sel:[0,0,0] op_sel_hi:[0,1,0]
	v_fma_mix_f32 v98, v85, v74, v98 op_sel:[0,1,0] op_sel_hi:[0,1,0]
	v_add_f32_dpp v188, v188, v187 quad_perm:[1,0,3,2] row_mask:0xf bank_mask:0xf bound_ctrl:1
	v_add_f32_dpp v189, v190, v189 quad_perm:[1,0,3,2] row_mask:0xf bank_mask:0xf bound_ctrl:1
	v_fma_mix_f32 v98, v86, v75, v98 op_sel:[0,0,0] op_sel_hi:[0,1,0]
	v_fma_mix_f32 v98, v87, v75, v98 op_sel:[0,1,0] op_sel_hi:[0,1,0]
	v_cndmask_b32_e64 v191, v189, v188, s[40:41]
	v_cndmask_b32_e64 v192, v188, v189, s[40:41]
	v_fma_mix_f32 v100, v92, v78, 0 op_sel:[0,0,0] op_sel_hi:[1,1,0]
	v_fma_mix_f32 v101, v92, v78, 0 op_sel:[0,1,0] op_sel_hi:[1,1,0]
	v_add_f32_dpp v192, v192, v191 quad_perm:[2,3,0,1] row_mask:0xf bank_mask:0xf bound_ctrl:1
	v_add_f32_dpp v98, v98, v98 quad_perm:[1,0,3,2] row_mask:0xf bank_mask:0xf bound_ctrl:1
	v_fma_mix_f32 v102, v92, v79, 0 op_sel:[0,0,0] op_sel_hi:[1,1,0]
	v_add_f32_dpp v192, v192, v192 row_ror:4 row_mask:0xf bank_mask:0xf bound_ctrl:1
	v_fma_mix_f32 v103, v92, v79, 0 op_sel:[0,1,0] op_sel_hi:[1,1,0]
	v_add_f32_dpp v98, v98, v98 quad_perm:[2,3,0,1] row_mask:0xf bank_mask:0xf bound_ctrl:1
	v_add_f32_dpp v192, v192, v192 row_ror:8 row_mask:0xf bank_mask:0xf bound_ctrl:1
	v_cvt_f16_f32_e32 v192, v192
	global_store_short v83, v192, s[36:37]
	s_add_u32 s36, s36, s44
	s_addc_u32 s37, s37, s45
	s_cmp_gt_i32 s35, 5
	s_cbranch_scc0 .Lc_poll_A1
.Lc_ret_A1:
	ds_read_b128 v[0:3], v194 offset:14336
	ds_read_b128 v[4:7], v194 offset:12288
	ds_read_b128 v[8:11], v194 offset:12544
	ds_read_b128 v[12:15], v194 offset:13312
	ds_read_b128 v[16:19], v194 offset:13568
	ds_read_b128 v[20:23], v194 offset:14592
	ds_read_b128 v[24:27], v194 offset:12800
	ds_read_b128 v[28:31], v194 offset:13056
	ds_read_b128 v[32:35], v194 offset:13824
	ds_read_b128 v[36:39], v194 offset:14080
	ds_read_u16 v88, v196 offset:14848
	ds_read_u16 v89, v196 offset:14976
	ds_read_u16 v90, v196 offset:15104
	ds_read_u16 v91, v196 offset:15232
	v_fma_mix_f32 v84, v84, v72, v100 op_sel:[0,0,0] op_sel_hi:[0,1,0]
	v_fma_mix_f32 v85, v85, v72, v101 op_sel:[0,1,0] op_sel_hi:[0,1,0]
	v_add_f32_dpp v98, v98, v98 row_half_mirror row_mask:0xf bank_mask:0xf bound_ctrl:1
	v_fma_mix_f32 v86, v86, v73, v102 op_sel:[0,0,0] op_sel_hi:[0,1,0]
	v_fma_mix_f32 v87, v87, v73, v103 op_sel:[0,1,0] op_sel_hi:[0,1,0]
	v_add_f32_dpp v98, v98, v98 row_mirror row_mask:0xf bank_mask:0xf bound_ctrl:1
	v_fma_mix_f32 v84, -v98, v76, v84 op_sel:[0,0,0] op_sel_hi:[0,1,0]
	v_fma_mix_f32 v85, -v98, v76, v85 op_sel:[0,1,0] op_sel_hi:[0,1,0]
	v_fma_mix_f32 v86, -v98, v77, v86 op_sel:[0,0,0] op_sel_hi:[0,1,0]
	v_fma_mix_f32 v87, -v98, v77, v87 op_sel:[0,1,0] op_sel_hi:[0,1,0]
	v_fma_mix_f32 v73, v84, v66, 0 op_sel:[0,0,0] op_sel_hi:[0,1,0]
	v_fma_mix_f32 v97, v84, v56, 0 op_sel:[0,0,0] op_sel_hi:[0,1,0]
	v_fma_mix_f32 v73, v85, v66, v73 op_sel:[0,1,0] op_sel_hi:[0,1,0]
	v_fma_mix_f32 v56, v85, v56, v97 op_sel:[0,1,0] op_sel_hi:[0,1,0]
	v_fma_mix_f32 v73, v86, v67, v73 op_sel:[0,0,0] op_sel_hi:[0,1,0]
	v_fma_mix_f32 v56, v86, v57, v56 op_sel:[0,0,0] op_sel_hi:[0,1,0]
	v_fma_mix_f32 v73, v87, v67, v73 op_sel:[0,1,0] op_sel_hi:[0,1,0]
	v_fma_mix_f32 v56, v87, v57, v56 op_sel:[0,1,0] op_sel_hi:[0,1,0]
	v_fma_mix_f32 v75, v93, v70, 0 op_sel:[0,0,0] op_sel_hi:[1,1,0]
	v_fma_mix_f32 v76, v93, v70, 0 op_sel:[0,1,0] op_sel_hi:[1,1,0]
	v_add_f32_dpp v73, v73, v73 quad_perm:[1,0,3,2] row_mask:0xf bank_mask:0xf bound_ctrl:1
	v_fma_mix_f32 v77, v93, v71, 0 op_sel:[0,0,0] op_sel_hi:[1,1,0]
	v_fma_mix_f32 v78, v93, v71, 0 op_sel:[0,1,0] op_sel_hi:[1,1,0]
	v_add_f32_dpp v73, v73, v73 quad_perm:[2,3,0,1] row_mask:0xf bank_mask:0xf bound_ctrl:1
	v_fma_mix_f32 v84, v84, v64, v75 op_sel:[0,0,0] op_sel_hi:[0,1,0]
	v_fma_mix_f32 v85, v85, v64, v76 op_sel:[0,1,0] op_sel_hi:[0,1,0]
	v_add_f32_dpp v73, v73, v73 row_half_mirror row_mask:0xf bank_mask:0xf bound_ctrl:1
	v_fma_mix_f32 v86, v86, v65, v77 op_sel:[0,0,0] op_sel_hi:[0,1,0]
	v_fma_mix_f32 v87, v87, v65, v78 op_sel:[0,1,0] op_sel_hi:[0,1,0]
	v_add_f32_dpp v73, v73, v73 row_mirror row_mask:0xf bank_mask:0xf bound_ctrl:1
	v_fma_mix_f32 v84, -v73, v68, v84 op_sel:[0,0,0] op_sel_hi:[0,1,0]
	v_fma_mix_f32 v85, -v73, v68, v85 op_sel:[0,1,0] op_sel_hi:[0,1,0]
	v_fma_mix_f32 v86, -v73, v69, v86 op_sel:[0,0,0] op_sel_hi:[0,1,0]
	v_fma_mix_f32 v87, -v73, v69, v87 op_sel:[0,1,0] op_sel_hi:[0,1,0]
	v_fma_mix_f32 v64, v84, v54, 0 op_sel:[0,0,0] op_sel_hi:[0,1,0]
	v_fma_mix_f32 v57, v84, v58, 0 op_sel:[0,0,0] op_sel_hi:[0,1,0]
	v_fma_mix_f32 v64, v85, v54, v64 op_sel:[0,1,0] op_sel_hi:[0,1,0]
	v_fma_mix_f32 v57, v85, v58, v57 op_sel:[0,1,0] op_sel_hi:[0,1,0]
	v_fma_mix_f32 v64, v86, v55, v64 op_sel:[0,0,0] op_sel_hi:[0,1,0]
	v_fma_mix_f32 v57, v86, v59, v57 op_sel:[0,0,0] op_sel_hi:[0,1,0]
	v_fma_mix_f32 v64, v87, v55, v64 op_sel:[0,1,0] op_sel_hi:[0,1,0]
	v_fma_mix_f32 v57, v87, v59, v57 op_sel:[0,1,0] op_sel_hi:[0,1,0]
	v_fma_mix_f32 v66, v94, v62, 0 op_sel:[0,0,0] op_sel_hi:[1,1,0]
	v_fma_mix_f32 v67, v94, v62, 0 op_sel:[0,1,0] op_sel_hi:[1,1,0]
	v_add_f32_dpp v64, v64, v64 quad_perm:[1,0,3,2] row_mask:0xf bank_mask:0xf bound_ctrl:1
	v_fma_mix_f32 v68, v94, v63, 0 op_sel:[0,0,0] op_sel_hi:[1,1,0]
	v_fma_mix_f32 v69, v94, v63, 0 op_sel:[0,1,0] op_sel_hi:[1,1,0]
	v_add_f32_dpp v64, v64, v64 quad_perm:[2,3,0,1] row_mask:0xf bank_mask:0xf bound_ctrl:1
	v_fma_mix_f32 v84, v84, v52, v66 op_sel:[0,0,0] op_sel_hi:[0,1,0]
	v_fma_mix_f32 v85, v85, v52, v67 op_sel:[0,1,0] op_sel_hi:[0,1,0]
	v_add_f32_dpp v64, v64, v64 row_half_mirror row_mask:0xf bank_mask:0xf bound_ctrl:1
	v_fma_mix_f32 v86, v86, v53, v68 op_sel:[0,0,0] op_sel_hi:[0,1,0]
	v_fma_mix_f32 v87, v87, v53, v69 op_sel:[0,1,0] op_sel_hi:[0,1,0]
	v_add_f32_dpp v64, v64, v64 row_mirror row_mask:0xf bank_mask:0xf bound_ctrl:1
	v_fma_mix_f32 v84, -v64, v60, v84 op_sel:[0,0,0] op_sel_hi:[0,1,0]
	v_fma_mix_f32 v85, -v64, v60, v85 op_sel:[0,1,0] op_sel_hi:[0,1,0]
	v_fma_mix_f32 v86, -v64, v61, v86 op_sel:[0,0,0] op_sel_hi:[0,1,0]
	v_fma_mix_f32 v87, -v64, v61, v87 op_sel:[0,1,0] op_sel_hi:[0,1,0]
	v_fma_mix_f32 v53, v84, v46, 0 op_sel:[0,0,0] op_sel_hi:[0,1,0]
	v_fma_mix_f32 v59, v84, v40, 0 op_sel:[0,0,0] op_sel_hi:[0,1,0]
	v_fma_mix_f32 v53, v85, v46, v53 op_sel:[0,1,0] op_sel_hi:[0,1,0]
	v_fma_mix_f32 v40, v85, v40, v59 op_sel:[0,1,0] op_sel_hi:[0,1,0]
	v_fma_mix_f32 v53, v86, v47, v53 op_sel:[0,0,0] op_sel_hi:[0,1,0]
	v_fma_mix_f32 v40, v86, v41, v40 op_sel:[0,0,0] op_sel_hi:[0,1,0]
	v_fma_mix_f32 v53, v87, v47, v53 op_sel:[0,1,0] op_sel_hi:[0,1,0]
	v_fma_mix_f32 v40, v87, v41, v40 op_sel:[0,1,0] op_sel_hi:[0,1,0]
	v_fma_mix_f32 v55, v95, v50, 0 op_sel:[0,0,0] op_sel_hi:[1,1,0]
	v_fma_mix_f32 v58, v95, v50, 0 op_sel:[0,1,0] op_sel_hi:[1,1,0]
	v_add_f32_dpp v53, v53, v53 quad_perm:[1,0,3,2] row_mask:0xf bank_mask:0xf bound_ctrl:1
	v_fma_mix_f32 v59, v95, v51, 0 op_sel:[0,0,0] op_sel_hi:[1,1,0]
	v_fma_mix_f32 v60, v95, v51, 0 op_sel:[0,1,0] op_sel_hi:[1,1,0]
	v_add_f32_dpp v53, v53, v53 quad_perm:[2,3,0,1] row_mask:0xf bank_mask:0xf bound_ctrl:1
	v_fma_mix_f32 v84, v84, v44, v55 op_sel:[0,0,0] op_sel_hi:[0,1,0]
	v_fma_mix_f32 v85, v85, v44, v58 op_sel:[0,1,0] op_sel_hi:[0,1,0]
	v_add_f32_dpp v53, v53, v53 row_half_mirror row_mask:0xf bank_mask:0xf bound_ctrl:1
	v_fma_mix_f32 v86, v86, v45, v59 op_sel:[0,0,0] op_sel_hi:[0,1,0]
	v_fma_mix_f32 v87, v87, v45, v60 op_sel:[0,1,0] op_sel_hi:[0,1,0]
	v_add_f32_dpp v53, v53, v53 row_mirror row_mask:0xf bank_mask:0xf bound_ctrl:1
	v_fma_mix_f32 v84, -v53, v48, v84 op_sel:[0,0,0] op_sel_hi:[0,1,0]
	v_fma_mix_f32 v85, -v53, v48, v85 op_sel:[0,1,0] op_sel_hi:[0,1,0]
	v_fma_mix_f32 v86, -v53, v49, v86 op_sel:[0,0,0] op_sel_hi:[0,1,0]
	v_fma_mix_f32 v87, -v53, v49, v87 op_sel:[0,1,0] op_sel_hi:[0,1,0]
	v_fma_mix_f32 v41, v84, v42, 0 op_sel:[0,0,0] op_sel_hi:[0,1,0]
	v_add_u32_e32 v173, 4, v193
	v_fma_mix_f32 v41, v85, v42, v41 op_sel:[0,1,0] op_sel_hi:[0,1,0]
	ds_write_b32 v172, v173 offset:49216
	v_fma_mix_f32 v41, v86, v43, v41 op_sel:[0,0,0] op_sel_hi:[0,1,0]
	v_cndmask_b32_e64 v187, v57, v56, s[38:39]
	v_fma_mix_f32 v41, v87, v43, v41 op_sel:[0,1,0] op_sel_hi:[0,1,0]
	v_cndmask_b32_e64 v188, v56, v57, s[38:39]
	v_cndmask_b32_e64 v189, v41, v40, s[38:39]
	v_cndmask_b32_e64 v190, v40, v41, s[38:39]
	s_waitcnt lgkmcnt(1)
	v_fma_mix_f32 v98, v84, v6, 0 op_sel:[0,0,0] op_sel_hi:[0,1,0]
	v_fma_mix_f32 v98, v85, v6, v98 op_sel:[0,1,0] op_sel_hi:[0,1,0]
	v_add_f32_dpp v188, v188, v187 quad_perm:[1,0,3,2] row_mask:0xf bank_mask:0xf bound_ctrl:1
	v_add_f32_dpp v189, v190, v189 quad_perm:[1,0,3,2] row_mask:0xf bank_mask:0xf bound_ctrl:1
	v_fma_mix_f32 v98, v86, v7, v98 op_sel:[0,0,0] op_sel_hi:[0,1,0]
	v_fma_mix_f32 v98, v87, v7, v98 op_sel:[0,1,0] op_sel_hi:[0,1,0]
	v_cndmask_b32_e64 v191, v189, v188, s[40:41]
	v_cndmask_b32_e64 v192, v188, v189, s[40:41]
	v_fma_mix_f32 v100, v88, v14, 0 op_sel:[0,0,0] op_sel_hi:[1,1,0]
	v_fma_mix_f32 v101, v88, v14, 0 op_sel:[0,1,0] op_sel_hi:[1,1,0]
	v_add_f32_dpp v192, v192, v191 quad_perm:[2,3,0,1] row_mask:0xf bank_mask:0xf bound_ctrl:1
	v_add_f32_dpp v98, v98, v98 quad_perm:[1,0,3,2] row_mask:0xf bank_mask:0xf bound_ctrl:1
	v_fma_mix_f32 v102, v88, v15, 0 op_sel:[0,0,0] op_sel_hi:[1,1,0]
	v_add_f32_dpp v192, v192, v192 row_ror:4 row_mask:0xf bank_mask:0xf bound_ctrl:1
	v_fma_mix_f32 v103, v88, v15, 0 op_sel:[0,1,0] op_sel_hi:[1,1,0]
	v_add_f32_dpp v98, v98, v98 quad_perm:[2,3,0,1] row_mask:0xf bank_mask:0xf bound_ctrl:1
	v_add_f32_dpp v192, v192, v192 row_ror:8 row_mask:0xf bank_mask:0xf bound_ctrl:1
	v_cvt_f16_f32_e32 v192, v192
	global_store_short v83, v192, s[36:37]
	s_add_u32 s36, s36, s44
	s_addc_u32 s37, s37, s45
	ds_read_b128 v[56:59], v194 offset:17408
	ds_read_b128 v[72:75], v194 offset:15360
	ds_read_b128 v[64:67], v194 offset:15616
	ds_read_b128 v[76:79], v194 offset:16384
	ds_read_b128 v[68:71], v194 offset:16640
	ds_read_b128 v[40:43], v194 offset:17664
	ds_read_b128 v[52:55], v194 offset:15872
	ds_read_b128 v[44:47], v194 offset:16128
	ds_read_b128 v[60:63], v194 offset:16896
	ds_read_b128 v[48:51], v194 offset:17152
	ds_read_u16 v92, v196 offset:17920
	ds_read_u16 v93, v196 offset:18048
	ds_read_u16 v94, v196 offset:18176
	ds_read_u16 v95, v196 offset:18304
	v_fma_mix_f32 v84, v84, v4, v100 op_sel:[0,0,0] op_sel_hi:[0,1,0]
	v_fma_mix_f32 v85, v85, v4, v101 op_sel:[0,1,0] op_sel_hi:[0,1,0]
	v_add_f32_dpp v98, v98, v98 row_half_mirror row_mask:0xf bank_mask:0xf bound_ctrl:1
	v_fma_mix_f32 v86, v86, v5, v102 op_sel:[0,0,0] op_sel_hi:[0,1,0]
	v_fma_mix_f32 v87, v87, v5, v103 op_sel:[0,1,0] op_sel_hi:[0,1,0]
	v_add_f32_dpp v98, v98, v98 row_mirror row_mask:0xf bank_mask:0xf bound_ctrl:1
	v_fma_mix_f32 v84, -v98, v12, v84 op_sel:[0,0,0] op_sel_hi:[0,1,0]
	v_fma_mix_f32 v85, -v98, v12, v85 op_sel:[0,1,0] op_sel_hi:[0,1,0]
	v_fma_mix_f32 v86, -v98, v13, v86 op_sel:[0,0,0] op_sel_hi:[0,1,0]
	v_fma_mix_f32 v87, -v98, v13, v87 op_sel:[0,1,0] op_sel_hi:[0,1,0]
	v_fma_mix_f32 v99, v84, v10, 0 op_sel:[0,0,0] op_sel_hi:[0,1,0]
	v_fma_mix_f32 v96, v84, v0, 0 op_sel:[0,0,0] op_sel_hi:[0,1,0]
	v_fma_mix_f32 v99, v85, v10, v99 op_sel:[0,1,0] op_sel_hi:[0,1,0]
	v_fma_mix_f32 v96, v85, v0, v96 op_sel:[0,1,0] op_sel_hi:[0,1,0]
	v_fma_mix_f32 v99, v86, v11, v99 op_sel:[0,0,0] op_sel_hi:[0,1,0]
	v_fma_mix_f32 v96, v86, v1, v96 op_sel:[0,0,0] op_sel_hi:[0,1,0]
	v_fma_mix_f32 v99, v87, v11, v99 op_sel:[0,1,0] op_sel_hi:[0,1,0]
	v_fma_mix_f32 v96, v87, v1, v96 op_sel:[0,1,0] op_sel_hi:[0,1,0]
	v_fma_mix_f32 v101, v89, v18, 0 op_sel:[0,0,0] op_sel_hi:[1,1,0]
	v_fma_mix_f32 v102, v89, v18, 0 op_sel:[0,1,0] op_sel_hi:[1,1,0]
	v_add_f32_dpp v99, v99, v99 quad_perm:[1,0,3,2] row_mask:0xf bank_mask:0xf bound_ctrl:1
	v_fma_mix_f32 v103, v89, v19, 0 op_sel:[0,0,0] op_sel_hi:[1,1,0]
	v_fma_mix_f32 v104, v89, v19, 0 op_sel:[0,1,0] op_sel_hi:[1,1,0]
	v_add_f32_dpp v99, v99, v99 quad_perm:[2,3,0,1] row_mask:0xf bank_mask:0xf bound_ctrl:1
	v_fma_mix_f32 v84, v84, v8, v101 op_sel:[0,0,0] op_sel_hi:[0,1,0]
	v_fma_mix_f32 v85, v85, v8, v102 op_sel:[0,1,0] op_sel_hi:[0,1,0]
	v_add_f32_dpp v99, v99, v99 row_half_mirror row_mask:0xf bank_mask:0xf bound_ctrl:1
	v_fma_mix_f32 v86, v86, v9, v103 op_sel:[0,0,0] op_sel_hi:[0,1,0]
	v_fma_mix_f32 v87, v87, v9, v104 op_sel:[0,1,0] op_sel_hi:[0,1,0]
	v_add_f32_dpp v99, v99, v99 row_mirror row_mask:0xf bank_mask:0xf bound_ctrl:1
	v_fma_mix_f32 v84, -v99, v16, v84 op_sel:[0,0,0] op_sel_hi:[0,1,0]
	v_fma_mix_f32 v85, -v99, v16, v85 op_sel:[0,1,0] op_sel_hi:[0,1,0]
	v_fma_mix_f32 v86, -v99, v17, v86 op_sel:[0,0,0] op_sel_hi:[0,1,0]
	v_fma_mix_f32 v87, -v99, v17, v87 op_sel:[0,1,0] op_sel_hi:[0,1,0]
	v_fma_mix_f32 v100, v84, v26, 0 op_sel:[0,0,0] op_sel_hi:[0,1,0]
	v_fma_mix_f32 v97, v84, v2, 0 op_sel:[0,0,0] op_sel_hi:[0,1,0]
	v_fma_mix_f32 v100, v85, v26, v100 op_sel:[0,1,0] op_sel_hi:[0,1,0]
	v_fma_mix_f32 v97, v85, v2, v97 op_sel:[0,1,0] op_sel_hi:[0,1,0]
	v_fma_mix_f32 v100, v86, v27, v100 op_sel:[0,0,0] op_sel_hi:[0,1,0]
	v_fma_mix_f32 v97, v86, v3, v97 op_sel:[0,0,0] op_sel_hi:[0,1,0]
	v_fma_mix_f32 v100, v87, v27, v100 op_sel:[0,1,0] op_sel_hi:[0,1,0]
	v_fma_mix_f32 v97, v87, v3, v97 op_sel:[0,1,0] op_sel_hi:[0,1,0]
	v_fma_mix_f32 v102, v90, v34, 0 op_sel:[0,0,0] op_sel_hi:[1,1,0]
	v_fma_mix_f32 v103, v90, v34, 0 op_sel:[0,1,0] op_sel_hi:[1,1,0]
	v_add_f32_dpp v100, v100, v100 quad_perm:[1,0,3,2] row_mask:0xf bank_mask:0xf bound_ctrl:1
	v_fma_mix_f32 v104, v90, v35, 0 op_sel:[0,0,0] op_sel_hi:[1,1,0]
	v_fma_mix_f32 v105, v90, v35, 0 op_sel:[0,1,0] op_sel_hi:[1,1,0]
	v_add_f32_dpp v100, v100, v100 quad_perm:[2,3,0,1] row_mask:0xf bank_mask:0xf bound_ctrl:1
	v_fma_mix_f32 v84, v84, v24, v102 op_sel:[0,0,0] op_sel_hi:[0,1,0]
	v_fma_mix_f32 v85, v85, v24, v103 op_sel:[0,1,0] op_sel_hi:[0,1,0]
	v_add_f32_dpp v100, v100, v100 row_half_mirror row_mask:0xf bank_mask:0xf bound_ctrl:1
	v_fma_mix_f32 v86, v86, v25, v104 op_sel:[0,0,0] op_sel_hi:[0,1,0]
	v_fma_mix_f32 v87, v87, v25, v105 op_sel:[0,1,0] op_sel_hi:[0,1,0]
	v_add_f32_dpp v100, v100, v100 row_mirror row_mask:0xf bank_mask:0xf bound_ctrl:1
	v_fma_mix_f32 v84, -v100, v32, v84 op_sel:[0,0,0] op_sel_hi:[0,1,0]
	v_fma_mix_f32 v85, -v100, v32, v85 op_sel:[0,1,0] op_sel_hi:[0,1,0]
	v_fma_mix_f32 v86, -v100, v33, v86 op_sel:[0,0,0] op_sel_hi:[0,1,0]
	v_fma_mix_f32 v87, -v100, v33, v87 op_sel:[0,1,0] op_sel_hi:[0,1,0]
	v_fma_mix_f32 v101, v84, v30, 0 op_sel:[0,0,0] op_sel_hi:[0,1,0]
	v_fma_mix_f32 v98, v84, v20, 0 op_sel:[0,0,0] op_sel_hi:[0,1,0]
	v_fma_mix_f32 v101, v85, v30, v101 op_sel:[0,1,0] op_sel_hi:[0,1,0]
	v_fma_mix_f32 v98, v85, v20, v98 op_sel:[0,1,0] op_sel_hi:[0,1,0]
	v_fma_mix_f32 v101, v86, v31, v101 op_sel:[0,0,0] op_sel_hi:[0,1,0]
	v_fma_mix_f32 v98, v86, v21, v98 op_sel:[0,0,0] op_sel_hi:[0,1,0]
	v_fma_mix_f32 v101, v87, v31, v101 op_sel:[0,1,0] op_sel_hi:[0,1,0]
	v_fma_mix_f32 v98, v87, v21, v98 op_sel:[0,1,0] op_sel_hi:[0,1,0]
	v_fma_mix_f32 v103, v91, v38, 0 op_sel:[0,0,0] op_sel_hi:[1,1,0]
	v_fma_mix_f32 v104, v91, v38, 0 op_sel:[0,1,0] op_sel_hi:[1,1,0]
	v_add_f32_dpp v101, v101, v101 quad_perm:[1,0,3,2] row_mask:0xf bank_mask:0xf bound_ctrl:1
	v_fma_mix_f32 v105, v91, v39, 0 op_sel:[0,0,0] op_sel_hi:[1,1,0]
	v_fma_mix_f32 v119, v91, v39, 0 op_sel:[0,1,0] op_sel_hi:[1,1,0]
	v_add_f32_dpp v101, v101, v101 quad_perm:[2,3,0,1] row_mask:0xf bank_mask:0xf bound_ctrl:1
	v_fma_mix_f32 v84, v84, v28, v103 op_sel:[0,0,0] op_sel_hi:[0,1,0]
	v_fma_mix_f32 v85, v85, v28, v104 op_sel:[0,1,0] op_sel_hi:[0,1,0]
	v_add_f32_dpp v101, v101, v101 row_half_mirror row_mask:0xf bank_mask:0xf bound_ctrl:1
	v_fma_mix_f32 v86, v86, v29, v105 op_sel:[0,0,0] op_sel_hi:[0,1,0]
	v_fma_mix_f32 v87, v87, v29, v119 op_sel:[0,1,0] op_sel_hi:[0,1,0]
	v_add_f32_dpp v101, v101, v101 row_mirror row_mask:0xf bank_mask:0xf bound_ctrl:1
	v_fma_mix_f32 v84, -v101, v36, v84 op_sel:[0,0,0] op_sel_hi:[0,1,0]
	v_fma_mix_f32 v85, -v101, v36, v85 op_sel:[0,1,0] op_sel_hi:[0,1,0]
	v_fma_mix_f32 v86, -v101, v37, v86 op_sel:[0,0,0] op_sel_hi:[0,1,0]
	v_fma_mix_f32 v87, -v101, v37, v87 op_sel:[0,1,0] op_sel_hi:[0,1,0]
	v_fma_mix_f32 v99, v84, v22, 0 op_sel:[0,0,0] op_sel_hi:[0,1,0]
	v_cndmask_b32_e64 v187, v97, v96, s[38:39]
	v_fma_mix_f32 v99, v85, v22, v99 op_sel:[0,1,0] op_sel_hi:[0,1,0]
	v_cndmask_b32_e64 v188, v96, v97, s[38:39]
	v_fma_mix_f32 v99, v86, v23, v99 op_sel:[0,0,0] op_sel_hi:[0,1,0]
	v_fma_mix_f32 v99, v87, v23, v99 op_sel:[0,1,0] op_sel_hi:[0,1,0]
	v_cndmask_b32_e64 v189, v99, v98, s[38:39]
	v_cndmask_b32_e64 v190, v98, v99, s[38:39]
	s_waitcnt lgkmcnt(0)
	v_fma_mix_f32 v98, v84, v74, 0 op_sel:[0,0,0] op_sel_hi:[0,1,0]
	v_fma_mix_f32 v98, v85, v74, v98 op_sel:[0,1,0] op_sel_hi:[0,1,0]
	v_add_f32_dpp v188, v188, v187 quad_perm:[1,0,3,2] row_mask:0xf bank_mask:0xf bound_ctrl:1
	v_add_f32_dpp v189, v190, v189 quad_perm:[1,0,3,2] row_mask:0xf bank_mask:0xf bound_ctrl:1
	v_fma_mix_f32 v98, v86, v75, v98 op_sel:[0,0,0] op_sel_hi:[0,1,0]
	v_fma_mix_f32 v98, v87, v75, v98 op_sel:[0,1,0] op_sel_hi:[0,1,0]
	v_cndmask_b32_e64 v191, v189, v188, s[40:41]
	v_cndmask_b32_e64 v192, v188, v189, s[40:41]
	v_fma_mix_f32 v100, v92, v78, 0 op_sel:[0,0,0] op_sel_hi:[1,1,0]
	v_fma_mix_f32 v101, v92, v78, 0 op_sel:[0,1,0] op_sel_hi:[1,1,0]
	v_add_f32_dpp v192, v192, v191 quad_perm:[2,3,0,1] row_mask:0xf bank_mask:0xf bound_ctrl:1
	v_add_f32_dpp v98, v98, v98 quad_perm:[1,0,3,2] row_mask:0xf bank_mask:0xf bound_ctrl:1
	v_fma_mix_f32 v102, v92, v79, 0 op_sel:[0,0,0] op_sel_hi:[1,1,0]
	v_add_f32_dpp v192, v192, v192 row_ror:4 row_mask:0xf bank_mask:0xf bound_ctrl:1
	v_fma_mix_f32 v103, v92, v79, 0 op_sel:[0,1,0] op_sel_hi:[1,1,0]
	v_add_f32_dpp v98, v98, v98 quad_perm:[2,3,0,1] row_mask:0xf bank_mask:0xf bound_ctrl:1
	v_add_f32_dpp v192, v192, v192 row_ror:8 row_mask:0xf bank_mask:0xf bound_ctrl:1
	v_cvt_f16_f32_e32 v192, v192
	global_store_short v83, v192, s[36:37]
	s_add_u32 s36, s36, s44
	s_addc_u32 s37, s37, s45
	s_cmp_gt_i32 s35, 7
	s_cbranch_scc0 .Lc_poll_A2
.Lc_ret_A2:
	ds_read_b128 v[0:3], v194 offset:20480
	ds_read_b128 v[4:7], v194 offset:18432
	ds_read_b128 v[8:11], v194 offset:18688
	ds_read_b128 v[12:15], v194 offset:19456
	ds_read_b128 v[16:19], v194 offset:19712
	ds_read_b128 v[20:23], v194 offset:20736
	ds_read_b128 v[24:27], v194 offset:18944
	ds_read_b128 v[28:31], v194 offset:19200
	ds_read_b128 v[32:35], v194 offset:19968
	ds_read_b128 v[36:39], v194 offset:20224
	ds_read_u16 v88, v196 offset:20992
	ds_read_u16 v89, v196 offset:21120
	ds_read_u16 v90, v196 offset:21248
	ds_read_u16 v91, v196 offset:21376
	v_fma_mix_f32 v84, v84, v72, v100 op_sel:[0,0,0] op_sel_hi:[0,1,0]
	v_fma_mix_f32 v85, v85, v72, v101 op_sel:[0,1,0] op_sel_hi:[0,1,0]
	v_add_f32_dpp v98, v98, v98 row_half_mirror row_mask:0xf bank_mask:0xf bound_ctrl:1
	v_fma_mix_f32 v86, v86, v73, v102 op_sel:[0,0,0] op_sel_hi:[0,1,0]
	v_fma_mix_f32 v87, v87, v73, v103 op_sel:[0,1,0] op_sel_hi:[0,1,0]
	v_add_f32_dpp v98, v98, v98 row_mirror row_mask:0xf bank_mask:0xf bound_ctrl:1
	v_fma_mix_f32 v84, -v98, v76, v84 op_sel:[0,0,0] op_sel_hi:[0,1,0]
	v_fma_mix_f32 v85, -v98, v76, v85 op_sel:[0,1,0] op_sel_hi:[0,1,0]
	v_fma_mix_f32 v86, -v98, v77, v86 op_sel:[0,0,0] op_sel_hi:[0,1,0]
	v_fma_mix_f32 v87, -v98, v77, v87 op_sel:[0,1,0] op_sel_hi:[0,1,0]
	v_fma_mix_f32 v73, v84, v66, 0 op_sel:[0,0,0] op_sel_hi:[0,1,0]
	v_fma_mix_f32 v97, v84, v56, 0 op_sel:[0,0,0] op_sel_hi:[0,1,0]
	v_fma_mix_f32 v73, v85, v66, v73 op_sel:[0,1,0] op_sel_hi:[0,1,0]
	v_fma_mix_f32 v56, v85, v56, v97 op_sel:[0,1,0] op_sel_hi:[0,1,0]
	v_fma_mix_f32 v73, v86, v67, v73 op_sel:[0,0,0] op_sel_hi:[0,1,0]
	v_fma_mix_f32 v56, v86, v57, v56 op_sel:[0,0,0] op_sel_hi:[0,1,0]
	v_fma_mix_f32 v73, v87, v67, v73 op_sel:[0,1,0] op_sel_hi:[0,1,0]
	v_fma_mix_f32 v56, v87, v57, v56 op_sel:[0,1,0] op_sel_hi:[0,1,0]
	v_fma_mix_f32 v75, v93, v70, 0 op_sel:[0,0,0] op_sel_hi:[1,1,0]
	v_fma_mix_f32 v76, v93, v70, 0 op_sel:[0,1,0] op_sel_hi:[1,1,0]
	v_add_f32_dpp v73, v73, v73 quad_perm:[1,0,3,2] row_mask:0xf bank_mask:0xf bound_ctrl:1
	v_fma_mix_f32 v77, v93, v71, 0 op_sel:[0,0,0] op_sel_hi:[1,1,0]
	v_fma_mix_f32 v78, v93, v71, 0 op_sel:[0,1,0] op_sel_hi:[1,1,0]
	v_add_f32_dpp v73, v73, v73 quad_perm:[2,3,0,1] row_mask:0xf bank_mask:0xf bound_ctrl:1
	v_fma_mix_f32 v84, v84, v64, v75 op_sel:[0,0,0] op_sel_hi:[0,1,0]
	v_fma_mix_f32 v85, v85, v64, v76 op_sel:[0,1,0] op_sel_hi:[0,1,0]
	v_add_f32_dpp v73, v73, v73 row_half_mirror row_mask:0xf bank_mask:0xf bound_ctrl:1
	v_fma_mix_f32 v86, v86, v65, v77 op_sel:[0,0,0] op_sel_hi:[0,1,0]
	v_fma_mix_f32 v87, v87, v65, v78 op_sel:[0,1,0] op_sel_hi:[0,1,0]
	v_add_f32_dpp v73, v73, v73 row_mirror row_mask:0xf bank_mask:0xf bound_ctrl:1
	v_fma_mix_f32 v84, -v73, v68, v84 op_sel:[0,0,0] op_sel_hi:[0,1,0]
	v_fma_mix_f32 v85, -v73, v68, v85 op_sel:[0,1,0] op_sel_hi:[0,1,0]
	v_fma_mix_f32 v86, -v73, v69, v86 op_sel:[0,0,0] op_sel_hi:[0,1,0]
	v_fma_mix_f32 v87, -v73, v69, v87 op_sel:[0,1,0] op_sel_hi:[0,1,0]
	v_fma_mix_f32 v64, v84, v54, 0 op_sel:[0,0,0] op_sel_hi:[0,1,0]
	v_fma_mix_f32 v57, v84, v58, 0 op_sel:[0,0,0] op_sel_hi:[0,1,0]
	v_fma_mix_f32 v64, v85, v54, v64 op_sel:[0,1,0] op_sel_hi:[0,1,0]
	v_fma_mix_f32 v57, v85, v58, v57 op_sel:[0,1,0] op_sel_hi:[0,1,0]
	v_fma_mix_f32 v64, v86, v55, v64 op_sel:[0,0,0] op_sel_hi:[0,1,0]
	v_fma_mix_f32 v57, v86, v59, v57 op_sel:[0,0,0] op_sel_hi:[0,1,0]
	v_fma_mix_f32 v64, v87, v55, v64 op_sel:[0,1,0] op_sel_hi:[0,1,0]
	v_fma_mix_f32 v57, v87, v59, v57 op_sel:[0,1,0] op_sel_hi:[0,1,0]
	v_fma_mix_f32 v66, v94, v62, 0 op_sel:[0,0,0] op_sel_hi:[1,1,0]
	v_fma_mix_f32 v67, v94, v62, 0 op_sel:[0,1,0] op_sel_hi:[1,1,0]
	v_add_f32_dpp v64, v64, v64 quad_perm:[1,0,3,2] row_mask:0xf bank_mask:0xf bound_ctrl:1
	v_fma_mix_f32 v68, v94, v63, 0 op_sel:[0,0,0] op_sel_hi:[1,1,0]
	v_fma_mix_f32 v69, v94, v63, 0 op_sel:[0,1,0] op_sel_hi:[1,1,0]
	v_add_f32_dpp v64, v64, v64 quad_perm:[2,3,0,1] row_mask:0xf bank_mask:0xf bound_ctrl:1
	v_fma_mix_f32 v84, v84, v52, v66 op_sel:[0,0,0] op_sel_hi:[0,1,0]
	v_fma_mix_f32 v85, v85, v52, v67 op_sel:[0,1,0] op_sel_hi:[0,1,0]
	v_add_f32_dpp v64, v64, v64 row_half_mirror row_mask:0xf bank_mask:0xf bound_ctrl:1
	v_fma_mix_f32 v86, v86, v53, v68 op_sel:[0,0,0] op_sel_hi:[0,1,0]
	v_fma_mix_f32 v87, v87, v53, v69 op_sel:[0,1,0] op_sel_hi:[0,1,0]
	v_add_f32_dpp v64, v64, v64 row_mirror row_mask:0xf bank_mask:0xf bound_ctrl:1
	v_fma_mix_f32 v84, -v64, v60, v84 op_sel:[0,0,0] op_sel_hi:[0,1,0]
	v_fma_mix_f32 v85, -v64, v60, v85 op_sel:[0,1,0] op_sel_hi:[0,1,0]
	v_fma_mix_f32 v86, -v64, v61, v86 op_sel:[0,0,0] op_sel_hi:[0,1,0]
	v_fma_mix_f32 v87, -v64, v61, v87 op_sel:[0,1,0] op_sel_hi:[0,1,0]
	v_fma_mix_f32 v53, v84, v46, 0 op_sel:[0,0,0] op_sel_hi:[0,1,0]
	v_fma_mix_f32 v59, v84, v40, 0 op_sel:[0,0,0] op_sel_hi:[0,1,0]
	v_fma_mix_f32 v53, v85, v46, v53 op_sel:[0,1,0] op_sel_hi:[0,1,0]
	v_fma_mix_f32 v40, v85, v40, v59 op_sel:[0,1,0] op_sel_hi:[0,1,0]
	v_fma_mix_f32 v53, v86, v47, v53 op_sel:[0,0,0] op_sel_hi:[0,1,0]
	v_fma_mix_f32 v40, v86, v41, v40 op_sel:[0,0,0] op_sel_hi:[0,1,0]
	v_fma_mix_f32 v53, v87, v47, v53 op_sel:[0,1,0] op_sel_hi:[0,1,0]
	v_fma_mix_f32 v40, v87, v41, v40 op_sel:[0,1,0] op_sel_hi:[0,1,0]
	v_fma_mix_f32 v55, v95, v50, 0 op_sel:[0,0,0] op_sel_hi:[1,1,0]
	v_fma_mix_f32 v58, v95, v50, 0 op_sel:[0,1,0] op_sel_hi:[1,1,0]
	v_add_f32_dpp v53, v53, v53 quad_perm:[1,0,3,2] row_mask:0xf bank_mask:0xf bound_ctrl:1
	v_fma_mix_f32 v59, v95, v51, 0 op_sel:[0,0,0] op_sel_hi:[1,1,0]
	v_fma_mix_f32 v60, v95, v51, 0 op_sel:[0,1,0] op_sel_hi:[1,1,0]
	v_add_f32_dpp v53, v53, v53 quad_perm:[2,3,0,1] row_mask:0xf bank_mask:0xf bound_ctrl:1
	v_fma_mix_f32 v84, v84, v44, v55 op_sel:[0,0,0] op_sel_hi:[0,1,0]
	v_fma_mix_f32 v85, v85, v44, v58 op_sel:[0,1,0] op_sel_hi:[0,1,0]
	v_add_f32_dpp v53, v53, v53 row_half_mirror row_mask:0xf bank_mask:0xf bound_ctrl:1
	v_fma_mix_f32 v86, v86, v45, v59 op_sel:[0,0,0] op_sel_hi:[0,1,0]
	v_fma_mix_f32 v87, v87, v45, v60 op_sel:[0,1,0] op_sel_hi:[0,1,0]
	v_add_f32_dpp v53, v53, v53 row_mirror row_mask:0xf bank_mask:0xf bound_ctrl:1
	v_fma_mix_f32 v84, -v53, v48, v84 op_sel:[0,0,0] op_sel_hi:[0,1,0]
	v_fma_mix_f32 v85, -v53, v48, v85 op_sel:[0,1,0] op_sel_hi:[0,1,0]
	v_fma_mix_f32 v86, -v53, v49, v86 op_sel:[0,0,0] op_sel_hi:[0,1,0]
	v_fma_mix_f32 v87, -v53, v49, v87 op_sel:[0,1,0] op_sel_hi:[0,1,0]
	v_fma_mix_f32 v41, v84, v42, 0 op_sel:[0,0,0] op_sel_hi:[0,1,0]
	v_cndmask_b32_e64 v187, v57, v56, s[38:39]
	v_fma_mix_f32 v41, v85, v42, v41 op_sel:[0,1,0] op_sel_hi:[0,1,0]
	v_cndmask_b32_e64 v188, v56, v57, s[38:39]
	v_fma_mix_f32 v41, v86, v43, v41 op_sel:[0,0,0] op_sel_hi:[0,1,0]
	v_fma_mix_f32 v41, v87, v43, v41 op_sel:[0,1,0] op_sel_hi:[0,1,0]
	v_cndmask_b32_e64 v189, v41, v40, s[38:39]
	v_cndmask_b32_e64 v190, v40, v41, s[38:39]
	s_waitcnt lgkmcnt(0)
	v_fma_mix_f32 v98, v84, v6, 0 op_sel:[0,0,0] op_sel_hi:[0,1,0]
	v_fma_mix_f32 v98, v85, v6, v98 op_sel:[0,1,0] op_sel_hi:[0,1,0]
	v_add_f32_dpp v188, v188, v187 quad_perm:[1,0,3,2] row_mask:0xf bank_mask:0xf bound_ctrl:1
	v_add_f32_dpp v189, v190, v189 quad_perm:[1,0,3,2] row_mask:0xf bank_mask:0xf bound_ctrl:1
	v_fma_mix_f32 v98, v86, v7, v98 op_sel:[0,0,0] op_sel_hi:[0,1,0]
	v_fma_mix_f32 v98, v87, v7, v98 op_sel:[0,1,0] op_sel_hi:[0,1,0]
	v_cndmask_b32_e64 v191, v189, v188, s[40:41]
	v_cndmask_b32_e64 v192, v188, v189, s[40:41]
	v_fma_mix_f32 v100, v88, v14, 0 op_sel:[0,0,0] op_sel_hi:[1,1,0]
	v_fma_mix_f32 v101, v88, v14, 0 op_sel:[0,1,0] op_sel_hi:[1,1,0]
	v_add_f32_dpp v192, v192, v191 quad_perm:[2,3,0,1] row_mask:0xf bank_mask:0xf bound_ctrl:1
	v_add_f32_dpp v98, v98, v98 quad_perm:[1,0,3,2] row_mask:0xf bank_mask:0xf bound_ctrl:1
	v_fma_mix_f32 v102, v88, v15, 0 op_sel:[0,0,0] op_sel_hi:[1,1,0]
	v_add_f32_dpp v192, v192, v192 row_ror:4 row_mask:0xf bank_mask:0xf bound_ctrl:1
	v_fma_mix_f32 v103, v88, v15, 0 op_sel:[0,1,0] op_sel_hi:[1,1,0]
	v_add_f32_dpp v98, v98, v98 quad_perm:[2,3,0,1] row_mask:0xf bank_mask:0xf bound_ctrl:1
	v_add_f32_dpp v192, v192, v192 row_ror:8 row_mask:0xf bank_mask:0xf bound_ctrl:1
	v_cvt_f16_f32_e32 v192, v192
	global_store_short v83, v192, s[36:37]
	s_add_u32 s36, s36, s44
	s_addc_u32 s37, s37, s45
	ds_read_b128 v[56:59], v194 offset:23552
	ds_read_b128 v[72:75], v194 offset:21504
	ds_read_b128 v[64:67], v194 offset:21760
	ds_read_b128 v[76:79], v194 offset:22528
	ds_read_b128 v[68:71], v194 offset:22784
	ds_read_b128 v[40:43], v194 offset:23808
	ds_read_b128 v[52:55], v194 offset:22016
	ds_read_b128 v[44:47], v194 offset:22272
	ds_read_b128 v[60:63], v194 offset:23040
	ds_read_b128 v[48:51], v194 offset:23296
	ds_read_u16 v92, v196 offset:24064
	ds_read_u16 v93, v196 offset:24192
	ds_read_u16 v94, v196 offset:24320
	ds_read_u16 v95, v196 offset:24448
	v_fma_mix_f32 v84, v84, v4, v100 op_sel:[0,0,0] op_sel_hi:[0,1,0]
	v_fma_mix_f32 v85, v85, v4, v101 op_sel:[0,1,0] op_sel_hi:[0,1,0]
	v_add_f32_dpp v98, v98, v98 row_half_mirror row_mask:0xf bank_mask:0xf bound_ctrl:1
	v_fma_mix_f32 v86, v86, v5, v102 op_sel:[0,0,0] op_sel_hi:[0,1,0]
	v_fma_mix_f32 v87, v87, v5, v103 op_sel:[0,1,0] op_sel_hi:[0,1,0]
	v_add_f32_dpp v98, v98, v98 row_mirror row_mask:0xf bank_mask:0xf bound_ctrl:1
	v_fma_mix_f32 v84, -v98, v12, v84 op_sel:[0,0,0] op_sel_hi:[0,1,0]
	v_fma_mix_f32 v85, -v98, v12, v85 op_sel:[0,1,0] op_sel_hi:[0,1,0]
	v_fma_mix_f32 v86, -v98, v13, v86 op_sel:[0,0,0] op_sel_hi:[0,1,0]
	v_fma_mix_f32 v87, -v98, v13, v87 op_sel:[0,1,0] op_sel_hi:[0,1,0]
	v_fma_mix_f32 v99, v84, v10, 0 op_sel:[0,0,0] op_sel_hi:[0,1,0]
	v_fma_mix_f32 v96, v84, v0, 0 op_sel:[0,0,0] op_sel_hi:[0,1,0]
	v_fma_mix_f32 v99, v85, v10, v99 op_sel:[0,1,0] op_sel_hi:[0,1,0]
	v_fma_mix_f32 v96, v85, v0, v96 op_sel:[0,1,0] op_sel_hi:[0,1,0]
	v_fma_mix_f32 v99, v86, v11, v99 op_sel:[0,0,0] op_sel_hi:[0,1,0]
	v_fma_mix_f32 v96, v86, v1, v96 op_sel:[0,0,0] op_sel_hi:[0,1,0]
	v_fma_mix_f32 v99, v87, v11, v99 op_sel:[0,1,0] op_sel_hi:[0,1,0]
	v_fma_mix_f32 v96, v87, v1, v96 op_sel:[0,1,0] op_sel_hi:[0,1,0]
	v_fma_mix_f32 v101, v89, v18, 0 op_sel:[0,0,0] op_sel_hi:[1,1,0]
	v_fma_mix_f32 v102, v89, v18, 0 op_sel:[0,1,0] op_sel_hi:[1,1,0]
	v_add_f32_dpp v99, v99, v99 quad_perm:[1,0,3,2] row_mask:0xf bank_mask:0xf bound_ctrl:1
	v_fma_mix_f32 v103, v89, v19, 0 op_sel:[0,0,0] op_sel_hi:[1,1,0]
	v_fma_mix_f32 v104, v89, v19, 0 op_sel:[0,1,0] op_sel_hi:[1,1,0]
	v_add_f32_dpp v99, v99, v99 quad_perm:[2,3,0,1] row_mask:0xf bank_mask:0xf bound_ctrl:1
	v_fma_mix_f32 v84, v84, v8, v101 op_sel:[0,0,0] op_sel_hi:[0,1,0]
	v_fma_mix_f32 v85, v85, v8, v102 op_sel:[0,1,0] op_sel_hi:[0,1,0]
	v_add_f32_dpp v99, v99, v99 row_half_mirror row_mask:0xf bank_mask:0xf bound_ctrl:1
	v_fma_mix_f32 v86, v86, v9, v103 op_sel:[0,0,0] op_sel_hi:[0,1,0]
	v_fma_mix_f32 v87, v87, v9, v104 op_sel:[0,1,0] op_sel_hi:[0,1,0]
	v_add_f32_dpp v99, v99, v99 row_mirror row_mask:0xf bank_mask:0xf bound_ctrl:1
	v_fma_mix_f32 v84, -v99, v16, v84 op_sel:[0,0,0] op_sel_hi:[0,1,0]
	v_fma_mix_f32 v85, -v99, v16, v85 op_sel:[0,1,0] op_sel_hi:[0,1,0]
	v_fma_mix_f32 v86, -v99, v17, v86 op_sel:[0,0,0] op_sel_hi:[0,1,0]
	v_fma_mix_f32 v87, -v99, v17, v87 op_sel:[0,1,0] op_sel_hi:[0,1,0]
	v_fma_mix_f32 v100, v84, v26, 0 op_sel:[0,0,0] op_sel_hi:[0,1,0]
	v_fma_mix_f32 v97, v84, v2, 0 op_sel:[0,0,0] op_sel_hi:[0,1,0]
	v_fma_mix_f32 v100, v85, v26, v100 op_sel:[0,1,0] op_sel_hi:[0,1,0]
	v_fma_mix_f32 v97, v85, v2, v97 op_sel:[0,1,0] op_sel_hi:[0,1,0]
	v_fma_mix_f32 v100, v86, v27, v100 op_sel:[0,0,0] op_sel_hi:[0,1,0]
	v_fma_mix_f32 v97, v86, v3, v97 op_sel:[0,0,0] op_sel_hi:[0,1,0]
	v_fma_mix_f32 v100, v87, v27, v100 op_sel:[0,1,0] op_sel_hi:[0,1,0]
	v_fma_mix_f32 v97, v87, v3, v97 op_sel:[0,1,0] op_sel_hi:[0,1,0]
	v_fma_mix_f32 v102, v90, v34, 0 op_sel:[0,0,0] op_sel_hi:[1,1,0]
	v_fma_mix_f32 v103, v90, v34, 0 op_sel:[0,1,0] op_sel_hi:[1,1,0]
	v_add_f32_dpp v100, v100, v100 quad_perm:[1,0,3,2] row_mask:0xf bank_mask:0xf bound_ctrl:1
	v_fma_mix_f32 v104, v90, v35, 0 op_sel:[0,0,0] op_sel_hi:[1,1,0]
	v_fma_mix_f32 v105, v90, v35, 0 op_sel:[0,1,0] op_sel_hi:[1,1,0]
	v_add_f32_dpp v100, v100, v100 quad_perm:[2,3,0,1] row_mask:0xf bank_mask:0xf bound_ctrl:1
	v_fma_mix_f32 v84, v84, v24, v102 op_sel:[0,0,0] op_sel_hi:[0,1,0]
	v_fma_mix_f32 v85, v85, v24, v103 op_sel:[0,1,0] op_sel_hi:[0,1,0]
	v_add_f32_dpp v100, v100, v100 row_half_mirror row_mask:0xf bank_mask:0xf bound_ctrl:1
	v_fma_mix_f32 v86, v86, v25, v104 op_sel:[0,0,0] op_sel_hi:[0,1,0]
	v_fma_mix_f32 v87, v87, v25, v105 op_sel:[0,1,0] op_sel_hi:[0,1,0]
	v_add_f32_dpp v100, v100, v100 row_mirror row_mask:0xf bank_mask:0xf bound_ctrl:1
	v_fma_mix_f32 v84, -v100, v32, v84 op_sel:[0,0,0] op_sel_hi:[0,1,0]
	v_fma_mix_f32 v85, -v100, v32, v85 op_sel:[0,1,0] op_sel_hi:[0,1,0]
	v_fma_mix_f32 v86, -v100, v33, v86 op_sel:[0,0,0] op_sel_hi:[0,1,0]
	v_fma_mix_f32 v87, -v100, v33, v87 op_sel:[0,1,0] op_sel_hi:[0,1,0]
	v_fma_mix_f32 v101, v84, v30, 0 op_sel:[0,0,0] op_sel_hi:[0,1,0]
	v_fma_mix_f32 v98, v84, v20, 0 op_sel:[0,0,0] op_sel_hi:[0,1,0]
	v_fma_mix_f32 v101, v85, v30, v101 op_sel:[0,1,0] op_sel_hi:[0,1,0]
	v_fma_mix_f32 v98, v85, v20, v98 op_sel:[0,1,0] op_sel_hi:[0,1,0]
	v_fma_mix_f32 v101, v86, v31, v101 op_sel:[0,0,0] op_sel_hi:[0,1,0]
	v_fma_mix_f32 v98, v86, v21, v98 op_sel:[0,0,0] op_sel_hi:[0,1,0]
	v_fma_mix_f32 v101, v87, v31, v101 op_sel:[0,1,0] op_sel_hi:[0,1,0]
	v_fma_mix_f32 v98, v87, v21, v98 op_sel:[0,1,0] op_sel_hi:[0,1,0]
	v_fma_mix_f32 v103, v91, v38, 0 op_sel:[0,0,0] op_sel_hi:[1,1,0]
	v_fma_mix_f32 v104, v91, v38, 0 op_sel:[0,1,0] op_sel_hi:[1,1,0]
	v_add_f32_dpp v101, v101, v101 quad_perm:[1,0,3,2] row_mask:0xf bank_mask:0xf bound_ctrl:1
	v_fma_mix_f32 v105, v91, v39, 0 op_sel:[0,0,0] op_sel_hi:[1,1,0]
	v_fma_mix_f32 v119, v91, v39, 0 op_sel:[0,1,0] op_sel_hi:[1,1,0]
	v_add_f32_dpp v101, v101, v101 quad_perm:[2,3,0,1] row_mask:0xf bank_mask:0xf bound_ctrl:1
	v_fma_mix_f32 v84, v84, v28, v103 op_sel:[0,0,0] op_sel_hi:[0,1,0]
	v_fma_mix_f32 v85, v85, v28, v104 op_sel:[0,1,0] op_sel_hi:[0,1,0]
	v_add_f32_dpp v101, v101, v101 row_half_mirror row_mask:0xf bank_mask:0xf bound_ctrl:1
	v_fma_mix_f32 v86, v86, v29, v105 op_sel:[0,0,0] op_sel_hi:[0,1,0]
	v_fma_mix_f32 v87, v87, v29, v119 op_sel:[0,1,0] op_sel_hi:[0,1,0]
	v_add_f32_dpp v101, v101, v101 row_mirror row_mask:0xf bank_mask:0xf bound_ctrl:1
	v_fma_mix_f32 v84, -v101, v36, v84 op_sel:[0,0,0] op_sel_hi:[0,1,0]
	v_fma_mix_f32 v85, -v101, v36, v85 op_sel:[0,1,0] op_sel_hi:[0,1,0]
	v_fma_mix_f32 v86, -v101, v37, v86 op_sel:[0,0,0] op_sel_hi:[0,1,0]
	v_fma_mix_f32 v87, -v101, v37, v87 op_sel:[0,1,0] op_sel_hi:[0,1,0]
	v_fma_mix_f32 v99, v84, v22, 0 op_sel:[0,0,0] op_sel_hi:[0,1,0]
	v_cndmask_b32_e64 v187, v97, v96, s[38:39]
	v_fma_mix_f32 v99, v85, v22, v99 op_sel:[0,1,0] op_sel_hi:[0,1,0]
	v_cndmask_b32_e64 v188, v96, v97, s[38:39]
	v_fma_mix_f32 v99, v86, v23, v99 op_sel:[0,0,0] op_sel_hi:[0,1,0]
	v_fma_mix_f32 v99, v87, v23, v99 op_sel:[0,1,0] op_sel_hi:[0,1,0]
	v_cndmask_b32_e64 v189, v99, v98, s[38:39]
	v_cndmask_b32_e64 v190, v98, v99, s[38:39]
	s_waitcnt lgkmcnt(0)
	v_fma_mix_f32 v98, v84, v74, 0 op_sel:[0,0,0] op_sel_hi:[0,1,0]
	v_fma_mix_f32 v98, v85, v74, v98 op_sel:[0,1,0] op_sel_hi:[0,1,0]
	v_add_f32_dpp v188, v188, v187 quad_perm:[1,0,3,2] row_mask:0xf bank_mask:0xf bound_ctrl:1
	v_add_f32_dpp v189, v190, v189 quad_perm:[1,0,3,2] row_mask:0xf bank_mask:0xf bound_ctrl:1
	v_fma_mix_f32 v98, v86, v75, v98 op_sel:[0,0,0] op_sel_hi:[0,1,0]
	v_fma_mix_f32 v98, v87, v75, v98 op_sel:[0,1,0] op_sel_hi:[0,1,0]
	v_cndmask_b32_e64 v191, v189, v188, s[40:41]
	v_cndmask_b32_e64 v192, v188, v189, s[40:41]
	v_fma_mix_f32 v100, v92, v78, 0 op_sel:[0,0,0] op_sel_hi:[1,1,0]
	v_fma_mix_f32 v101, v92, v78, 0 op_sel:[0,1,0] op_sel_hi:[1,1,0]
	v_add_f32_dpp v192, v192, v191 quad_perm:[2,3,0,1] row_mask:0xf bank_mask:0xf bound_ctrl:1
	v_add_f32_dpp v98, v98, v98 quad_perm:[1,0,3,2] row_mask:0xf bank_mask:0xf bound_ctrl:1
	v_fma_mix_f32 v102, v92, v79, 0 op_sel:[0,0,0] op_sel_hi:[1,1,0]
	v_add_f32_dpp v192, v192, v192 row_ror:4 row_mask:0xf bank_mask:0xf bound_ctrl:1
	v_fma_mix_f32 v103, v92, v79, 0 op_sel:[0,1,0] op_sel_hi:[1,1,0]
	v_add_f32_dpp v98, v98, v98 quad_perm:[2,3,0,1] row_mask:0xf bank_mask:0xf bound_ctrl:1
	v_add_f32_dpp v192, v192, v192 row_ror:8 row_mask:0xf bank_mask:0xf bound_ctrl:1
	v_cvt_f16_f32_e32 v192, v192
	global_store_short v83, v192, s[36:37]
	s_add_u32 s36, s36, s44
	s_addc_u32 s37, s37, s45
	s_cmp_gt_i32 s35, 9
	s_cbranch_scc0 .Lc_poll_A3
.Lc_ret_A3:
	ds_read_b128 v[0:3], v194 offset:26624
	ds_read_b128 v[4:7], v194 offset:24576
	ds_read_b128 v[8:11], v194 offset:24832
	ds_read_b128 v[12:15], v194 offset:25600
	ds_read_b128 v[16:19], v194 offset:25856
	ds_read_b128 v[20:23], v194 offset:26880
	ds_read_b128 v[24:27], v194 offset:25088
	ds_read_b128 v[28:31], v194 offset:25344
	ds_read_b128 v[32:35], v194 offset:26112
	ds_read_b128 v[36:39], v194 offset:26368
	ds_read_u16 v88, v196 offset:27136
	ds_read_u16 v89, v196 offset:27264
	ds_read_u16 v90, v196 offset:27392
	ds_read_u16 v91, v196 offset:27520
	v_fma_mix_f32 v84, v84, v72, v100 op_sel:[0,0,0] op_sel_hi:[0,1,0]
	v_fma_mix_f32 v85, v85, v72, v101 op_sel:[0,1,0] op_sel_hi:[0,1,0]
	v_add_f32_dpp v98, v98, v98 row_half_mirror row_mask:0xf bank_mask:0xf bound_ctrl:1
	v_fma_mix_f32 v86, v86, v73, v102 op_sel:[0,0,0] op_sel_hi:[0,1,0]
	v_fma_mix_f32 v87, v87, v73, v103 op_sel:[0,1,0] op_sel_hi:[0,1,0]
	v_add_f32_dpp v98, v98, v98 row_mirror row_mask:0xf bank_mask:0xf bound_ctrl:1
	v_fma_mix_f32 v84, -v98, v76, v84 op_sel:[0,0,0] op_sel_hi:[0,1,0]
	v_fma_mix_f32 v85, -v98, v76, v85 op_sel:[0,1,0] op_sel_hi:[0,1,0]
	v_fma_mix_f32 v86, -v98, v77, v86 op_sel:[0,0,0] op_sel_hi:[0,1,0]
	v_fma_mix_f32 v87, -v98, v77, v87 op_sel:[0,1,0] op_sel_hi:[0,1,0]
	v_fma_mix_f32 v73, v84, v66, 0 op_sel:[0,0,0] op_sel_hi:[0,1,0]
	v_fma_mix_f32 v97, v84, v56, 0 op_sel:[0,0,0] op_sel_hi:[0,1,0]
	v_fma_mix_f32 v73, v85, v66, v73 op_sel:[0,1,0] op_sel_hi:[0,1,0]
	v_fma_mix_f32 v56, v85, v56, v97 op_sel:[0,1,0] op_sel_hi:[0,1,0]
	v_fma_mix_f32 v73, v86, v67, v73 op_sel:[0,0,0] op_sel_hi:[0,1,0]
	v_fma_mix_f32 v56, v86, v57, v56 op_sel:[0,0,0] op_sel_hi:[0,1,0]
	v_fma_mix_f32 v73, v87, v67, v73 op_sel:[0,1,0] op_sel_hi:[0,1,0]
	v_fma_mix_f32 v56, v87, v57, v56 op_sel:[0,1,0] op_sel_hi:[0,1,0]
	v_fma_mix_f32 v75, v93, v70, 0 op_sel:[0,0,0] op_sel_hi:[1,1,0]
	v_fma_mix_f32 v76, v93, v70, 0 op_sel:[0,1,0] op_sel_hi:[1,1,0]
	v_add_f32_dpp v73, v73, v73 quad_perm:[1,0,3,2] row_mask:0xf bank_mask:0xf bound_ctrl:1
	v_fma_mix_f32 v77, v93, v71, 0 op_sel:[0,0,0] op_sel_hi:[1,1,0]
	v_fma_mix_f32 v78, v93, v71, 0 op_sel:[0,1,0] op_sel_hi:[1,1,0]
	v_add_f32_dpp v73, v73, v73 quad_perm:[2,3,0,1] row_mask:0xf bank_mask:0xf bound_ctrl:1
	v_fma_mix_f32 v84, v84, v64, v75 op_sel:[0,0,0] op_sel_hi:[0,1,0]
	v_fma_mix_f32 v85, v85, v64, v76 op_sel:[0,1,0] op_sel_hi:[0,1,0]
	v_add_f32_dpp v73, v73, v73 row_half_mirror row_mask:0xf bank_mask:0xf bound_ctrl:1
	v_fma_mix_f32 v86, v86, v65, v77 op_sel:[0,0,0] op_sel_hi:[0,1,0]
	v_fma_mix_f32 v87, v87, v65, v78 op_sel:[0,1,0] op_sel_hi:[0,1,0]
	v_add_f32_dpp v73, v73, v73 row_mirror row_mask:0xf bank_mask:0xf bound_ctrl:1
	v_fma_mix_f32 v84, -v73, v68, v84 op_sel:[0,0,0] op_sel_hi:[0,1,0]
	v_fma_mix_f32 v85, -v73, v68, v85 op_sel:[0,1,0] op_sel_hi:[0,1,0]
	v_fma_mix_f32 v86, -v73, v69, v86 op_sel:[0,0,0] op_sel_hi:[0,1,0]
	v_fma_mix_f32 v87, -v73, v69, v87 op_sel:[0,1,0] op_sel_hi:[0,1,0]
	v_fma_mix_f32 v64, v84, v54, 0 op_sel:[0,0,0] op_sel_hi:[0,1,0]
	v_fma_mix_f32 v57, v84, v58, 0 op_sel:[0,0,0] op_sel_hi:[0,1,0]
	v_fma_mix_f32 v64, v85, v54, v64 op_sel:[0,1,0] op_sel_hi:[0,1,0]
	v_fma_mix_f32 v57, v85, v58, v57 op_sel:[0,1,0] op_sel_hi:[0,1,0]
	v_fma_mix_f32 v64, v86, v55, v64 op_sel:[0,0,0] op_sel_hi:[0,1,0]
	v_fma_mix_f32 v57, v86, v59, v57 op_sel:[0,0,0] op_sel_hi:[0,1,0]
	v_fma_mix_f32 v64, v87, v55, v64 op_sel:[0,1,0] op_sel_hi:[0,1,0]
	v_fma_mix_f32 v57, v87, v59, v57 op_sel:[0,1,0] op_sel_hi:[0,1,0]
	v_fma_mix_f32 v66, v94, v62, 0 op_sel:[0,0,0] op_sel_hi:[1,1,0]
	v_fma_mix_f32 v67, v94, v62, 0 op_sel:[0,1,0] op_sel_hi:[1,1,0]
	v_add_f32_dpp v64, v64, v64 quad_perm:[1,0,3,2] row_mask:0xf bank_mask:0xf bound_ctrl:1
	v_fma_mix_f32 v68, v94, v63, 0 op_sel:[0,0,0] op_sel_hi:[1,1,0]
	v_fma_mix_f32 v69, v94, v63, 0 op_sel:[0,1,0] op_sel_hi:[1,1,0]
	v_add_f32_dpp v64, v64, v64 quad_perm:[2,3,0,1] row_mask:0xf bank_mask:0xf bound_ctrl:1
	v_fma_mix_f32 v84, v84, v52, v66 op_sel:[0,0,0] op_sel_hi:[0,1,0]
	v_fma_mix_f32 v85, v85, v52, v67 op_sel:[0,1,0] op_sel_hi:[0,1,0]
	v_add_f32_dpp v64, v64, v64 row_half_mirror row_mask:0xf bank_mask:0xf bound_ctrl:1
	v_fma_mix_f32 v86, v86, v53, v68 op_sel:[0,0,0] op_sel_hi:[0,1,0]
	v_fma_mix_f32 v87, v87, v53, v69 op_sel:[0,1,0] op_sel_hi:[0,1,0]
	v_add_f32_dpp v64, v64, v64 row_mirror row_mask:0xf bank_mask:0xf bound_ctrl:1
	v_fma_mix_f32 v84, -v64, v60, v84 op_sel:[0,0,0] op_sel_hi:[0,1,0]
	v_fma_mix_f32 v85, -v64, v60, v85 op_sel:[0,1,0] op_sel_hi:[0,1,0]
	v_fma_mix_f32 v86, -v64, v61, v86 op_sel:[0,0,0] op_sel_hi:[0,1,0]
	v_fma_mix_f32 v87, -v64, v61, v87 op_sel:[0,1,0] op_sel_hi:[0,1,0]
	v_fma_mix_f32 v53, v84, v46, 0 op_sel:[0,0,0] op_sel_hi:[0,1,0]
	v_fma_mix_f32 v59, v84, v40, 0 op_sel:[0,0,0] op_sel_hi:[0,1,0]
	v_fma_mix_f32 v53, v85, v46, v53 op_sel:[0,1,0] op_sel_hi:[0,1,0]
	v_fma_mix_f32 v40, v85, v40, v59 op_sel:[0,1,0] op_sel_hi:[0,1,0]
	v_fma_mix_f32 v53, v86, v47, v53 op_sel:[0,0,0] op_sel_hi:[0,1,0]
	v_fma_mix_f32 v40, v86, v41, v40 op_sel:[0,0,0] op_sel_hi:[0,1,0]
	v_fma_mix_f32 v53, v87, v47, v53 op_sel:[0,1,0] op_sel_hi:[0,1,0]
	v_fma_mix_f32 v40, v87, v41, v40 op_sel:[0,1,0] op_sel_hi:[0,1,0]
	v_fma_mix_f32 v55, v95, v50, 0 op_sel:[0,0,0] op_sel_hi:[1,1,0]
	v_fma_mix_f32 v58, v95, v50, 0 op_sel:[0,1,0] op_sel_hi:[1,1,0]
	v_add_f32_dpp v53, v53, v53 quad_perm:[1,0,3,2] row_mask:0xf bank_mask:0xf bound_ctrl:1
	v_fma_mix_f32 v59, v95, v51, 0 op_sel:[0,0,0] op_sel_hi:[1,1,0]
	v_fma_mix_f32 v60, v95, v51, 0 op_sel:[0,1,0] op_sel_hi:[1,1,0]
	v_add_f32_dpp v53, v53, v53 quad_perm:[2,3,0,1] row_mask:0xf bank_mask:0xf bound_ctrl:1
	v_fma_mix_f32 v84, v84, v44, v55 op_sel:[0,0,0] op_sel_hi:[0,1,0]
	v_fma_mix_f32 v85, v85, v44, v58 op_sel:[0,1,0] op_sel_hi:[0,1,0]
	v_add_f32_dpp v53, v53, v53 row_half_mirror row_mask:0xf bank_mask:0xf bound_ctrl:1
	v_fma_mix_f32 v86, v86, v45, v59 op_sel:[0,0,0] op_sel_hi:[0,1,0]
	v_fma_mix_f32 v87, v87, v45, v60 op_sel:[0,1,0] op_sel_hi:[0,1,0]
	v_add_f32_dpp v53, v53, v53 row_mirror row_mask:0xf bank_mask:0xf bound_ctrl:1
	v_fma_mix_f32 v84, -v53, v48, v84 op_sel:[0,0,0] op_sel_hi:[0,1,0]
	v_fma_mix_f32 v85, -v53, v48, v85 op_sel:[0,1,0] op_sel_hi:[0,1,0]
	v_fma_mix_f32 v86, -v53, v49, v86 op_sel:[0,0,0] op_sel_hi:[0,1,0]
	v_fma_mix_f32 v87, -v53, v49, v87 op_sel:[0,1,0] op_sel_hi:[0,1,0]
	v_fma_mix_f32 v41, v84, v42, 0 op_sel:[0,0,0] op_sel_hi:[0,1,0]
	v_add_u32_e32 v173, 8, v193
	v_fma_mix_f32 v41, v85, v42, v41 op_sel:[0,1,0] op_sel_hi:[0,1,0]
	ds_write_b32 v172, v173 offset:49216
	v_fma_mix_f32 v41, v86, v43, v41 op_sel:[0,0,0] op_sel_hi:[0,1,0]
	v_cndmask_b32_e64 v187, v57, v56, s[38:39]
	v_fma_mix_f32 v41, v87, v43, v41 op_sel:[0,1,0] op_sel_hi:[0,1,0]
	v_cndmask_b32_e64 v188, v56, v57, s[38:39]
	v_cndmask_b32_e64 v189, v41, v40, s[38:39]
	v_cndmask_b32_e64 v190, v40, v41, s[38:39]
	s_waitcnt lgkmcnt(1)
	v_fma_mix_f32 v98, v84, v6, 0 op_sel:[0,0,0] op_sel_hi:[0,1,0]
	v_fma_mix_f32 v98, v85, v6, v98 op_sel:[0,1,0] op_sel_hi:[0,1,0]
	v_add_f32_dpp v188, v188, v187 quad_perm:[1,0,3,2] row_mask:0xf bank_mask:0xf bound_ctrl:1
	v_add_f32_dpp v189, v190, v189 quad_perm:[1,0,3,2] row_mask:0xf bank_mask:0xf bound_ctrl:1
	v_fma_mix_f32 v98, v86, v7, v98 op_sel:[0,0,0] op_sel_hi:[0,1,0]
	v_fma_mix_f32 v98, v87, v7, v98 op_sel:[0,1,0] op_sel_hi:[0,1,0]
	v_cndmask_b32_e64 v191, v189, v188, s[40:41]
	v_cndmask_b32_e64 v192, v188, v189, s[40:41]
	v_fma_mix_f32 v100, v88, v14, 0 op_sel:[0,0,0] op_sel_hi:[1,1,0]
	v_fma_mix_f32 v101, v88, v14, 0 op_sel:[0,1,0] op_sel_hi:[1,1,0]
	v_add_f32_dpp v192, v192, v191 quad_perm:[2,3,0,1] row_mask:0xf bank_mask:0xf bound_ctrl:1
	v_add_f32_dpp v98, v98, v98 quad_perm:[1,0,3,2] row_mask:0xf bank_mask:0xf bound_ctrl:1
	v_fma_mix_f32 v102, v88, v15, 0 op_sel:[0,0,0] op_sel_hi:[1,1,0]
	v_add_f32_dpp v192, v192, v192 row_ror:4 row_mask:0xf bank_mask:0xf bound_ctrl:1
	v_fma_mix_f32 v103, v88, v15, 0 op_sel:[0,1,0] op_sel_hi:[1,1,0]
	v_add_f32_dpp v98, v98, v98 quad_perm:[2,3,0,1] row_mask:0xf bank_mask:0xf bound_ctrl:1
	v_add_f32_dpp v192, v192, v192 row_ror:8 row_mask:0xf bank_mask:0xf bound_ctrl:1
	v_cvt_f16_f32_e32 v192, v192
	global_store_short v83, v192, s[36:37]
	s_add_u32 s36, s36, s44
	s_addc_u32 s37, s37, s45
	ds_read_b128 v[56:59], v194 offset:29696
	ds_read_b128 v[72:75], v194 offset:27648
	ds_read_b128 v[64:67], v194 offset:27904
	ds_read_b128 v[76:79], v194 offset:28672
	ds_read_b128 v[68:71], v194 offset:28928
	ds_read_b128 v[40:43], v194 offset:29952
	ds_read_b128 v[52:55], v194 offset:28160
	ds_read_b128 v[44:47], v194 offset:28416
	ds_read_b128 v[60:63], v194 offset:29184
	ds_read_b128 v[48:51], v194 offset:29440
	ds_read_u16 v92, v196 offset:30208
	ds_read_u16 v93, v196 offset:30336
	ds_read_u16 v94, v196 offset:30464
	ds_read_u16 v95, v196 offset:30592
	v_fma_mix_f32 v84, v84, v4, v100 op_sel:[0,0,0] op_sel_hi:[0,1,0]
	v_fma_mix_f32 v85, v85, v4, v101 op_sel:[0,1,0] op_sel_hi:[0,1,0]
	v_add_f32_dpp v98, v98, v98 row_half_mirror row_mask:0xf bank_mask:0xf bound_ctrl:1
	v_fma_mix_f32 v86, v86, v5, v102 op_sel:[0,0,0] op_sel_hi:[0,1,0]
	v_fma_mix_f32 v87, v87, v5, v103 op_sel:[0,1,0] op_sel_hi:[0,1,0]
	v_add_f32_dpp v98, v98, v98 row_mirror row_mask:0xf bank_mask:0xf bound_ctrl:1
	v_fma_mix_f32 v84, -v98, v12, v84 op_sel:[0,0,0] op_sel_hi:[0,1,0]
	v_fma_mix_f32 v85, -v98, v12, v85 op_sel:[0,1,0] op_sel_hi:[0,1,0]
	v_fma_mix_f32 v86, -v98, v13, v86 op_sel:[0,0,0] op_sel_hi:[0,1,0]
	v_fma_mix_f32 v87, -v98, v13, v87 op_sel:[0,1,0] op_sel_hi:[0,1,0]
	v_fma_mix_f32 v99, v84, v10, 0 op_sel:[0,0,0] op_sel_hi:[0,1,0]
	v_fma_mix_f32 v96, v84, v0, 0 op_sel:[0,0,0] op_sel_hi:[0,1,0]
	v_fma_mix_f32 v99, v85, v10, v99 op_sel:[0,1,0] op_sel_hi:[0,1,0]
	v_fma_mix_f32 v96, v85, v0, v96 op_sel:[0,1,0] op_sel_hi:[0,1,0]
	v_fma_mix_f32 v99, v86, v11, v99 op_sel:[0,0,0] op_sel_hi:[0,1,0]
	v_fma_mix_f32 v96, v86, v1, v96 op_sel:[0,0,0] op_sel_hi:[0,1,0]
	v_fma_mix_f32 v99, v87, v11, v99 op_sel:[0,1,0] op_sel_hi:[0,1,0]
	v_fma_mix_f32 v96, v87, v1, v96 op_sel:[0,1,0] op_sel_hi:[0,1,0]
	v_fma_mix_f32 v101, v89, v18, 0 op_sel:[0,0,0] op_sel_hi:[1,1,0]
	v_fma_mix_f32 v102, v89, v18, 0 op_sel:[0,1,0] op_sel_hi:[1,1,0]
	v_add_f32_dpp v99, v99, v99 quad_perm:[1,0,3,2] row_mask:0xf bank_mask:0xf bound_ctrl:1
	v_fma_mix_f32 v103, v89, v19, 0 op_sel:[0,0,0] op_sel_hi:[1,1,0]
	v_fma_mix_f32 v104, v89, v19, 0 op_sel:[0,1,0] op_sel_hi:[1,1,0]
	v_add_f32_dpp v99, v99, v99 quad_perm:[2,3,0,1] row_mask:0xf bank_mask:0xf bound_ctrl:1
	v_fma_mix_f32 v84, v84, v8, v101 op_sel:[0,0,0] op_sel_hi:[0,1,0]
	v_fma_mix_f32 v85, v85, v8, v102 op_sel:[0,1,0] op_sel_hi:[0,1,0]
	v_add_f32_dpp v99, v99, v99 row_half_mirror row_mask:0xf bank_mask:0xf bound_ctrl:1
	v_fma_mix_f32 v86, v86, v9, v103 op_sel:[0,0,0] op_sel_hi:[0,1,0]
	v_fma_mix_f32 v87, v87, v9, v104 op_sel:[0,1,0] op_sel_hi:[0,1,0]
	v_add_f32_dpp v99, v99, v99 row_mirror row_mask:0xf bank_mask:0xf bound_ctrl:1
	v_fma_mix_f32 v84, -v99, v16, v84 op_sel:[0,0,0] op_sel_hi:[0,1,0]
	v_fma_mix_f32 v85, -v99, v16, v85 op_sel:[0,1,0] op_sel_hi:[0,1,0]
	v_fma_mix_f32 v86, -v99, v17, v86 op_sel:[0,0,0] op_sel_hi:[0,1,0]
	v_fma_mix_f32 v87, -v99, v17, v87 op_sel:[0,1,0] op_sel_hi:[0,1,0]
	v_fma_mix_f32 v100, v84, v26, 0 op_sel:[0,0,0] op_sel_hi:[0,1,0]
	v_fma_mix_f32 v97, v84, v2, 0 op_sel:[0,0,0] op_sel_hi:[0,1,0]
	v_fma_mix_f32 v100, v85, v26, v100 op_sel:[0,1,0] op_sel_hi:[0,1,0]
	v_fma_mix_f32 v97, v85, v2, v97 op_sel:[0,1,0] op_sel_hi:[0,1,0]
	v_fma_mix_f32 v100, v86, v27, v100 op_sel:[0,0,0] op_sel_hi:[0,1,0]
	v_fma_mix_f32 v97, v86, v3, v97 op_sel:[0,0,0] op_sel_hi:[0,1,0]
	v_fma_mix_f32 v100, v87, v27, v100 op_sel:[0,1,0] op_sel_hi:[0,1,0]
	v_fma_mix_f32 v97, v87, v3, v97 op_sel:[0,1,0] op_sel_hi:[0,1,0]
	v_fma_mix_f32 v102, v90, v34, 0 op_sel:[0,0,0] op_sel_hi:[1,1,0]
	v_fma_mix_f32 v103, v90, v34, 0 op_sel:[0,1,0] op_sel_hi:[1,1,0]
	v_add_f32_dpp v100, v100, v100 quad_perm:[1,0,3,2] row_mask:0xf bank_mask:0xf bound_ctrl:1
	v_fma_mix_f32 v104, v90, v35, 0 op_sel:[0,0,0] op_sel_hi:[1,1,0]
	v_fma_mix_f32 v105, v90, v35, 0 op_sel:[0,1,0] op_sel_hi:[1,1,0]
	v_add_f32_dpp v100, v100, v100 quad_perm:[2,3,0,1] row_mask:0xf bank_mask:0xf bound_ctrl:1
	v_fma_mix_f32 v84, v84, v24, v102 op_sel:[0,0,0] op_sel_hi:[0,1,0]
	v_fma_mix_f32 v85, v85, v24, v103 op_sel:[0,1,0] op_sel_hi:[0,1,0]
	v_add_f32_dpp v100, v100, v100 row_half_mirror row_mask:0xf bank_mask:0xf bound_ctrl:1
	v_fma_mix_f32 v86, v86, v25, v104 op_sel:[0,0,0] op_sel_hi:[0,1,0]
	v_fma_mix_f32 v87, v87, v25, v105 op_sel:[0,1,0] op_sel_hi:[0,1,0]
	v_add_f32_dpp v100, v100, v100 row_mirror row_mask:0xf bank_mask:0xf bound_ctrl:1
	v_fma_mix_f32 v84, -v100, v32, v84 op_sel:[0,0,0] op_sel_hi:[0,1,0]
	v_fma_mix_f32 v85, -v100, v32, v85 op_sel:[0,1,0] op_sel_hi:[0,1,0]
	v_fma_mix_f32 v86, -v100, v33, v86 op_sel:[0,0,0] op_sel_hi:[0,1,0]
	v_fma_mix_f32 v87, -v100, v33, v87 op_sel:[0,1,0] op_sel_hi:[0,1,0]
	v_fma_mix_f32 v101, v84, v30, 0 op_sel:[0,0,0] op_sel_hi:[0,1,0]
	v_fma_mix_f32 v98, v84, v20, 0 op_sel:[0,0,0] op_sel_hi:[0,1,0]
	v_fma_mix_f32 v101, v85, v30, v101 op_sel:[0,1,0] op_sel_hi:[0,1,0]
	v_fma_mix_f32 v98, v85, v20, v98 op_sel:[0,1,0] op_sel_hi:[0,1,0]
	v_fma_mix_f32 v101, v86, v31, v101 op_sel:[0,0,0] op_sel_hi:[0,1,0]
	v_fma_mix_f32 v98, v86, v21, v98 op_sel:[0,0,0] op_sel_hi:[0,1,0]
	v_fma_mix_f32 v101, v87, v31, v101 op_sel:[0,1,0] op_sel_hi:[0,1,0]
	v_fma_mix_f32 v98, v87, v21, v98 op_sel:[0,1,0] op_sel_hi:[0,1,0]
	v_fma_mix_f32 v103, v91, v38, 0 op_sel:[0,0,0] op_sel_hi:[1,1,0]
	v_fma_mix_f32 v104, v91, v38, 0 op_sel:[0,1,0] op_sel_hi:[1,1,0]
	v_add_f32_dpp v101, v101, v101 quad_perm:[1,0,3,2] row_mask:0xf bank_mask:0xf bound_ctrl:1
	v_fma_mix_f32 v105, v91, v39, 0 op_sel:[0,0,0] op_sel_hi:[1,1,0]
	v_fma_mix_f32 v119, v91, v39, 0 op_sel:[0,1,0] op_sel_hi:[1,1,0]
	v_add_f32_dpp v101, v101, v101 quad_perm:[2,3,0,1] row_mask:0xf bank_mask:0xf bound_ctrl:1
	v_fma_mix_f32 v84, v84, v28, v103 op_sel:[0,0,0] op_sel_hi:[0,1,0]
	v_fma_mix_f32 v85, v85, v28, v104 op_sel:[0,1,0] op_sel_hi:[0,1,0]
	v_add_f32_dpp v101, v101, v101 row_half_mirror row_mask:0xf bank_mask:0xf bound_ctrl:1
	v_fma_mix_f32 v86, v86, v29, v105 op_sel:[0,0,0] op_sel_hi:[0,1,0]
	v_fma_mix_f32 v87, v87, v29, v119 op_sel:[0,1,0] op_sel_hi:[0,1,0]
	v_add_f32_dpp v101, v101, v101 row_mirror row_mask:0xf bank_mask:0xf bound_ctrl:1
	v_fma_mix_f32 v84, -v101, v36, v84 op_sel:[0,0,0] op_sel_hi:[0,1,0]
	v_fma_mix_f32 v85, -v101, v36, v85 op_sel:[0,1,0] op_sel_hi:[0,1,0]
	v_fma_mix_f32 v86, -v101, v37, v86 op_sel:[0,0,0] op_sel_hi:[0,1,0]
	v_fma_mix_f32 v87, -v101, v37, v87 op_sel:[0,1,0] op_sel_hi:[0,1,0]
	v_fma_mix_f32 v99, v84, v22, 0 op_sel:[0,0,0] op_sel_hi:[0,1,0]
	v_cndmask_b32_e64 v187, v97, v96, s[38:39]
	v_fma_mix_f32 v99, v85, v22, v99 op_sel:[0,1,0] op_sel_hi:[0,1,0]
	v_cndmask_b32_e64 v188, v96, v97, s[38:39]
	v_fma_mix_f32 v99, v86, v23, v99 op_sel:[0,0,0] op_sel_hi:[0,1,0]
	v_fma_mix_f32 v99, v87, v23, v99 op_sel:[0,1,0] op_sel_hi:[0,1,0]
	v_cndmask_b32_e64 v189, v99, v98, s[38:39]
	v_cndmask_b32_e64 v190, v98, v99, s[38:39]
	s_waitcnt lgkmcnt(0)
	v_fma_mix_f32 v98, v84, v74, 0 op_sel:[0,0,0] op_sel_hi:[0,1,0]
	v_fma_mix_f32 v98, v85, v74, v98 op_sel:[0,1,0] op_sel_hi:[0,1,0]
	v_add_f32_dpp v188, v188, v187 quad_perm:[1,0,3,2] row_mask:0xf bank_mask:0xf bound_ctrl:1
	v_add_f32_dpp v189, v190, v189 quad_perm:[1,0,3,2] row_mask:0xf bank_mask:0xf bound_ctrl:1
	v_fma_mix_f32 v98, v86, v75, v98 op_sel:[0,0,0] op_sel_hi:[0,1,0]
	v_fma_mix_f32 v98, v87, v75, v98 op_sel:[0,1,0] op_sel_hi:[0,1,0]
	v_cndmask_b32_e64 v191, v189, v188, s[40:41]
	v_cndmask_b32_e64 v192, v188, v189, s[40:41]
	v_fma_mix_f32 v100, v92, v78, 0 op_sel:[0,0,0] op_sel_hi:[1,1,0]
	v_fma_mix_f32 v101, v92, v78, 0 op_sel:[0,1,0] op_sel_hi:[1,1,0]
	v_add_f32_dpp v192, v192, v191 quad_perm:[2,3,0,1] row_mask:0xf bank_mask:0xf bound_ctrl:1
	v_add_f32_dpp v98, v98, v98 quad_perm:[1,0,3,2] row_mask:0xf bank_mask:0xf bound_ctrl:1
	v_fma_mix_f32 v102, v92, v79, 0 op_sel:[0,0,0] op_sel_hi:[1,1,0]
	v_add_f32_dpp v192, v192, v192 row_ror:4 row_mask:0xf bank_mask:0xf bound_ctrl:1
	v_fma_mix_f32 v103, v92, v79, 0 op_sel:[0,1,0] op_sel_hi:[1,1,0]
	v_add_f32_dpp v98, v98, v98 quad_perm:[2,3,0,1] row_mask:0xf bank_mask:0xf bound_ctrl:1
	v_add_f32_dpp v192, v192, v192 row_ror:8 row_mask:0xf bank_mask:0xf bound_ctrl:1
	v_cvt_f16_f32_e32 v192, v192
	global_store_short v83, v192, s[36:37]
	s_add_u32 s36, s36, s44
	s_addc_u32 s37, s37, s45
	s_cmp_gt_i32 s35, 11
	s_cbranch_scc0 .Lc_poll_A4
.Lc_ret_A4:
	ds_read_b128 v[0:3], v194 offset:32768
	ds_read_b128 v[4:7], v194 offset:30720
	ds_read_b128 v[8:11], v194 offset:30976
	ds_read_b128 v[12:15], v194 offset:31744
	ds_read_b128 v[16:19], v194 offset:32000
	ds_read_b128 v[20:23], v194 offset:33024
	ds_read_b128 v[24:27], v194 offset:31232
	ds_read_b128 v[28:31], v194 offset:31488
	ds_read_b128 v[32:35], v194 offset:32256
	ds_read_b128 v[36:39], v194 offset:32512
	ds_read_u16 v88, v196 offset:33280
	ds_read_u16 v89, v196 offset:33408
	ds_read_u16 v90, v196 offset:33536
	ds_read_u16 v91, v196 offset:33664
	v_fma_mix_f32 v84, v84, v72, v100 op_sel:[0,0,0] op_sel_hi:[0,1,0]
	v_fma_mix_f32 v85, v85, v72, v101 op_sel:[0,1,0] op_sel_hi:[0,1,0]
	v_add_f32_dpp v98, v98, v98 row_half_mirror row_mask:0xf bank_mask:0xf bound_ctrl:1
	v_fma_mix_f32 v86, v86, v73, v102 op_sel:[0,0,0] op_sel_hi:[0,1,0]
	v_fma_mix_f32 v87, v87, v73, v103 op_sel:[0,1,0] op_sel_hi:[0,1,0]
	v_add_f32_dpp v98, v98, v98 row_mirror row_mask:0xf bank_mask:0xf bound_ctrl:1
	v_fma_mix_f32 v84, -v98, v76, v84 op_sel:[0,0,0] op_sel_hi:[0,1,0]
	v_fma_mix_f32 v85, -v98, v76, v85 op_sel:[0,1,0] op_sel_hi:[0,1,0]
	v_fma_mix_f32 v86, -v98, v77, v86 op_sel:[0,0,0] op_sel_hi:[0,1,0]
	v_fma_mix_f32 v87, -v98, v77, v87 op_sel:[0,1,0] op_sel_hi:[0,1,0]
	v_fma_mix_f32 v73, v84, v66, 0 op_sel:[0,0,0] op_sel_hi:[0,1,0]
	v_fma_mix_f32 v97, v84, v56, 0 op_sel:[0,0,0] op_sel_hi:[0,1,0]
	v_fma_mix_f32 v73, v85, v66, v73 op_sel:[0,1,0] op_sel_hi:[0,1,0]
	v_fma_mix_f32 v56, v85, v56, v97 op_sel:[0,1,0] op_sel_hi:[0,1,0]
	v_fma_mix_f32 v73, v86, v67, v73 op_sel:[0,0,0] op_sel_hi:[0,1,0]
	v_fma_mix_f32 v56, v86, v57, v56 op_sel:[0,0,0] op_sel_hi:[0,1,0]
	v_fma_mix_f32 v73, v87, v67, v73 op_sel:[0,1,0] op_sel_hi:[0,1,0]
	v_fma_mix_f32 v56, v87, v57, v56 op_sel:[0,1,0] op_sel_hi:[0,1,0]
	v_fma_mix_f32 v75, v93, v70, 0 op_sel:[0,0,0] op_sel_hi:[1,1,0]
	v_fma_mix_f32 v76, v93, v70, 0 op_sel:[0,1,0] op_sel_hi:[1,1,0]
	v_add_f32_dpp v73, v73, v73 quad_perm:[1,0,3,2] row_mask:0xf bank_mask:0xf bound_ctrl:1
	v_fma_mix_f32 v77, v93, v71, 0 op_sel:[0,0,0] op_sel_hi:[1,1,0]
	v_fma_mix_f32 v78, v93, v71, 0 op_sel:[0,1,0] op_sel_hi:[1,1,0]
	v_add_f32_dpp v73, v73, v73 quad_perm:[2,3,0,1] row_mask:0xf bank_mask:0xf bound_ctrl:1
	v_fma_mix_f32 v84, v84, v64, v75 op_sel:[0,0,0] op_sel_hi:[0,1,0]
	v_fma_mix_f32 v85, v85, v64, v76 op_sel:[0,1,0] op_sel_hi:[0,1,0]
	v_add_f32_dpp v73, v73, v73 row_half_mirror row_mask:0xf bank_mask:0xf bound_ctrl:1
	v_fma_mix_f32 v86, v86, v65, v77 op_sel:[0,0,0] op_sel_hi:[0,1,0]
	v_fma_mix_f32 v87, v87, v65, v78 op_sel:[0,1,0] op_sel_hi:[0,1,0]
	v_add_f32_dpp v73, v73, v73 row_mirror row_mask:0xf bank_mask:0xf bound_ctrl:1
	v_fma_mix_f32 v84, -v73, v68, v84 op_sel:[0,0,0] op_sel_hi:[0,1,0]
	v_fma_mix_f32 v85, -v73, v68, v85 op_sel:[0,1,0] op_sel_hi:[0,1,0]
	v_fma_mix_f32 v86, -v73, v69, v86 op_sel:[0,0,0] op_sel_hi:[0,1,0]
	v_fma_mix_f32 v87, -v73, v69, v87 op_sel:[0,1,0] op_sel_hi:[0,1,0]
	v_fma_mix_f32 v64, v84, v54, 0 op_sel:[0,0,0] op_sel_hi:[0,1,0]
	v_fma_mix_f32 v57, v84, v58, 0 op_sel:[0,0,0] op_sel_hi:[0,1,0]
	v_fma_mix_f32 v64, v85, v54, v64 op_sel:[0,1,0] op_sel_hi:[0,1,0]
	v_fma_mix_f32 v57, v85, v58, v57 op_sel:[0,1,0] op_sel_hi:[0,1,0]
	v_fma_mix_f32 v64, v86, v55, v64 op_sel:[0,0,0] op_sel_hi:[0,1,0]
	v_fma_mix_f32 v57, v86, v59, v57 op_sel:[0,0,0] op_sel_hi:[0,1,0]
	v_fma_mix_f32 v64, v87, v55, v64 op_sel:[0,1,0] op_sel_hi:[0,1,0]
	v_fma_mix_f32 v57, v87, v59, v57 op_sel:[0,1,0] op_sel_hi:[0,1,0]
	v_fma_mix_f32 v66, v94, v62, 0 op_sel:[0,0,0] op_sel_hi:[1,1,0]
	v_fma_mix_f32 v67, v94, v62, 0 op_sel:[0,1,0] op_sel_hi:[1,1,0]
	v_add_f32_dpp v64, v64, v64 quad_perm:[1,0,3,2] row_mask:0xf bank_mask:0xf bound_ctrl:1
	v_fma_mix_f32 v68, v94, v63, 0 op_sel:[0,0,0] op_sel_hi:[1,1,0]
	v_fma_mix_f32 v69, v94, v63, 0 op_sel:[0,1,0] op_sel_hi:[1,1,0]
	v_add_f32_dpp v64, v64, v64 quad_perm:[2,3,0,1] row_mask:0xf bank_mask:0xf bound_ctrl:1
	v_fma_mix_f32 v84, v84, v52, v66 op_sel:[0,0,0] op_sel_hi:[0,1,0]
	v_fma_mix_f32 v85, v85, v52, v67 op_sel:[0,1,0] op_sel_hi:[0,1,0]
	v_add_f32_dpp v64, v64, v64 row_half_mirror row_mask:0xf bank_mask:0xf bound_ctrl:1
	v_fma_mix_f32 v86, v86, v53, v68 op_sel:[0,0,0] op_sel_hi:[0,1,0]
	v_fma_mix_f32 v87, v87, v53, v69 op_sel:[0,1,0] op_sel_hi:[0,1,0]
	v_add_f32_dpp v64, v64, v64 row_mirror row_mask:0xf bank_mask:0xf bound_ctrl:1
	v_fma_mix_f32 v84, -v64, v60, v84 op_sel:[0,0,0] op_sel_hi:[0,1,0]
	v_fma_mix_f32 v85, -v64, v60, v85 op_sel:[0,1,0] op_sel_hi:[0,1,0]
	v_fma_mix_f32 v86, -v64, v61, v86 op_sel:[0,0,0] op_sel_hi:[0,1,0]
	v_fma_mix_f32 v87, -v64, v61, v87 op_sel:[0,1,0] op_sel_hi:[0,1,0]
	v_fma_mix_f32 v53, v84, v46, 0 op_sel:[0,0,0] op_sel_hi:[0,1,0]
	v_fma_mix_f32 v59, v84, v40, 0 op_sel:[0,0,0] op_sel_hi:[0,1,0]
	v_fma_mix_f32 v53, v85, v46, v53 op_sel:[0,1,0] op_sel_hi:[0,1,0]
	v_fma_mix_f32 v40, v85, v40, v59 op_sel:[0,1,0] op_sel_hi:[0,1,0]
	v_fma_mix_f32 v53, v86, v47, v53 op_sel:[0,0,0] op_sel_hi:[0,1,0]
	v_fma_mix_f32 v40, v86, v41, v40 op_sel:[0,0,0] op_sel_hi:[0,1,0]
	v_fma_mix_f32 v53, v87, v47, v53 op_sel:[0,1,0] op_sel_hi:[0,1,0]
	v_fma_mix_f32 v40, v87, v41, v40 op_sel:[0,1,0] op_sel_hi:[0,1,0]
	v_fma_mix_f32 v55, v95, v50, 0 op_sel:[0,0,0] op_sel_hi:[1,1,0]
	v_fma_mix_f32 v58, v95, v50, 0 op_sel:[0,1,0] op_sel_hi:[1,1,0]
	v_add_f32_dpp v53, v53, v53 quad_perm:[1,0,3,2] row_mask:0xf bank_mask:0xf bound_ctrl:1
	v_fma_mix_f32 v59, v95, v51, 0 op_sel:[0,0,0] op_sel_hi:[1,1,0]
	v_fma_mix_f32 v60, v95, v51, 0 op_sel:[0,1,0] op_sel_hi:[1,1,0]
	v_add_f32_dpp v53, v53, v53 quad_perm:[2,3,0,1] row_mask:0xf bank_mask:0xf bound_ctrl:1
	v_fma_mix_f32 v84, v84, v44, v55 op_sel:[0,0,0] op_sel_hi:[0,1,0]
	v_fma_mix_f32 v85, v85, v44, v58 op_sel:[0,1,0] op_sel_hi:[0,1,0]
	v_add_f32_dpp v53, v53, v53 row_half_mirror row_mask:0xf bank_mask:0xf bound_ctrl:1
	v_fma_mix_f32 v86, v86, v45, v59 op_sel:[0,0,0] op_sel_hi:[0,1,0]
	v_fma_mix_f32 v87, v87, v45, v60 op_sel:[0,1,0] op_sel_hi:[0,1,0]
	v_add_f32_dpp v53, v53, v53 row_mirror row_mask:0xf bank_mask:0xf bound_ctrl:1
	v_fma_mix_f32 v84, -v53, v48, v84 op_sel:[0,0,0] op_sel_hi:[0,1,0]
	v_fma_mix_f32 v85, -v53, v48, v85 op_sel:[0,1,0] op_sel_hi:[0,1,0]
	v_fma_mix_f32 v86, -v53, v49, v86 op_sel:[0,0,0] op_sel_hi:[0,1,0]
	v_fma_mix_f32 v87, -v53, v49, v87 op_sel:[0,1,0] op_sel_hi:[0,1,0]
	v_fma_mix_f32 v41, v84, v42, 0 op_sel:[0,0,0] op_sel_hi:[0,1,0]
	v_cndmask_b32_e64 v187, v57, v56, s[38:39]
	v_fma_mix_f32 v41, v85, v42, v41 op_sel:[0,1,0] op_sel_hi:[0,1,0]
	v_cndmask_b32_e64 v188, v56, v57, s[38:39]
	v_fma_mix_f32 v41, v86, v43, v41 op_sel:[0,0,0] op_sel_hi:[0,1,0]
	v_fma_mix_f32 v41, v87, v43, v41 op_sel:[0,1,0] op_sel_hi:[0,1,0]
	v_cndmask_b32_e64 v189, v41, v40, s[38:39]
	v_cndmask_b32_e64 v190, v40, v41, s[38:39]
	s_waitcnt lgkmcnt(0)
	v_fma_mix_f32 v98, v84, v6, 0 op_sel:[0,0,0] op_sel_hi:[0,1,0]
	v_fma_mix_f32 v98, v85, v6, v98 op_sel:[0,1,0] op_sel_hi:[0,1,0]
	v_add_f32_dpp v188, v188, v187 quad_perm:[1,0,3,2] row_mask:0xf bank_mask:0xf bound_ctrl:1
	v_add_f32_dpp v189, v190, v189 quad_perm:[1,0,3,2] row_mask:0xf bank_mask:0xf bound_ctrl:1
	v_fma_mix_f32 v98, v86, v7, v98 op_sel:[0,0,0] op_sel_hi:[0,1,0]
	v_fma_mix_f32 v98, v87, v7, v98 op_sel:[0,1,0] op_sel_hi:[0,1,0]
	v_cndmask_b32_e64 v191, v189, v188, s[40:41]
	v_cndmask_b32_e64 v192, v188, v189, s[40:41]
	v_fma_mix_f32 v100, v88, v14, 0 op_sel:[0,0,0] op_sel_hi:[1,1,0]
	v_fma_mix_f32 v101, v88, v14, 0 op_sel:[0,1,0] op_sel_hi:[1,1,0]
	v_add_f32_dpp v192, v192, v191 quad_perm:[2,3,0,1] row_mask:0xf bank_mask:0xf bound_ctrl:1
	v_add_f32_dpp v98, v98, v98 quad_perm:[1,0,3,2] row_mask:0xf bank_mask:0xf bound_ctrl:1
	v_fma_mix_f32 v102, v88, v15, 0 op_sel:[0,0,0] op_sel_hi:[1,1,0]
	v_add_f32_dpp v192, v192, v192 row_ror:4 row_mask:0xf bank_mask:0xf bound_ctrl:1
	v_fma_mix_f32 v103, v88, v15, 0 op_sel:[0,1,0] op_sel_hi:[1,1,0]
	v_add_f32_dpp v98, v98, v98 quad_perm:[2,3,0,1] row_mask:0xf bank_mask:0xf bound_ctrl:1
	v_add_f32_dpp v192, v192, v192 row_ror:8 row_mask:0xf bank_mask:0xf bound_ctrl:1
	v_cvt_f16_f32_e32 v192, v192
	global_store_short v83, v192, s[36:37]
	s_add_u32 s36, s36, s44
	s_addc_u32 s37, s37, s45
	ds_read_b128 v[56:59], v194 offset:35840
	ds_read_b128 v[72:75], v194 offset:33792
	ds_read_b128 v[64:67], v194 offset:34048
	ds_read_b128 v[76:79], v194 offset:34816
	ds_read_b128 v[68:71], v194 offset:35072
	ds_read_b128 v[40:43], v194 offset:36096
	ds_read_b128 v[52:55], v194 offset:34304
	ds_read_b128 v[44:47], v194 offset:34560
	ds_read_b128 v[60:63], v194 offset:35328
	ds_read_b128 v[48:51], v194 offset:35584
	ds_read_u16 v92, v196 offset:36352
	ds_read_u16 v93, v196 offset:36480
	ds_read_u16 v94, v196 offset:36608
	ds_read_u16 v95, v196 offset:36736
	v_fma_mix_f32 v84, v84, v4, v100 op_sel:[0,0,0] op_sel_hi:[0,1,0]
	v_fma_mix_f32 v85, v85, v4, v101 op_sel:[0,1,0] op_sel_hi:[0,1,0]
	v_add_f32_dpp v98, v98, v98 row_half_mirror row_mask:0xf bank_mask:0xf bound_ctrl:1
	v_fma_mix_f32 v86, v86, v5, v102 op_sel:[0,0,0] op_sel_hi:[0,1,0]
	v_fma_mix_f32 v87, v87, v5, v103 op_sel:[0,1,0] op_sel_hi:[0,1,0]
	v_add_f32_dpp v98, v98, v98 row_mirror row_mask:0xf bank_mask:0xf bound_ctrl:1
	v_fma_mix_f32 v84, -v98, v12, v84 op_sel:[0,0,0] op_sel_hi:[0,1,0]
	v_fma_mix_f32 v85, -v98, v12, v85 op_sel:[0,1,0] op_sel_hi:[0,1,0]
	v_fma_mix_f32 v86, -v98, v13, v86 op_sel:[0,0,0] op_sel_hi:[0,1,0]
	v_fma_mix_f32 v87, -v98, v13, v87 op_sel:[0,1,0] op_sel_hi:[0,1,0]
	v_fma_mix_f32 v99, v84, v10, 0 op_sel:[0,0,0] op_sel_hi:[0,1,0]
	v_fma_mix_f32 v96, v84, v0, 0 op_sel:[0,0,0] op_sel_hi:[0,1,0]
	v_fma_mix_f32 v99, v85, v10, v99 op_sel:[0,1,0] op_sel_hi:[0,1,0]
	v_fma_mix_f32 v96, v85, v0, v96 op_sel:[0,1,0] op_sel_hi:[0,1,0]
	v_fma_mix_f32 v99, v86, v11, v99 op_sel:[0,0,0] op_sel_hi:[0,1,0]
	v_fma_mix_f32 v96, v86, v1, v96 op_sel:[0,0,0] op_sel_hi:[0,1,0]
	v_fma_mix_f32 v99, v87, v11, v99 op_sel:[0,1,0] op_sel_hi:[0,1,0]
	v_fma_mix_f32 v96, v87, v1, v96 op_sel:[0,1,0] op_sel_hi:[0,1,0]
	v_fma_mix_f32 v101, v89, v18, 0 op_sel:[0,0,0] op_sel_hi:[1,1,0]
	v_fma_mix_f32 v102, v89, v18, 0 op_sel:[0,1,0] op_sel_hi:[1,1,0]
	v_add_f32_dpp v99, v99, v99 quad_perm:[1,0,3,2] row_mask:0xf bank_mask:0xf bound_ctrl:1
	v_fma_mix_f32 v103, v89, v19, 0 op_sel:[0,0,0] op_sel_hi:[1,1,0]
	v_fma_mix_f32 v104, v89, v19, 0 op_sel:[0,1,0] op_sel_hi:[1,1,0]
	v_add_f32_dpp v99, v99, v99 quad_perm:[2,3,0,1] row_mask:0xf bank_mask:0xf bound_ctrl:1
	v_fma_mix_f32 v84, v84, v8, v101 op_sel:[0,0,0] op_sel_hi:[0,1,0]
	v_fma_mix_f32 v85, v85, v8, v102 op_sel:[0,1,0] op_sel_hi:[0,1,0]
	v_add_f32_dpp v99, v99, v99 row_half_mirror row_mask:0xf bank_mask:0xf bound_ctrl:1
	v_fma_mix_f32 v86, v86, v9, v103 op_sel:[0,0,0] op_sel_hi:[0,1,0]
	v_fma_mix_f32 v87, v87, v9, v104 op_sel:[0,1,0] op_sel_hi:[0,1,0]
	v_add_f32_dpp v99, v99, v99 row_mirror row_mask:0xf bank_mask:0xf bound_ctrl:1
	v_fma_mix_f32 v84, -v99, v16, v84 op_sel:[0,0,0] op_sel_hi:[0,1,0]
	v_fma_mix_f32 v85, -v99, v16, v85 op_sel:[0,1,0] op_sel_hi:[0,1,0]
	v_fma_mix_f32 v86, -v99, v17, v86 op_sel:[0,0,0] op_sel_hi:[0,1,0]
	v_fma_mix_f32 v87, -v99, v17, v87 op_sel:[0,1,0] op_sel_hi:[0,1,0]
	v_fma_mix_f32 v100, v84, v26, 0 op_sel:[0,0,0] op_sel_hi:[0,1,0]
	v_fma_mix_f32 v97, v84, v2, 0 op_sel:[0,0,0] op_sel_hi:[0,1,0]
	v_fma_mix_f32 v100, v85, v26, v100 op_sel:[0,1,0] op_sel_hi:[0,1,0]
	v_fma_mix_f32 v97, v85, v2, v97 op_sel:[0,1,0] op_sel_hi:[0,1,0]
	v_fma_mix_f32 v100, v86, v27, v100 op_sel:[0,0,0] op_sel_hi:[0,1,0]
	v_fma_mix_f32 v97, v86, v3, v97 op_sel:[0,0,0] op_sel_hi:[0,1,0]
	v_fma_mix_f32 v100, v87, v27, v100 op_sel:[0,1,0] op_sel_hi:[0,1,0]
	v_fma_mix_f32 v97, v87, v3, v97 op_sel:[0,1,0] op_sel_hi:[0,1,0]
	v_fma_mix_f32 v102, v90, v34, 0 op_sel:[0,0,0] op_sel_hi:[1,1,0]
	v_fma_mix_f32 v103, v90, v34, 0 op_sel:[0,1,0] op_sel_hi:[1,1,0]
	v_add_f32_dpp v100, v100, v100 quad_perm:[1,0,3,2] row_mask:0xf bank_mask:0xf bound_ctrl:1
	v_fma_mix_f32 v104, v90, v35, 0 op_sel:[0,0,0] op_sel_hi:[1,1,0]
	v_fma_mix_f32 v105, v90, v35, 0 op_sel:[0,1,0] op_sel_hi:[1,1,0]
	v_add_f32_dpp v100, v100, v100 quad_perm:[2,3,0,1] row_mask:0xf bank_mask:0xf bound_ctrl:1
	v_fma_mix_f32 v84, v84, v24, v102 op_sel:[0,0,0] op_sel_hi:[0,1,0]
	v_fma_mix_f32 v85, v85, v24, v103 op_sel:[0,1,0] op_sel_hi:[0,1,0]
	v_add_f32_dpp v100, v100, v100 row_half_mirror row_mask:0xf bank_mask:0xf bound_ctrl:1
	v_fma_mix_f32 v86, v86, v25, v104 op_sel:[0,0,0] op_sel_hi:[0,1,0]
	v_fma_mix_f32 v87, v87, v25, v105 op_sel:[0,1,0] op_sel_hi:[0,1,0]
	v_add_f32_dpp v100, v100, v100 row_mirror row_mask:0xf bank_mask:0xf bound_ctrl:1
	v_fma_mix_f32 v84, -v100, v32, v84 op_sel:[0,0,0] op_sel_hi:[0,1,0]
	v_fma_mix_f32 v85, -v100, v32, v85 op_sel:[0,1,0] op_sel_hi:[0,1,0]
	v_fma_mix_f32 v86, -v100, v33, v86 op_sel:[0,0,0] op_sel_hi:[0,1,0]
	v_fma_mix_f32 v87, -v100, v33, v87 op_sel:[0,1,0] op_sel_hi:[0,1,0]
	v_fma_mix_f32 v101, v84, v30, 0 op_sel:[0,0,0] op_sel_hi:[0,1,0]
	v_fma_mix_f32 v98, v84, v20, 0 op_sel:[0,0,0] op_sel_hi:[0,1,0]
	v_fma_mix_f32 v101, v85, v30, v101 op_sel:[0,1,0] op_sel_hi:[0,1,0]
	v_fma_mix_f32 v98, v85, v20, v98 op_sel:[0,1,0] op_sel_hi:[0,1,0]
	v_fma_mix_f32 v101, v86, v31, v101 op_sel:[0,0,0] op_sel_hi:[0,1,0]
	v_fma_mix_f32 v98, v86, v21, v98 op_sel:[0,0,0] op_sel_hi:[0,1,0]
	v_fma_mix_f32 v101, v87, v31, v101 op_sel:[0,1,0] op_sel_hi:[0,1,0]
	v_fma_mix_f32 v98, v87, v21, v98 op_sel:[0,1,0] op_sel_hi:[0,1,0]
	v_fma_mix_f32 v103, v91, v38, 0 op_sel:[0,0,0] op_sel_hi:[1,1,0]
	v_fma_mix_f32 v104, v91, v38, 0 op_sel:[0,1,0] op_sel_hi:[1,1,0]
	v_add_f32_dpp v101, v101, v101 quad_perm:[1,0,3,2] row_mask:0xf bank_mask:0xf bound_ctrl:1
	v_fma_mix_f32 v105, v91, v39, 0 op_sel:[0,0,0] op_sel_hi:[1,1,0]
	v_fma_mix_f32 v119, v91, v39, 0 op_sel:[0,1,0] op_sel_hi:[1,1,0]
	v_add_f32_dpp v101, v101, v101 quad_perm:[2,3,0,1] row_mask:0xf bank_mask:0xf bound_ctrl:1
	v_fma_mix_f32 v84, v84, v28, v103 op_sel:[0,0,0] op_sel_hi:[0,1,0]
	v_fma_mix_f32 v85, v85, v28, v104 op_sel:[0,1,0] op_sel_hi:[0,1,0]
	v_add_f32_dpp v101, v101, v101 row_half_mirror row_mask:0xf bank_mask:0xf bound_ctrl:1
	v_fma_mix_f32 v86, v86, v29, v105 op_sel:[0,0,0] op_sel_hi:[0,1,0]
	v_fma_mix_f32 v87, v87, v29, v119 op_sel:[0,1,0] op_sel_hi:[0,1,0]
	v_add_f32_dpp v101, v101, v101 row_mirror row_mask:0xf bank_mask:0xf bound_ctrl:1
	v_fma_mix_f32 v84, -v101, v36, v84 op_sel:[0,0,0] op_sel_hi:[0,1,0]
	v_fma_mix_f32 v85, -v101, v36, v85 op_sel:[0,1,0] op_sel_hi:[0,1,0]
	v_fma_mix_f32 v86, -v101, v37, v86 op_sel:[0,0,0] op_sel_hi:[0,1,0]
	v_fma_mix_f32 v87, -v101, v37, v87 op_sel:[0,1,0] op_sel_hi:[0,1,0]
	v_fma_mix_f32 v99, v84, v22, 0 op_sel:[0,0,0] op_sel_hi:[0,1,0]
	v_cndmask_b32_e64 v187, v97, v96, s[38:39]
	v_fma_mix_f32 v99, v85, v22, v99 op_sel:[0,1,0] op_sel_hi:[0,1,0]
	v_cndmask_b32_e64 v188, v96, v97, s[38:39]
	v_fma_mix_f32 v99, v86, v23, v99 op_sel:[0,0,0] op_sel_hi:[0,1,0]
	v_fma_mix_f32 v99, v87, v23, v99 op_sel:[0,1,0] op_sel_hi:[0,1,0]
	v_cndmask_b32_e64 v189, v99, v98, s[38:39]
	v_cndmask_b32_e64 v190, v98, v99, s[38:39]
	s_waitcnt lgkmcnt(0)
	v_fma_mix_f32 v98, v84, v74, 0 op_sel:[0,0,0] op_sel_hi:[0,1,0]
	v_fma_mix_f32 v98, v85, v74, v98 op_sel:[0,1,0] op_sel_hi:[0,1,0]
	v_add_f32_dpp v188, v188, v187 quad_perm:[1,0,3,2] row_mask:0xf bank_mask:0xf bound_ctrl:1
	v_add_f32_dpp v189, v190, v189 quad_perm:[1,0,3,2] row_mask:0xf bank_mask:0xf bound_ctrl:1
	v_fma_mix_f32 v98, v86, v75, v98 op_sel:[0,0,0] op_sel_hi:[0,1,0]
	v_fma_mix_f32 v98, v87, v75, v98 op_sel:[0,1,0] op_sel_hi:[0,1,0]
	v_cndmask_b32_e64 v191, v189, v188, s[40:41]
	v_cndmask_b32_e64 v192, v188, v189, s[40:41]
	v_fma_mix_f32 v100, v92, v78, 0 op_sel:[0,0,0] op_sel_hi:[1,1,0]
	v_fma_mix_f32 v101, v92, v78, 0 op_sel:[0,1,0] op_sel_hi:[1,1,0]
	v_add_f32_dpp v192, v192, v191 quad_perm:[2,3,0,1] row_mask:0xf bank_mask:0xf bound_ctrl:1
	v_add_f32_dpp v98, v98, v98 quad_perm:[1,0,3,2] row_mask:0xf bank_mask:0xf bound_ctrl:1
	v_fma_mix_f32 v102, v92, v79, 0 op_sel:[0,0,0] op_sel_hi:[1,1,0]
	v_add_f32_dpp v192, v192, v192 row_ror:4 row_mask:0xf bank_mask:0xf bound_ctrl:1
	v_fma_mix_f32 v103, v92, v79, 0 op_sel:[0,1,0] op_sel_hi:[1,1,0]
	v_add_f32_dpp v98, v98, v98 quad_perm:[2,3,0,1] row_mask:0xf bank_mask:0xf bound_ctrl:1
	v_add_f32_dpp v192, v192, v192 row_ror:8 row_mask:0xf bank_mask:0xf bound_ctrl:1
	v_cvt_f16_f32_e32 v192, v192
	global_store_short v83, v192, s[36:37]
	s_add_u32 s36, s36, s44
	s_addc_u32 s37, s37, s45
	s_cmp_gt_i32 s35, 13
	s_cbranch_scc0 .Lc_poll_A5
.Lc_ret_A5:
	ds_read_b128 v[0:3], v194 offset:38912
	ds_read_b128 v[4:7], v194 offset:36864
	ds_read_b128 v[8:11], v194 offset:37120
	ds_read_b128 v[12:15], v194 offset:37888
	ds_read_b128 v[16:19], v194 offset:38144
	ds_read_b128 v[20:23], v194 offset:39168
	ds_read_b128 v[24:27], v194 offset:37376
	ds_read_b128 v[28:31], v194 offset:37632
	ds_read_b128 v[32:35], v194 offset:38400
	ds_read_b128 v[36:39], v194 offset:38656
	ds_read_u16 v88, v196 offset:39424
	ds_read_u16 v89, v196 offset:39552
	ds_read_u16 v90, v196 offset:39680
	ds_read_u16 v91, v196 offset:39808
	v_fma_mix_f32 v84, v84, v72, v100 op_sel:[0,0,0] op_sel_hi:[0,1,0]
	v_fma_mix_f32 v85, v85, v72, v101 op_sel:[0,1,0] op_sel_hi:[0,1,0]
	v_add_f32_dpp v98, v98, v98 row_half_mirror row_mask:0xf bank_mask:0xf bound_ctrl:1
	v_fma_mix_f32 v86, v86, v73, v102 op_sel:[0,0,0] op_sel_hi:[0,1,0]
	v_fma_mix_f32 v87, v87, v73, v103 op_sel:[0,1,0] op_sel_hi:[0,1,0]
	v_add_f32_dpp v98, v98, v98 row_mirror row_mask:0xf bank_mask:0xf bound_ctrl:1
	v_fma_mix_f32 v84, -v98, v76, v84 op_sel:[0,0,0] op_sel_hi:[0,1,0]
	v_fma_mix_f32 v85, -v98, v76, v85 op_sel:[0,1,0] op_sel_hi:[0,1,0]
	v_fma_mix_f32 v86, -v98, v77, v86 op_sel:[0,0,0] op_sel_hi:[0,1,0]
	v_fma_mix_f32 v87, -v98, v77, v87 op_sel:[0,1,0] op_sel_hi:[0,1,0]
	v_fma_mix_f32 v73, v84, v66, 0 op_sel:[0,0,0] op_sel_hi:[0,1,0]
	v_fma_mix_f32 v97, v84, v56, 0 op_sel:[0,0,0] op_sel_hi:[0,1,0]
	v_fma_mix_f32 v73, v85, v66, v73 op_sel:[0,1,0] op_sel_hi:[0,1,0]
	v_fma_mix_f32 v56, v85, v56, v97 op_sel:[0,1,0] op_sel_hi:[0,1,0]
	v_fma_mix_f32 v73, v86, v67, v73 op_sel:[0,0,0] op_sel_hi:[0,1,0]
	v_fma_mix_f32 v56, v86, v57, v56 op_sel:[0,0,0] op_sel_hi:[0,1,0]
	v_fma_mix_f32 v73, v87, v67, v73 op_sel:[0,1,0] op_sel_hi:[0,1,0]
	v_fma_mix_f32 v56, v87, v57, v56 op_sel:[0,1,0] op_sel_hi:[0,1,0]
	v_fma_mix_f32 v75, v93, v70, 0 op_sel:[0,0,0] op_sel_hi:[1,1,0]
	v_fma_mix_f32 v76, v93, v70, 0 op_sel:[0,1,0] op_sel_hi:[1,1,0]
	v_add_f32_dpp v73, v73, v73 quad_perm:[1,0,3,2] row_mask:0xf bank_mask:0xf bound_ctrl:1
	v_fma_mix_f32 v77, v93, v71, 0 op_sel:[0,0,0] op_sel_hi:[1,1,0]
	v_fma_mix_f32 v78, v93, v71, 0 op_sel:[0,1,0] op_sel_hi:[1,1,0]
	v_add_f32_dpp v73, v73, v73 quad_perm:[2,3,0,1] row_mask:0xf bank_mask:0xf bound_ctrl:1
	v_fma_mix_f32 v84, v84, v64, v75 op_sel:[0,0,0] op_sel_hi:[0,1,0]
	v_fma_mix_f32 v85, v85, v64, v76 op_sel:[0,1,0] op_sel_hi:[0,1,0]
	v_add_f32_dpp v73, v73, v73 row_half_mirror row_mask:0xf bank_mask:0xf bound_ctrl:1
	v_fma_mix_f32 v86, v86, v65, v77 op_sel:[0,0,0] op_sel_hi:[0,1,0]
	v_fma_mix_f32 v87, v87, v65, v78 op_sel:[0,1,0] op_sel_hi:[0,1,0]
	v_add_f32_dpp v73, v73, v73 row_mirror row_mask:0xf bank_mask:0xf bound_ctrl:1
	v_fma_mix_f32 v84, -v73, v68, v84 op_sel:[0,0,0] op_sel_hi:[0,1,0]
	v_fma_mix_f32 v85, -v73, v68, v85 op_sel:[0,1,0] op_sel_hi:[0,1,0]
	v_fma_mix_f32 v86, -v73, v69, v86 op_sel:[0,0,0] op_sel_hi:[0,1,0]
	v_fma_mix_f32 v87, -v73, v69, v87 op_sel:[0,1,0] op_sel_hi:[0,1,0]
	v_fma_mix_f32 v64, v84, v54, 0 op_sel:[0,0,0] op_sel_hi:[0,1,0]
	v_fma_mix_f32 v57, v84, v58, 0 op_sel:[0,0,0] op_sel_hi:[0,1,0]
	v_fma_mix_f32 v64, v85, v54, v64 op_sel:[0,1,0] op_sel_hi:[0,1,0]
	v_fma_mix_f32 v57, v85, v58, v57 op_sel:[0,1,0] op_sel_hi:[0,1,0]
	v_fma_mix_f32 v64, v86, v55, v64 op_sel:[0,0,0] op_sel_hi:[0,1,0]
	v_fma_mix_f32 v57, v86, v59, v57 op_sel:[0,0,0] op_sel_hi:[0,1,0]
	v_fma_mix_f32 v64, v87, v55, v64 op_sel:[0,1,0] op_sel_hi:[0,1,0]
	v_fma_mix_f32 v57, v87, v59, v57 op_sel:[0,1,0] op_sel_hi:[0,1,0]
	v_fma_mix_f32 v66, v94, v62, 0 op_sel:[0,0,0] op_sel_hi:[1,1,0]
	v_fma_mix_f32 v67, v94, v62, 0 op_sel:[0,1,0] op_sel_hi:[1,1,0]
	v_add_f32_dpp v64, v64, v64 quad_perm:[1,0,3,2] row_mask:0xf bank_mask:0xf bound_ctrl:1
	v_fma_mix_f32 v68, v94, v63, 0 op_sel:[0,0,0] op_sel_hi:[1,1,0]
	v_fma_mix_f32 v69, v94, v63, 0 op_sel:[0,1,0] op_sel_hi:[1,1,0]
	v_add_f32_dpp v64, v64, v64 quad_perm:[2,3,0,1] row_mask:0xf bank_mask:0xf bound_ctrl:1
	v_fma_mix_f32 v84, v84, v52, v66 op_sel:[0,0,0] op_sel_hi:[0,1,0]
	v_fma_mix_f32 v85, v85, v52, v67 op_sel:[0,1,0] op_sel_hi:[0,1,0]
	v_add_f32_dpp v64, v64, v64 row_half_mirror row_mask:0xf bank_mask:0xf bound_ctrl:1
	v_fma_mix_f32 v86, v86, v53, v68 op_sel:[0,0,0] op_sel_hi:[0,1,0]
	v_fma_mix_f32 v87, v87, v53, v69 op_sel:[0,1,0] op_sel_hi:[0,1,0]
	v_add_f32_dpp v64, v64, v64 row_mirror row_mask:0xf bank_mask:0xf bound_ctrl:1
	v_fma_mix_f32 v84, -v64, v60, v84 op_sel:[0,0,0] op_sel_hi:[0,1,0]
	v_fma_mix_f32 v85, -v64, v60, v85 op_sel:[0,1,0] op_sel_hi:[0,1,0]
	v_fma_mix_f32 v86, -v64, v61, v86 op_sel:[0,0,0] op_sel_hi:[0,1,0]
	v_fma_mix_f32 v87, -v64, v61, v87 op_sel:[0,1,0] op_sel_hi:[0,1,0]
	v_fma_mix_f32 v53, v84, v46, 0 op_sel:[0,0,0] op_sel_hi:[0,1,0]
	v_fma_mix_f32 v59, v84, v40, 0 op_sel:[0,0,0] op_sel_hi:[0,1,0]
	v_fma_mix_f32 v53, v85, v46, v53 op_sel:[0,1,0] op_sel_hi:[0,1,0]
	v_fma_mix_f32 v40, v85, v40, v59 op_sel:[0,1,0] op_sel_hi:[0,1,0]
	v_fma_mix_f32 v53, v86, v47, v53 op_sel:[0,0,0] op_sel_hi:[0,1,0]
	v_fma_mix_f32 v40, v86, v41, v40 op_sel:[0,0,0] op_sel_hi:[0,1,0]
	v_fma_mix_f32 v53, v87, v47, v53 op_sel:[0,1,0] op_sel_hi:[0,1,0]
	v_fma_mix_f32 v40, v87, v41, v40 op_sel:[0,1,0] op_sel_hi:[0,1,0]
	v_fma_mix_f32 v55, v95, v50, 0 op_sel:[0,0,0] op_sel_hi:[1,1,0]
	v_fma_mix_f32 v58, v95, v50, 0 op_sel:[0,1,0] op_sel_hi:[1,1,0]
	v_add_f32_dpp v53, v53, v53 quad_perm:[1,0,3,2] row_mask:0xf bank_mask:0xf bound_ctrl:1
	v_fma_mix_f32 v59, v95, v51, 0 op_sel:[0,0,0] op_sel_hi:[1,1,0]
	v_fma_mix_f32 v60, v95, v51, 0 op_sel:[0,1,0] op_sel_hi:[1,1,0]
	v_add_f32_dpp v53, v53, v53 quad_perm:[2,3,0,1] row_mask:0xf bank_mask:0xf bound_ctrl:1
	v_fma_mix_f32 v84, v84, v44, v55 op_sel:[0,0,0] op_sel_hi:[0,1,0]
	v_fma_mix_f32 v85, v85, v44, v58 op_sel:[0,1,0] op_sel_hi:[0,1,0]
	v_add_f32_dpp v53, v53, v53 row_half_mirror row_mask:0xf bank_mask:0xf bound_ctrl:1
	v_fma_mix_f32 v86, v86, v45, v59 op_sel:[0,0,0] op_sel_hi:[0,1,0]
	v_fma_mix_f32 v87, v87, v45, v60 op_sel:[0,1,0] op_sel_hi:[0,1,0]
	v_add_f32_dpp v53, v53, v53 row_mirror row_mask:0xf bank_mask:0xf bound_ctrl:1
	v_fma_mix_f32 v84, -v53, v48, v84 op_sel:[0,0,0] op_sel_hi:[0,1,0]
	v_fma_mix_f32 v85, -v53, v48, v85 op_sel:[0,1,0] op_sel_hi:[0,1,0]
	v_fma_mix_f32 v86, -v53, v49, v86 op_sel:[0,0,0] op_sel_hi:[0,1,0]
	v_fma_mix_f32 v87, -v53, v49, v87 op_sel:[0,1,0] op_sel_hi:[0,1,0]
	v_fma_mix_f32 v41, v84, v42, 0 op_sel:[0,0,0] op_sel_hi:[0,1,0]
	v_add_u32_e32 v173, 12, v193
	v_fma_mix_f32 v41, v85, v42, v41 op_sel:[0,1,0] op_sel_hi:[0,1,0]
	ds_write_b32 v172, v173 offset:49216
	v_fma_mix_f32 v41, v86, v43, v41 op_sel:[0,0,0] op_sel_hi:[0,1,0]
	v_cndmask_b32_e64 v187, v57, v56, s[38:39]
	v_fma_mix_f32 v41, v87, v43, v41 op_sel:[0,1,0] op_sel_hi:[0,1,0]
	v_cndmask_b32_e64 v188, v56, v57, s[38:39]
	v_cndmask_b32_e64 v189, v41, v40, s[38:39]
	v_cndmask_b32_e64 v190, v40, v41, s[38:39]
	s_waitcnt lgkmcnt(1)
	v_fma_mix_f32 v98, v84, v6, 0 op_sel:[0,0,0] op_sel_hi:[0,1,0]
	v_fma_mix_f32 v98, v85, v6, v98 op_sel:[0,1,0] op_sel_hi:[0,1,0]
	v_add_f32_dpp v188, v188, v187 quad_perm:[1,0,3,2] row_mask:0xf bank_mask:0xf bound_ctrl:1
	v_add_f32_dpp v189, v190, v189 quad_perm:[1,0,3,2] row_mask:0xf bank_mask:0xf bound_ctrl:1
	v_fma_mix_f32 v98, v86, v7, v98 op_sel:[0,0,0] op_sel_hi:[0,1,0]
	v_fma_mix_f32 v98, v87, v7, v98 op_sel:[0,1,0] op_sel_hi:[0,1,0]
	v_cndmask_b32_e64 v191, v189, v188, s[40:41]
	v_cndmask_b32_e64 v192, v188, v189, s[40:41]
	v_fma_mix_f32 v100, v88, v14, 0 op_sel:[0,0,0] op_sel_hi:[1,1,0]
	v_fma_mix_f32 v101, v88, v14, 0 op_sel:[0,1,0] op_sel_hi:[1,1,0]
	v_add_f32_dpp v192, v192, v191 quad_perm:[2,3,0,1] row_mask:0xf bank_mask:0xf bound_ctrl:1
	v_add_f32_dpp v98, v98, v98 quad_perm:[1,0,3,2] row_mask:0xf bank_mask:0xf bound_ctrl:1
	v_fma_mix_f32 v102, v88, v15, 0 op_sel:[0,0,0] op_sel_hi:[1,1,0]
	v_add_f32_dpp v192, v192, v192 row_ror:4 row_mask:0xf bank_mask:0xf bound_ctrl:1
	v_fma_mix_f32 v103, v88, v15, 0 op_sel:[0,1,0] op_sel_hi:[1,1,0]
	v_add_f32_dpp v98, v98, v98 quad_perm:[2,3,0,1] row_mask:0xf bank_mask:0xf bound_ctrl:1
	v_add_f32_dpp v192, v192, v192 row_ror:8 row_mask:0xf bank_mask:0xf bound_ctrl:1
	v_cvt_f16_f32_e32 v192, v192
	global_store_short v83, v192, s[36:37]
	s_add_u32 s36, s36, s44
	s_addc_u32 s37, s37, s45
	ds_read_b128 v[56:59], v194 offset:41984
	ds_read_b128 v[72:75], v194 offset:39936
	ds_read_b128 v[64:67], v194 offset:40192
	ds_read_b128 v[76:79], v194 offset:40960
	ds_read_b128 v[68:71], v194 offset:41216
	ds_read_b128 v[40:43], v194 offset:42240
	ds_read_b128 v[52:55], v194 offset:40448
	ds_read_b128 v[44:47], v194 offset:40704
	ds_read_b128 v[60:63], v194 offset:41472
	ds_read_b128 v[48:51], v194 offset:41728
	ds_read_u16 v92, v196 offset:42496
	ds_read_u16 v93, v196 offset:42624
	ds_read_u16 v94, v196 offset:42752
	ds_read_u16 v95, v196 offset:42880
	v_fma_mix_f32 v84, v84, v4, v100 op_sel:[0,0,0] op_sel_hi:[0,1,0]
	v_fma_mix_f32 v85, v85, v4, v101 op_sel:[0,1,0] op_sel_hi:[0,1,0]
	v_add_f32_dpp v98, v98, v98 row_half_mirror row_mask:0xf bank_mask:0xf bound_ctrl:1
	v_fma_mix_f32 v86, v86, v5, v102 op_sel:[0,0,0] op_sel_hi:[0,1,0]
	v_fma_mix_f32 v87, v87, v5, v103 op_sel:[0,1,0] op_sel_hi:[0,1,0]
	v_add_f32_dpp v98, v98, v98 row_mirror row_mask:0xf bank_mask:0xf bound_ctrl:1
	v_fma_mix_f32 v84, -v98, v12, v84 op_sel:[0,0,0] op_sel_hi:[0,1,0]
	v_fma_mix_f32 v85, -v98, v12, v85 op_sel:[0,1,0] op_sel_hi:[0,1,0]
	v_fma_mix_f32 v86, -v98, v13, v86 op_sel:[0,0,0] op_sel_hi:[0,1,0]
	v_fma_mix_f32 v87, -v98, v13, v87 op_sel:[0,1,0] op_sel_hi:[0,1,0]
	v_fma_mix_f32 v99, v84, v10, 0 op_sel:[0,0,0] op_sel_hi:[0,1,0]
	v_fma_mix_f32 v96, v84, v0, 0 op_sel:[0,0,0] op_sel_hi:[0,1,0]
	v_fma_mix_f32 v99, v85, v10, v99 op_sel:[0,1,0] op_sel_hi:[0,1,0]
	v_fma_mix_f32 v96, v85, v0, v96 op_sel:[0,1,0] op_sel_hi:[0,1,0]
	v_fma_mix_f32 v99, v86, v11, v99 op_sel:[0,0,0] op_sel_hi:[0,1,0]
	v_fma_mix_f32 v96, v86, v1, v96 op_sel:[0,0,0] op_sel_hi:[0,1,0]
	v_fma_mix_f32 v99, v87, v11, v99 op_sel:[0,1,0] op_sel_hi:[0,1,0]
	v_fma_mix_f32 v96, v87, v1, v96 op_sel:[0,1,0] op_sel_hi:[0,1,0]
	v_fma_mix_f32 v101, v89, v18, 0 op_sel:[0,0,0] op_sel_hi:[1,1,0]
	v_fma_mix_f32 v102, v89, v18, 0 op_sel:[0,1,0] op_sel_hi:[1,1,0]
	v_add_f32_dpp v99, v99, v99 quad_perm:[1,0,3,2] row_mask:0xf bank_mask:0xf bound_ctrl:1
	v_fma_mix_f32 v103, v89, v19, 0 op_sel:[0,0,0] op_sel_hi:[1,1,0]
	v_fma_mix_f32 v104, v89, v19, 0 op_sel:[0,1,0] op_sel_hi:[1,1,0]
	v_add_f32_dpp v99, v99, v99 quad_perm:[2,3,0,1] row_mask:0xf bank_mask:0xf bound_ctrl:1
	v_fma_mix_f32 v84, v84, v8, v101 op_sel:[0,0,0] op_sel_hi:[0,1,0]
	v_fma_mix_f32 v85, v85, v8, v102 op_sel:[0,1,0] op_sel_hi:[0,1,0]
	v_add_f32_dpp v99, v99, v99 row_half_mirror row_mask:0xf bank_mask:0xf bound_ctrl:1
	v_fma_mix_f32 v86, v86, v9, v103 op_sel:[0,0,0] op_sel_hi:[0,1,0]
	v_fma_mix_f32 v87, v87, v9, v104 op_sel:[0,1,0] op_sel_hi:[0,1,0]
	v_add_f32_dpp v99, v99, v99 row_mirror row_mask:0xf bank_mask:0xf bound_ctrl:1
	v_fma_mix_f32 v84, -v99, v16, v84 op_sel:[0,0,0] op_sel_hi:[0,1,0]
	v_fma_mix_f32 v85, -v99, v16, v85 op_sel:[0,1,0] op_sel_hi:[0,1,0]
	v_fma_mix_f32 v86, -v99, v17, v86 op_sel:[0,0,0] op_sel_hi:[0,1,0]
	v_fma_mix_f32 v87, -v99, v17, v87 op_sel:[0,1,0] op_sel_hi:[0,1,0]
	v_fma_mix_f32 v100, v84, v26, 0 op_sel:[0,0,0] op_sel_hi:[0,1,0]
	v_fma_mix_f32 v97, v84, v2, 0 op_sel:[0,0,0] op_sel_hi:[0,1,0]
	v_fma_mix_f32 v100, v85, v26, v100 op_sel:[0,1,0] op_sel_hi:[0,1,0]
	v_fma_mix_f32 v97, v85, v2, v97 op_sel:[0,1,0] op_sel_hi:[0,1,0]
	v_fma_mix_f32 v100, v86, v27, v100 op_sel:[0,0,0] op_sel_hi:[0,1,0]
	v_fma_mix_f32 v97, v86, v3, v97 op_sel:[0,0,0] op_sel_hi:[0,1,0]
	v_fma_mix_f32 v100, v87, v27, v100 op_sel:[0,1,0] op_sel_hi:[0,1,0]
	v_fma_mix_f32 v97, v87, v3, v97 op_sel:[0,1,0] op_sel_hi:[0,1,0]
	v_fma_mix_f32 v102, v90, v34, 0 op_sel:[0,0,0] op_sel_hi:[1,1,0]
	v_fma_mix_f32 v103, v90, v34, 0 op_sel:[0,1,0] op_sel_hi:[1,1,0]
	v_add_f32_dpp v100, v100, v100 quad_perm:[1,0,3,2] row_mask:0xf bank_mask:0xf bound_ctrl:1
	v_fma_mix_f32 v104, v90, v35, 0 op_sel:[0,0,0] op_sel_hi:[1,1,0]
	v_fma_mix_f32 v105, v90, v35, 0 op_sel:[0,1,0] op_sel_hi:[1,1,0]
	v_add_f32_dpp v100, v100, v100 quad_perm:[2,3,0,1] row_mask:0xf bank_mask:0xf bound_ctrl:1
	v_fma_mix_f32 v84, v84, v24, v102 op_sel:[0,0,0] op_sel_hi:[0,1,0]
	v_fma_mix_f32 v85, v85, v24, v103 op_sel:[0,1,0] op_sel_hi:[0,1,0]
	v_add_f32_dpp v100, v100, v100 row_half_mirror row_mask:0xf bank_mask:0xf bound_ctrl:1
	v_fma_mix_f32 v86, v86, v25, v104 op_sel:[0,0,0] op_sel_hi:[0,1,0]
	v_fma_mix_f32 v87, v87, v25, v105 op_sel:[0,1,0] op_sel_hi:[0,1,0]
	v_add_f32_dpp v100, v100, v100 row_mirror row_mask:0xf bank_mask:0xf bound_ctrl:1
	v_fma_mix_f32 v84, -v100, v32, v84 op_sel:[0,0,0] op_sel_hi:[0,1,0]
	v_fma_mix_f32 v85, -v100, v32, v85 op_sel:[0,1,0] op_sel_hi:[0,1,0]
	v_fma_mix_f32 v86, -v100, v33, v86 op_sel:[0,0,0] op_sel_hi:[0,1,0]
	v_fma_mix_f32 v87, -v100, v33, v87 op_sel:[0,1,0] op_sel_hi:[0,1,0]
	v_fma_mix_f32 v101, v84, v30, 0 op_sel:[0,0,0] op_sel_hi:[0,1,0]
	v_fma_mix_f32 v98, v84, v20, 0 op_sel:[0,0,0] op_sel_hi:[0,1,0]
	v_fma_mix_f32 v101, v85, v30, v101 op_sel:[0,1,0] op_sel_hi:[0,1,0]
	v_fma_mix_f32 v98, v85, v20, v98 op_sel:[0,1,0] op_sel_hi:[0,1,0]
	v_fma_mix_f32 v101, v86, v31, v101 op_sel:[0,0,0] op_sel_hi:[0,1,0]
	v_fma_mix_f32 v98, v86, v21, v98 op_sel:[0,0,0] op_sel_hi:[0,1,0]
	v_fma_mix_f32 v101, v87, v31, v101 op_sel:[0,1,0] op_sel_hi:[0,1,0]
	v_fma_mix_f32 v98, v87, v21, v98 op_sel:[0,1,0] op_sel_hi:[0,1,0]
	v_fma_mix_f32 v103, v91, v38, 0 op_sel:[0,0,0] op_sel_hi:[1,1,0]
	v_fma_mix_f32 v104, v91, v38, 0 op_sel:[0,1,0] op_sel_hi:[1,1,0]
	v_add_f32_dpp v101, v101, v101 quad_perm:[1,0,3,2] row_mask:0xf bank_mask:0xf bound_ctrl:1
	v_fma_mix_f32 v105, v91, v39, 0 op_sel:[0,0,0] op_sel_hi:[1,1,0]
	v_fma_mix_f32 v119, v91, v39, 0 op_sel:[0,1,0] op_sel_hi:[1,1,0]
	v_add_f32_dpp v101, v101, v101 quad_perm:[2,3,0,1] row_mask:0xf bank_mask:0xf bound_ctrl:1
	v_fma_mix_f32 v84, v84, v28, v103 op_sel:[0,0,0] op_sel_hi:[0,1,0]
	v_fma_mix_f32 v85, v85, v28, v104 op_sel:[0,1,0] op_sel_hi:[0,1,0]
	v_add_f32_dpp v101, v101, v101 row_half_mirror row_mask:0xf bank_mask:0xf bound_ctrl:1
	v_fma_mix_f32 v86, v86, v29, v105 op_sel:[0,0,0] op_sel_hi:[0,1,0]
	v_fma_mix_f32 v87, v87, v29, v119 op_sel:[0,1,0] op_sel_hi:[0,1,0]
	v_add_f32_dpp v101, v101, v101 row_mirror row_mask:0xf bank_mask:0xf bound_ctrl:1
	v_fma_mix_f32 v84, -v101, v36, v84 op_sel:[0,0,0] op_sel_hi:[0,1,0]
	v_fma_mix_f32 v85, -v101, v36, v85 op_sel:[0,1,0] op_sel_hi:[0,1,0]
	v_fma_mix_f32 v86, -v101, v37, v86 op_sel:[0,0,0] op_sel_hi:[0,1,0]
	v_fma_mix_f32 v87, -v101, v37, v87 op_sel:[0,1,0] op_sel_hi:[0,1,0]
	v_fma_mix_f32 v99, v84, v22, 0 op_sel:[0,0,0] op_sel_hi:[0,1,0]
	v_cndmask_b32_e64 v187, v97, v96, s[38:39]
	v_fma_mix_f32 v99, v85, v22, v99 op_sel:[0,1,0] op_sel_hi:[0,1,0]
	v_cndmask_b32_e64 v188, v96, v97, s[38:39]
	v_fma_mix_f32 v99, v86, v23, v99 op_sel:[0,0,0] op_sel_hi:[0,1,0]
	v_fma_mix_f32 v99, v87, v23, v99 op_sel:[0,1,0] op_sel_hi:[0,1,0]
	v_cndmask_b32_e64 v189, v99, v98, s[38:39]
	v_cndmask_b32_e64 v190, v98, v99, s[38:39]
	s_waitcnt lgkmcnt(0)
	v_fma_mix_f32 v98, v84, v74, 0 op_sel:[0,0,0] op_sel_hi:[0,1,0]
	v_fma_mix_f32 v98, v85, v74, v98 op_sel:[0,1,0] op_sel_hi:[0,1,0]
	v_add_f32_dpp v188, v188, v187 quad_perm:[1,0,3,2] row_mask:0xf bank_mask:0xf bound_ctrl:1
	v_add_f32_dpp v189, v190, v189 quad_perm:[1,0,3,2] row_mask:0xf bank_mask:0xf bound_ctrl:1
	v_fma_mix_f32 v98, v86, v75, v98 op_sel:[0,0,0] op_sel_hi:[0,1,0]
	v_fma_mix_f32 v98, v87, v75, v98 op_sel:[0,1,0] op_sel_hi:[0,1,0]
	v_cndmask_b32_e64 v191, v189, v188, s[40:41]
	v_cndmask_b32_e64 v192, v188, v189, s[40:41]
	v_fma_mix_f32 v100, v92, v78, 0 op_sel:[0,0,0] op_sel_hi:[1,1,0]
	v_fma_mix_f32 v101, v92, v78, 0 op_sel:[0,1,0] op_sel_hi:[1,1,0]
	v_add_f32_dpp v192, v192, v191 quad_perm:[2,3,0,1] row_mask:0xf bank_mask:0xf bound_ctrl:1
	v_add_f32_dpp v98, v98, v98 quad_perm:[1,0,3,2] row_mask:0xf bank_mask:0xf bound_ctrl:1
	v_fma_mix_f32 v102, v92, v79, 0 op_sel:[0,0,0] op_sel_hi:[1,1,0]
	v_add_f32_dpp v192, v192, v192 row_ror:4 row_mask:0xf bank_mask:0xf bound_ctrl:1
	v_fma_mix_f32 v103, v92, v79, 0 op_sel:[0,1,0] op_sel_hi:[1,1,0]
	v_add_f32_dpp v98, v98, v98 quad_perm:[2,3,0,1] row_mask:0xf bank_mask:0xf bound_ctrl:1
	v_add_f32_dpp v192, v192, v192 row_ror:8 row_mask:0xf bank_mask:0xf bound_ctrl:1
	v_cvt_f16_f32_e32 v192, v192
	global_store_short v83, v192, s[36:37]
	s_add_u32 s36, s36, s44
	s_addc_u32 s37, s37, s45
	s_cmp_gt_i32 s35, 15
	s_cbranch_scc0 .Lc_poll_A6
.Lc_ret_A6:
	ds_read_b128 v[0:3], v194 offset:45056
	ds_read_b128 v[4:7], v194 offset:43008
	ds_read_b128 v[8:11], v194 offset:43264
	ds_read_b128 v[12:15], v194 offset:44032
	ds_read_b128 v[16:19], v194 offset:44288
	ds_read_b128 v[20:23], v194 offset:45312
	ds_read_b128 v[24:27], v194 offset:43520
	ds_read_b128 v[28:31], v194 offset:43776
	ds_read_b128 v[32:35], v194 offset:44544
	ds_read_b128 v[36:39], v194 offset:44800
	ds_read_u16 v88, v196 offset:45568
	ds_read_u16 v89, v196 offset:45696
	ds_read_u16 v90, v196 offset:45824
	ds_read_u16 v91, v196 offset:45952
	v_fma_mix_f32 v84, v84, v72, v100 op_sel:[0,0,0] op_sel_hi:[0,1,0]
	v_fma_mix_f32 v85, v85, v72, v101 op_sel:[0,1,0] op_sel_hi:[0,1,0]
	v_add_f32_dpp v98, v98, v98 row_half_mirror row_mask:0xf bank_mask:0xf bound_ctrl:1
	v_fma_mix_f32 v86, v86, v73, v102 op_sel:[0,0,0] op_sel_hi:[0,1,0]
	v_fma_mix_f32 v87, v87, v73, v103 op_sel:[0,1,0] op_sel_hi:[0,1,0]
	v_add_f32_dpp v98, v98, v98 row_mirror row_mask:0xf bank_mask:0xf bound_ctrl:1
	v_fma_mix_f32 v84, -v98, v76, v84 op_sel:[0,0,0] op_sel_hi:[0,1,0]
	v_fma_mix_f32 v85, -v98, v76, v85 op_sel:[0,1,0] op_sel_hi:[0,1,0]
	v_fma_mix_f32 v86, -v98, v77, v86 op_sel:[0,0,0] op_sel_hi:[0,1,0]
	v_fma_mix_f32 v87, -v98, v77, v87 op_sel:[0,1,0] op_sel_hi:[0,1,0]
	v_fma_mix_f32 v73, v84, v66, 0 op_sel:[0,0,0] op_sel_hi:[0,1,0]
	v_fma_mix_f32 v97, v84, v56, 0 op_sel:[0,0,0] op_sel_hi:[0,1,0]
	v_fma_mix_f32 v73, v85, v66, v73 op_sel:[0,1,0] op_sel_hi:[0,1,0]
	v_fma_mix_f32 v56, v85, v56, v97 op_sel:[0,1,0] op_sel_hi:[0,1,0]
	v_fma_mix_f32 v73, v86, v67, v73 op_sel:[0,0,0] op_sel_hi:[0,1,0]
	v_fma_mix_f32 v56, v86, v57, v56 op_sel:[0,0,0] op_sel_hi:[0,1,0]
	v_fma_mix_f32 v73, v87, v67, v73 op_sel:[0,1,0] op_sel_hi:[0,1,0]
	v_fma_mix_f32 v56, v87, v57, v56 op_sel:[0,1,0] op_sel_hi:[0,1,0]
	v_fma_mix_f32 v75, v93, v70, 0 op_sel:[0,0,0] op_sel_hi:[1,1,0]
	v_fma_mix_f32 v76, v93, v70, 0 op_sel:[0,1,0] op_sel_hi:[1,1,0]
	v_add_f32_dpp v73, v73, v73 quad_perm:[1,0,3,2] row_mask:0xf bank_mask:0xf bound_ctrl:1
	v_fma_mix_f32 v77, v93, v71, 0 op_sel:[0,0,0] op_sel_hi:[1,1,0]
	v_fma_mix_f32 v78, v93, v71, 0 op_sel:[0,1,0] op_sel_hi:[1,1,0]
	v_add_f32_dpp v73, v73, v73 quad_perm:[2,3,0,1] row_mask:0xf bank_mask:0xf bound_ctrl:1
	v_fma_mix_f32 v84, v84, v64, v75 op_sel:[0,0,0] op_sel_hi:[0,1,0]
	v_fma_mix_f32 v85, v85, v64, v76 op_sel:[0,1,0] op_sel_hi:[0,1,0]
	v_add_f32_dpp v73, v73, v73 row_half_mirror row_mask:0xf bank_mask:0xf bound_ctrl:1
	v_fma_mix_f32 v86, v86, v65, v77 op_sel:[0,0,0] op_sel_hi:[0,1,0]
	v_fma_mix_f32 v87, v87, v65, v78 op_sel:[0,1,0] op_sel_hi:[0,1,0]
	v_add_f32_dpp v73, v73, v73 row_mirror row_mask:0xf bank_mask:0xf bound_ctrl:1
	v_fma_mix_f32 v84, -v73, v68, v84 op_sel:[0,0,0] op_sel_hi:[0,1,0]
	v_fma_mix_f32 v85, -v73, v68, v85 op_sel:[0,1,0] op_sel_hi:[0,1,0]
	v_fma_mix_f32 v86, -v73, v69, v86 op_sel:[0,0,0] op_sel_hi:[0,1,0]
	v_fma_mix_f32 v87, -v73, v69, v87 op_sel:[0,1,0] op_sel_hi:[0,1,0]
	v_fma_mix_f32 v64, v84, v54, 0 op_sel:[0,0,0] op_sel_hi:[0,1,0]
	v_fma_mix_f32 v57, v84, v58, 0 op_sel:[0,0,0] op_sel_hi:[0,1,0]
	v_fma_mix_f32 v64, v85, v54, v64 op_sel:[0,1,0] op_sel_hi:[0,1,0]
	v_fma_mix_f32 v57, v85, v58, v57 op_sel:[0,1,0] op_sel_hi:[0,1,0]
	v_fma_mix_f32 v64, v86, v55, v64 op_sel:[0,0,0] op_sel_hi:[0,1,0]
	v_fma_mix_f32 v57, v86, v59, v57 op_sel:[0,0,0] op_sel_hi:[0,1,0]
	v_fma_mix_f32 v64, v87, v55, v64 op_sel:[0,1,0] op_sel_hi:[0,1,0]
	v_fma_mix_f32 v57, v87, v59, v57 op_sel:[0,1,0] op_sel_hi:[0,1,0]
	v_fma_mix_f32 v66, v94, v62, 0 op_sel:[0,0,0] op_sel_hi:[1,1,0]
	v_fma_mix_f32 v67, v94, v62, 0 op_sel:[0,1,0] op_sel_hi:[1,1,0]
	v_add_f32_dpp v64, v64, v64 quad_perm:[1,0,3,2] row_mask:0xf bank_mask:0xf bound_ctrl:1
	v_fma_mix_f32 v68, v94, v63, 0 op_sel:[0,0,0] op_sel_hi:[1,1,0]
	v_fma_mix_f32 v69, v94, v63, 0 op_sel:[0,1,0] op_sel_hi:[1,1,0]
	v_add_f32_dpp v64, v64, v64 quad_perm:[2,3,0,1] row_mask:0xf bank_mask:0xf bound_ctrl:1
	v_fma_mix_f32 v84, v84, v52, v66 op_sel:[0,0,0] op_sel_hi:[0,1,0]
	v_fma_mix_f32 v85, v85, v52, v67 op_sel:[0,1,0] op_sel_hi:[0,1,0]
	v_add_f32_dpp v64, v64, v64 row_half_mirror row_mask:0xf bank_mask:0xf bound_ctrl:1
	v_fma_mix_f32 v86, v86, v53, v68 op_sel:[0,0,0] op_sel_hi:[0,1,0]
	v_fma_mix_f32 v87, v87, v53, v69 op_sel:[0,1,0] op_sel_hi:[0,1,0]
	v_add_f32_dpp v64, v64, v64 row_mirror row_mask:0xf bank_mask:0xf bound_ctrl:1
	v_fma_mix_f32 v84, -v64, v60, v84 op_sel:[0,0,0] op_sel_hi:[0,1,0]
	v_fma_mix_f32 v85, -v64, v60, v85 op_sel:[0,1,0] op_sel_hi:[0,1,0]
	v_fma_mix_f32 v86, -v64, v61, v86 op_sel:[0,0,0] op_sel_hi:[0,1,0]
	v_fma_mix_f32 v87, -v64, v61, v87 op_sel:[0,1,0] op_sel_hi:[0,1,0]
	v_fma_mix_f32 v53, v84, v46, 0 op_sel:[0,0,0] op_sel_hi:[0,1,0]
	v_fma_mix_f32 v59, v84, v40, 0 op_sel:[0,0,0] op_sel_hi:[0,1,0]
	v_fma_mix_f32 v53, v85, v46, v53 op_sel:[0,1,0] op_sel_hi:[0,1,0]
	v_fma_mix_f32 v40, v85, v40, v59 op_sel:[0,1,0] op_sel_hi:[0,1,0]
	v_fma_mix_f32 v53, v86, v47, v53 op_sel:[0,0,0] op_sel_hi:[0,1,0]
	v_fma_mix_f32 v40, v86, v41, v40 op_sel:[0,0,0] op_sel_hi:[0,1,0]
	v_fma_mix_f32 v53, v87, v47, v53 op_sel:[0,1,0] op_sel_hi:[0,1,0]
	v_fma_mix_f32 v40, v87, v41, v40 op_sel:[0,1,0] op_sel_hi:[0,1,0]
	v_fma_mix_f32 v55, v95, v50, 0 op_sel:[0,0,0] op_sel_hi:[1,1,0]
	v_fma_mix_f32 v58, v95, v50, 0 op_sel:[0,1,0] op_sel_hi:[1,1,0]
	v_add_f32_dpp v53, v53, v53 quad_perm:[1,0,3,2] row_mask:0xf bank_mask:0xf bound_ctrl:1
	v_fma_mix_f32 v59, v95, v51, 0 op_sel:[0,0,0] op_sel_hi:[1,1,0]
	v_fma_mix_f32 v60, v95, v51, 0 op_sel:[0,1,0] op_sel_hi:[1,1,0]
	v_add_f32_dpp v53, v53, v53 quad_perm:[2,3,0,1] row_mask:0xf bank_mask:0xf bound_ctrl:1
	v_fma_mix_f32 v84, v84, v44, v55 op_sel:[0,0,0] op_sel_hi:[0,1,0]
	v_fma_mix_f32 v85, v85, v44, v58 op_sel:[0,1,0] op_sel_hi:[0,1,0]
	v_add_f32_dpp v53, v53, v53 row_half_mirror row_mask:0xf bank_mask:0xf bound_ctrl:1
	v_fma_mix_f32 v86, v86, v45, v59 op_sel:[0,0,0] op_sel_hi:[0,1,0]
	v_fma_mix_f32 v87, v87, v45, v60 op_sel:[0,1,0] op_sel_hi:[0,1,0]
	v_add_f32_dpp v53, v53, v53 row_mirror row_mask:0xf bank_mask:0xf bound_ctrl:1
	v_fma_mix_f32 v84, -v53, v48, v84 op_sel:[0,0,0] op_sel_hi:[0,1,0]
	v_fma_mix_f32 v85, -v53, v48, v85 op_sel:[0,1,0] op_sel_hi:[0,1,0]
	v_fma_mix_f32 v86, -v53, v49, v86 op_sel:[0,0,0] op_sel_hi:[0,1,0]
	v_fma_mix_f32 v87, -v53, v49, v87 op_sel:[0,1,0] op_sel_hi:[0,1,0]
	v_fma_mix_f32 v41, v84, v42, 0 op_sel:[0,0,0] op_sel_hi:[0,1,0]
	v_cndmask_b32_e64 v187, v57, v56, s[38:39]
	v_fma_mix_f32 v41, v85, v42, v41 op_sel:[0,1,0] op_sel_hi:[0,1,0]
	v_cndmask_b32_e64 v188, v56, v57, s[38:39]
	v_fma_mix_f32 v41, v86, v43, v41 op_sel:[0,0,0] op_sel_hi:[0,1,0]
	v_fma_mix_f32 v41, v87, v43, v41 op_sel:[0,1,0] op_sel_hi:[0,1,0]
	v_cndmask_b32_e64 v189, v41, v40, s[38:39]
	v_cndmask_b32_e64 v190, v40, v41, s[38:39]
	s_waitcnt lgkmcnt(0)
	v_fma_mix_f32 v98, v84, v6, 0 op_sel:[0,0,0] op_sel_hi:[0,1,0]
	v_fma_mix_f32 v98, v85, v6, v98 op_sel:[0,1,0] op_sel_hi:[0,1,0]
	v_add_f32_dpp v188, v188, v187 quad_perm:[1,0,3,2] row_mask:0xf bank_mask:0xf bound_ctrl:1
	v_add_f32_dpp v189, v190, v189 quad_perm:[1,0,3,2] row_mask:0xf bank_mask:0xf bound_ctrl:1
	v_fma_mix_f32 v98, v86, v7, v98 op_sel:[0,0,0] op_sel_hi:[0,1,0]
	v_fma_mix_f32 v98, v87, v7, v98 op_sel:[0,1,0] op_sel_hi:[0,1,0]
	v_cndmask_b32_e64 v191, v189, v188, s[40:41]
	v_cndmask_b32_e64 v192, v188, v189, s[40:41]
	v_fma_mix_f32 v100, v88, v14, 0 op_sel:[0,0,0] op_sel_hi:[1,1,0]
	v_fma_mix_f32 v101, v88, v14, 0 op_sel:[0,1,0] op_sel_hi:[1,1,0]
	v_add_f32_dpp v192, v192, v191 quad_perm:[2,3,0,1] row_mask:0xf bank_mask:0xf bound_ctrl:1
	v_add_f32_dpp v98, v98, v98 quad_perm:[1,0,3,2] row_mask:0xf bank_mask:0xf bound_ctrl:1
	v_fma_mix_f32 v102, v88, v15, 0 op_sel:[0,0,0] op_sel_hi:[1,1,0]
	v_add_f32_dpp v192, v192, v192 row_ror:4 row_mask:0xf bank_mask:0xf bound_ctrl:1
	v_fma_mix_f32 v103, v88, v15, 0 op_sel:[0,1,0] op_sel_hi:[1,1,0]
	v_add_f32_dpp v98, v98, v98 quad_perm:[2,3,0,1] row_mask:0xf bank_mask:0xf bound_ctrl:1
	v_add_f32_dpp v192, v192, v192 row_ror:8 row_mask:0xf bank_mask:0xf bound_ctrl:1
	v_cvt_f16_f32_e32 v192, v192
	global_store_short v83, v192, s[36:37]
	s_add_u32 s36, s36, s44
	s_addc_u32 s37, s37, s45
	ds_read_b128 v[56:59], v194 offset:48128
	ds_read_b128 v[72:75], v194 offset:46080
	ds_read_b128 v[64:67], v194 offset:46336
	ds_read_b128 v[76:79], v194 offset:47104
	ds_read_b128 v[68:71], v194 offset:47360
	ds_read_b128 v[40:43], v194 offset:48384
	ds_read_b128 v[52:55], v194 offset:46592
	ds_read_b128 v[44:47], v194 offset:46848
	ds_read_b128 v[60:63], v194 offset:47616
	ds_read_b128 v[48:51], v194 offset:47872
	ds_read_u16 v92, v196 offset:48640
	ds_read_u16 v93, v196 offset:48768
	ds_read_u16 v94, v196 offset:48896
	ds_read_u16 v95, v196 offset:49024
	v_fma_mix_f32 v84, v84, v4, v100 op_sel:[0,0,0] op_sel_hi:[0,1,0]
	v_fma_mix_f32 v85, v85, v4, v101 op_sel:[0,1,0] op_sel_hi:[0,1,0]
	v_add_f32_dpp v98, v98, v98 row_half_mirror row_mask:0xf bank_mask:0xf bound_ctrl:1
	v_fma_mix_f32 v86, v86, v5, v102 op_sel:[0,0,0] op_sel_hi:[0,1,0]
	v_fma_mix_f32 v87, v87, v5, v103 op_sel:[0,1,0] op_sel_hi:[0,1,0]
	v_add_f32_dpp v98, v98, v98 row_mirror row_mask:0xf bank_mask:0xf bound_ctrl:1
	v_fma_mix_f32 v84, -v98, v12, v84 op_sel:[0,0,0] op_sel_hi:[0,1,0]
	v_fma_mix_f32 v85, -v98, v12, v85 op_sel:[0,1,0] op_sel_hi:[0,1,0]
	v_fma_mix_f32 v86, -v98, v13, v86 op_sel:[0,0,0] op_sel_hi:[0,1,0]
	v_fma_mix_f32 v87, -v98, v13, v87 op_sel:[0,1,0] op_sel_hi:[0,1,0]
	v_fma_mix_f32 v99, v84, v10, 0 op_sel:[0,0,0] op_sel_hi:[0,1,0]
	v_fma_mix_f32 v96, v84, v0, 0 op_sel:[0,0,0] op_sel_hi:[0,1,0]
	v_fma_mix_f32 v99, v85, v10, v99 op_sel:[0,1,0] op_sel_hi:[0,1,0]
	v_fma_mix_f32 v96, v85, v0, v96 op_sel:[0,1,0] op_sel_hi:[0,1,0]
	v_fma_mix_f32 v99, v86, v11, v99 op_sel:[0,0,0] op_sel_hi:[0,1,0]
	v_fma_mix_f32 v96, v86, v1, v96 op_sel:[0,0,0] op_sel_hi:[0,1,0]
	v_fma_mix_f32 v99, v87, v11, v99 op_sel:[0,1,0] op_sel_hi:[0,1,0]
	v_fma_mix_f32 v96, v87, v1, v96 op_sel:[0,1,0] op_sel_hi:[0,1,0]
	v_fma_mix_f32 v101, v89, v18, 0 op_sel:[0,0,0] op_sel_hi:[1,1,0]
	v_fma_mix_f32 v102, v89, v18, 0 op_sel:[0,1,0] op_sel_hi:[1,1,0]
	v_add_f32_dpp v99, v99, v99 quad_perm:[1,0,3,2] row_mask:0xf bank_mask:0xf bound_ctrl:1
	v_fma_mix_f32 v103, v89, v19, 0 op_sel:[0,0,0] op_sel_hi:[1,1,0]
	v_fma_mix_f32 v104, v89, v19, 0 op_sel:[0,1,0] op_sel_hi:[1,1,0]
	v_add_f32_dpp v99, v99, v99 quad_perm:[2,3,0,1] row_mask:0xf bank_mask:0xf bound_ctrl:1
	v_fma_mix_f32 v84, v84, v8, v101 op_sel:[0,0,0] op_sel_hi:[0,1,0]
	v_fma_mix_f32 v85, v85, v8, v102 op_sel:[0,1,0] op_sel_hi:[0,1,0]
	v_add_f32_dpp v99, v99, v99 row_half_mirror row_mask:0xf bank_mask:0xf bound_ctrl:1
	v_fma_mix_f32 v86, v86, v9, v103 op_sel:[0,0,0] op_sel_hi:[0,1,0]
	v_fma_mix_f32 v87, v87, v9, v104 op_sel:[0,1,0] op_sel_hi:[0,1,0]
	v_add_f32_dpp v99, v99, v99 row_mirror row_mask:0xf bank_mask:0xf bound_ctrl:1
	v_fma_mix_f32 v84, -v99, v16, v84 op_sel:[0,0,0] op_sel_hi:[0,1,0]
	v_fma_mix_f32 v85, -v99, v16, v85 op_sel:[0,1,0] op_sel_hi:[0,1,0]
	v_fma_mix_f32 v86, -v99, v17, v86 op_sel:[0,0,0] op_sel_hi:[0,1,0]
	v_fma_mix_f32 v87, -v99, v17, v87 op_sel:[0,1,0] op_sel_hi:[0,1,0]
	v_fma_mix_f32 v100, v84, v26, 0 op_sel:[0,0,0] op_sel_hi:[0,1,0]
	v_fma_mix_f32 v97, v84, v2, 0 op_sel:[0,0,0] op_sel_hi:[0,1,0]
	v_fma_mix_f32 v100, v85, v26, v100 op_sel:[0,1,0] op_sel_hi:[0,1,0]
	v_fma_mix_f32 v97, v85, v2, v97 op_sel:[0,1,0] op_sel_hi:[0,1,0]
	v_fma_mix_f32 v100, v86, v27, v100 op_sel:[0,0,0] op_sel_hi:[0,1,0]
	v_fma_mix_f32 v97, v86, v3, v97 op_sel:[0,0,0] op_sel_hi:[0,1,0]
	v_fma_mix_f32 v100, v87, v27, v100 op_sel:[0,1,0] op_sel_hi:[0,1,0]
	v_fma_mix_f32 v97, v87, v3, v97 op_sel:[0,1,0] op_sel_hi:[0,1,0]
	v_fma_mix_f32 v102, v90, v34, 0 op_sel:[0,0,0] op_sel_hi:[1,1,0]
	v_fma_mix_f32 v103, v90, v34, 0 op_sel:[0,1,0] op_sel_hi:[1,1,0]
	v_add_f32_dpp v100, v100, v100 quad_perm:[1,0,3,2] row_mask:0xf bank_mask:0xf bound_ctrl:1
	v_fma_mix_f32 v104, v90, v35, 0 op_sel:[0,0,0] op_sel_hi:[1,1,0]
	v_fma_mix_f32 v105, v90, v35, 0 op_sel:[0,1,0] op_sel_hi:[1,1,0]
	v_add_f32_dpp v100, v100, v100 quad_perm:[2,3,0,1] row_mask:0xf bank_mask:0xf bound_ctrl:1
	v_fma_mix_f32 v84, v84, v24, v102 op_sel:[0,0,0] op_sel_hi:[0,1,0]
	v_fma_mix_f32 v85, v85, v24, v103 op_sel:[0,1,0] op_sel_hi:[0,1,0]
	v_add_f32_dpp v100, v100, v100 row_half_mirror row_mask:0xf bank_mask:0xf bound_ctrl:1
	v_fma_mix_f32 v86, v86, v25, v104 op_sel:[0,0,0] op_sel_hi:[0,1,0]
	v_fma_mix_f32 v87, v87, v25, v105 op_sel:[0,1,0] op_sel_hi:[0,1,0]
	v_add_f32_dpp v100, v100, v100 row_mirror row_mask:0xf bank_mask:0xf bound_ctrl:1
	v_fma_mix_f32 v84, -v100, v32, v84 op_sel:[0,0,0] op_sel_hi:[0,1,0]
	v_fma_mix_f32 v85, -v100, v32, v85 op_sel:[0,1,0] op_sel_hi:[0,1,0]
	v_fma_mix_f32 v86, -v100, v33, v86 op_sel:[0,0,0] op_sel_hi:[0,1,0]
	v_fma_mix_f32 v87, -v100, v33, v87 op_sel:[0,1,0] op_sel_hi:[0,1,0]
	v_fma_mix_f32 v101, v84, v30, 0 op_sel:[0,0,0] op_sel_hi:[0,1,0]
	v_fma_mix_f32 v98, v84, v20, 0 op_sel:[0,0,0] op_sel_hi:[0,1,0]
	v_fma_mix_f32 v101, v85, v30, v101 op_sel:[0,1,0] op_sel_hi:[0,1,0]
	v_fma_mix_f32 v98, v85, v20, v98 op_sel:[0,1,0] op_sel_hi:[0,1,0]
	v_fma_mix_f32 v101, v86, v31, v101 op_sel:[0,0,0] op_sel_hi:[0,1,0]
	v_fma_mix_f32 v98, v86, v21, v98 op_sel:[0,0,0] op_sel_hi:[0,1,0]
	v_fma_mix_f32 v101, v87, v31, v101 op_sel:[0,1,0] op_sel_hi:[0,1,0]
	v_fma_mix_f32 v98, v87, v21, v98 op_sel:[0,1,0] op_sel_hi:[0,1,0]
	v_fma_mix_f32 v103, v91, v38, 0 op_sel:[0,0,0] op_sel_hi:[1,1,0]
	v_fma_mix_f32 v104, v91, v38, 0 op_sel:[0,1,0] op_sel_hi:[1,1,0]
	v_add_f32_dpp v101, v101, v101 quad_perm:[1,0,3,2] row_mask:0xf bank_mask:0xf bound_ctrl:1
	v_fma_mix_f32 v105, v91, v39, 0 op_sel:[0,0,0] op_sel_hi:[1,1,0]
	v_fma_mix_f32 v119, v91, v39, 0 op_sel:[0,1,0] op_sel_hi:[1,1,0]
	v_add_f32_dpp v101, v101, v101 quad_perm:[2,3,0,1] row_mask:0xf bank_mask:0xf bound_ctrl:1
	v_fma_mix_f32 v84, v84, v28, v103 op_sel:[0,0,0] op_sel_hi:[0,1,0]
	v_fma_mix_f32 v85, v85, v28, v104 op_sel:[0,1,0] op_sel_hi:[0,1,0]
	v_add_f32_dpp v101, v101, v101 row_half_mirror row_mask:0xf bank_mask:0xf bound_ctrl:1
	v_fma_mix_f32 v86, v86, v29, v105 op_sel:[0,0,0] op_sel_hi:[0,1,0]
	v_fma_mix_f32 v87, v87, v29, v119 op_sel:[0,1,0] op_sel_hi:[0,1,0]
	v_add_f32_dpp v101, v101, v101 row_mirror row_mask:0xf bank_mask:0xf bound_ctrl:1
	v_fma_mix_f32 v84, -v101, v36, v84 op_sel:[0,0,0] op_sel_hi:[0,1,0]
	v_fma_mix_f32 v85, -v101, v36, v85 op_sel:[0,1,0] op_sel_hi:[0,1,0]
	v_fma_mix_f32 v86, -v101, v37, v86 op_sel:[0,0,0] op_sel_hi:[0,1,0]
	v_fma_mix_f32 v87, -v101, v37, v87 op_sel:[0,1,0] op_sel_hi:[0,1,0]
	v_fma_mix_f32 v99, v84, v22, 0 op_sel:[0,0,0] op_sel_hi:[0,1,0]
	v_cndmask_b32_e64 v187, v97, v96, s[38:39]
	v_fma_mix_f32 v99, v85, v22, v99 op_sel:[0,1,0] op_sel_hi:[0,1,0]
	v_cndmask_b32_e64 v188, v96, v97, s[38:39]
	v_fma_mix_f32 v99, v86, v23, v99 op_sel:[0,0,0] op_sel_hi:[0,1,0]
	v_fma_mix_f32 v99, v87, v23, v99 op_sel:[0,1,0] op_sel_hi:[0,1,0]
	v_cndmask_b32_e64 v189, v99, v98, s[38:39]
	v_cndmask_b32_e64 v190, v98, v99, s[38:39]
	s_waitcnt lgkmcnt(0)
	v_fma_mix_f32 v98, v84, v74, 0 op_sel:[0,0,0] op_sel_hi:[0,1,0]
	v_fma_mix_f32 v98, v85, v74, v98 op_sel:[0,1,0] op_sel_hi:[0,1,0]
	v_add_f32_dpp v188, v188, v187 quad_perm:[1,0,3,2] row_mask:0xf bank_mask:0xf bound_ctrl:1
	v_add_f32_dpp v189, v190, v189 quad_perm:[1,0,3,2] row_mask:0xf bank_mask:0xf bound_ctrl:1
	v_fma_mix_f32 v98, v86, v75, v98 op_sel:[0,0,0] op_sel_hi:[0,1,0]
	v_fma_mix_f32 v98, v87, v75, v98 op_sel:[0,1,0] op_sel_hi:[0,1,0]
	v_cndmask_b32_e64 v191, v189, v188, s[40:41]
	v_cndmask_b32_e64 v192, v188, v189, s[40:41]
	v_fma_mix_f32 v100, v92, v78, 0 op_sel:[0,0,0] op_sel_hi:[1,1,0]
	v_fma_mix_f32 v101, v92, v78, 0 op_sel:[0,1,0] op_sel_hi:[1,1,0]
	v_add_f32_dpp v192, v192, v191 quad_perm:[2,3,0,1] row_mask:0xf bank_mask:0xf bound_ctrl:1
	v_add_f32_dpp v98, v98, v98 quad_perm:[1,0,3,2] row_mask:0xf bank_mask:0xf bound_ctrl:1
	v_fma_mix_f32 v102, v92, v79, 0 op_sel:[0,0,0] op_sel_hi:[1,1,0]
	v_add_f32_dpp v192, v192, v192 row_ror:4 row_mask:0xf bank_mask:0xf bound_ctrl:1
	v_fma_mix_f32 v103, v92, v79, 0 op_sel:[0,1,0] op_sel_hi:[1,1,0]
	v_add_f32_dpp v98, v98, v98 quad_perm:[2,3,0,1] row_mask:0xf bank_mask:0xf bound_ctrl:1
	v_add_f32_dpp v192, v192, v192 row_ror:8 row_mask:0xf bank_mask:0xf bound_ctrl:1
	v_cvt_f16_f32_e32 v192, v192
	global_store_short v83, v192, s[36:37]
	s_add_u32 s36, s36, s44
	s_addc_u32 s37, s37, s45
	s_cmp_gt_i32 s35, 17
	s_cbranch_scc0 .Lc_poll_A7
.Lc_ret_A7:
	ds_read_b128 v[0:3], v194 offset:2048
	ds_read_b128 v[4:7], v194 offset:0
	ds_read_b128 v[8:11], v194 offset:256
	ds_read_b128 v[12:15], v194 offset:1024
	ds_read_b128 v[16:19], v194 offset:1280
	ds_read_b128 v[20:23], v194 offset:2304
	ds_read_b128 v[24:27], v194 offset:512
	ds_read_b128 v[28:31], v194 offset:768
	ds_read_b128 v[32:35], v194 offset:1536
	ds_read_b128 v[36:39], v194 offset:1792
	ds_read_u16 v88, v196 offset:2560
	ds_read_u16 v89, v196 offset:2688
	ds_read_u16 v90, v196 offset:2816
	ds_read_u16 v91, v196 offset:2944
	v_fma_mix_f32 v84, v84, v72, v100 op_sel:[0,0,0] op_sel_hi:[0,1,0]
	v_fma_mix_f32 v85, v85, v72, v101 op_sel:[0,1,0] op_sel_hi:[0,1,0]
	v_add_f32_dpp v98, v98, v98 row_half_mirror row_mask:0xf bank_mask:0xf bound_ctrl:1
	v_fma_mix_f32 v86, v86, v73, v102 op_sel:[0,0,0] op_sel_hi:[0,1,0]
	v_fma_mix_f32 v87, v87, v73, v103 op_sel:[0,1,0] op_sel_hi:[0,1,0]
	v_add_f32_dpp v98, v98, v98 row_mirror row_mask:0xf bank_mask:0xf bound_ctrl:1
	v_fma_mix_f32 v84, -v98, v76, v84 op_sel:[0,0,0] op_sel_hi:[0,1,0]
	v_fma_mix_f32 v85, -v98, v76, v85 op_sel:[0,1,0] op_sel_hi:[0,1,0]
	v_fma_mix_f32 v86, -v98, v77, v86 op_sel:[0,0,0] op_sel_hi:[0,1,0]
	v_fma_mix_f32 v87, -v98, v77, v87 op_sel:[0,1,0] op_sel_hi:[0,1,0]
	v_fma_mix_f32 v73, v84, v66, 0 op_sel:[0,0,0] op_sel_hi:[0,1,0]
	v_fma_mix_f32 v97, v84, v56, 0 op_sel:[0,0,0] op_sel_hi:[0,1,0]
	v_fma_mix_f32 v73, v85, v66, v73 op_sel:[0,1,0] op_sel_hi:[0,1,0]
	v_fma_mix_f32 v56, v85, v56, v97 op_sel:[0,1,0] op_sel_hi:[0,1,0]
	v_fma_mix_f32 v73, v86, v67, v73 op_sel:[0,0,0] op_sel_hi:[0,1,0]
	v_fma_mix_f32 v56, v86, v57, v56 op_sel:[0,0,0] op_sel_hi:[0,1,0]
	v_fma_mix_f32 v73, v87, v67, v73 op_sel:[0,1,0] op_sel_hi:[0,1,0]
	v_fma_mix_f32 v56, v87, v57, v56 op_sel:[0,1,0] op_sel_hi:[0,1,0]
	v_fma_mix_f32 v75, v93, v70, 0 op_sel:[0,0,0] op_sel_hi:[1,1,0]
	v_fma_mix_f32 v76, v93, v70, 0 op_sel:[0,1,0] op_sel_hi:[1,1,0]
	v_add_f32_dpp v73, v73, v73 quad_perm:[1,0,3,2] row_mask:0xf bank_mask:0xf bound_ctrl:1
	v_fma_mix_f32 v77, v93, v71, 0 op_sel:[0,0,0] op_sel_hi:[1,1,0]
	v_fma_mix_f32 v78, v93, v71, 0 op_sel:[0,1,0] op_sel_hi:[1,1,0]
	v_add_f32_dpp v73, v73, v73 quad_perm:[2,3,0,1] row_mask:0xf bank_mask:0xf bound_ctrl:1
	v_fma_mix_f32 v84, v84, v64, v75 op_sel:[0,0,0] op_sel_hi:[0,1,0]
	v_fma_mix_f32 v85, v85, v64, v76 op_sel:[0,1,0] op_sel_hi:[0,1,0]
	v_add_f32_dpp v73, v73, v73 row_half_mirror row_mask:0xf bank_mask:0xf bound_ctrl:1
	v_fma_mix_f32 v86, v86, v65, v77 op_sel:[0,0,0] op_sel_hi:[0,1,0]
	v_fma_mix_f32 v87, v87, v65, v78 op_sel:[0,1,0] op_sel_hi:[0,1,0]
	v_add_f32_dpp v73, v73, v73 row_mirror row_mask:0xf bank_mask:0xf bound_ctrl:1
	v_fma_mix_f32 v84, -v73, v68, v84 op_sel:[0,0,0] op_sel_hi:[0,1,0]
	v_fma_mix_f32 v85, -v73, v68, v85 op_sel:[0,1,0] op_sel_hi:[0,1,0]
	v_fma_mix_f32 v86, -v73, v69, v86 op_sel:[0,0,0] op_sel_hi:[0,1,0]
	v_fma_mix_f32 v87, -v73, v69, v87 op_sel:[0,1,0] op_sel_hi:[0,1,0]
	v_fma_mix_f32 v64, v84, v54, 0 op_sel:[0,0,0] op_sel_hi:[0,1,0]
	v_fma_mix_f32 v57, v84, v58, 0 op_sel:[0,0,0] op_sel_hi:[0,1,0]
	v_fma_mix_f32 v64, v85, v54, v64 op_sel:[0,1,0] op_sel_hi:[0,1,0]
	v_fma_mix_f32 v57, v85, v58, v57 op_sel:[0,1,0] op_sel_hi:[0,1,0]
	v_fma_mix_f32 v64, v86, v55, v64 op_sel:[0,0,0] op_sel_hi:[0,1,0]
	v_fma_mix_f32 v57, v86, v59, v57 op_sel:[0,0,0] op_sel_hi:[0,1,0]
	v_fma_mix_f32 v64, v87, v55, v64 op_sel:[0,1,0] op_sel_hi:[0,1,0]
	v_fma_mix_f32 v57, v87, v59, v57 op_sel:[0,1,0] op_sel_hi:[0,1,0]
	v_fma_mix_f32 v66, v94, v62, 0 op_sel:[0,0,0] op_sel_hi:[1,1,0]
	v_fma_mix_f32 v67, v94, v62, 0 op_sel:[0,1,0] op_sel_hi:[1,1,0]
	v_add_f32_dpp v64, v64, v64 quad_perm:[1,0,3,2] row_mask:0xf bank_mask:0xf bound_ctrl:1
	v_fma_mix_f32 v68, v94, v63, 0 op_sel:[0,0,0] op_sel_hi:[1,1,0]
	v_fma_mix_f32 v69, v94, v63, 0 op_sel:[0,1,0] op_sel_hi:[1,1,0]
	v_add_f32_dpp v64, v64, v64 quad_perm:[2,3,0,1] row_mask:0xf bank_mask:0xf bound_ctrl:1
	v_fma_mix_f32 v84, v84, v52, v66 op_sel:[0,0,0] op_sel_hi:[0,1,0]
	v_fma_mix_f32 v85, v85, v52, v67 op_sel:[0,1,0] op_sel_hi:[0,1,0]
	v_add_f32_dpp v64, v64, v64 row_half_mirror row_mask:0xf bank_mask:0xf bound_ctrl:1
	v_fma_mix_f32 v86, v86, v53, v68 op_sel:[0,0,0] op_sel_hi:[0,1,0]
	v_fma_mix_f32 v87, v87, v53, v69 op_sel:[0,1,0] op_sel_hi:[0,1,0]
	v_add_f32_dpp v64, v64, v64 row_mirror row_mask:0xf bank_mask:0xf bound_ctrl:1
	v_fma_mix_f32 v84, -v64, v60, v84 op_sel:[0,0,0] op_sel_hi:[0,1,0]
	v_fma_mix_f32 v85, -v64, v60, v85 op_sel:[0,1,0] op_sel_hi:[0,1,0]
	v_fma_mix_f32 v86, -v64, v61, v86 op_sel:[0,0,0] op_sel_hi:[0,1,0]
	v_fma_mix_f32 v87, -v64, v61, v87 op_sel:[0,1,0] op_sel_hi:[0,1,0]
	v_fma_mix_f32 v53, v84, v46, 0 op_sel:[0,0,0] op_sel_hi:[0,1,0]
	v_fma_mix_f32 v59, v84, v40, 0 op_sel:[0,0,0] op_sel_hi:[0,1,0]
	v_fma_mix_f32 v53, v85, v46, v53 op_sel:[0,1,0] op_sel_hi:[0,1,0]
	v_fma_mix_f32 v40, v85, v40, v59 op_sel:[0,1,0] op_sel_hi:[0,1,0]
	v_fma_mix_f32 v53, v86, v47, v53 op_sel:[0,0,0] op_sel_hi:[0,1,0]
	v_fma_mix_f32 v40, v86, v41, v40 op_sel:[0,0,0] op_sel_hi:[0,1,0]
	v_fma_mix_f32 v53, v87, v47, v53 op_sel:[0,1,0] op_sel_hi:[0,1,0]
	v_fma_mix_f32 v40, v87, v41, v40 op_sel:[0,1,0] op_sel_hi:[0,1,0]
	v_fma_mix_f32 v55, v95, v50, 0 op_sel:[0,0,0] op_sel_hi:[1,1,0]
	v_fma_mix_f32 v58, v95, v50, 0 op_sel:[0,1,0] op_sel_hi:[1,1,0]
	v_add_f32_dpp v53, v53, v53 quad_perm:[1,0,3,2] row_mask:0xf bank_mask:0xf bound_ctrl:1
	v_fma_mix_f32 v59, v95, v51, 0 op_sel:[0,0,0] op_sel_hi:[1,1,0]
	v_fma_mix_f32 v60, v95, v51, 0 op_sel:[0,1,0] op_sel_hi:[1,1,0]
	v_add_f32_dpp v53, v53, v53 quad_perm:[2,3,0,1] row_mask:0xf bank_mask:0xf bound_ctrl:1
	v_fma_mix_f32 v84, v84, v44, v55 op_sel:[0,0,0] op_sel_hi:[0,1,0]
	v_fma_mix_f32 v85, v85, v44, v58 op_sel:[0,1,0] op_sel_hi:[0,1,0]
	v_add_f32_dpp v53, v53, v53 row_half_mirror row_mask:0xf bank_mask:0xf bound_ctrl:1
	v_fma_mix_f32 v86, v86, v45, v59 op_sel:[0,0,0] op_sel_hi:[0,1,0]
	v_fma_mix_f32 v87, v87, v45, v60 op_sel:[0,1,0] op_sel_hi:[0,1,0]
	v_add_f32_dpp v53, v53, v53 row_mirror row_mask:0xf bank_mask:0xf bound_ctrl:1
	v_fma_mix_f32 v84, -v53, v48, v84 op_sel:[0,0,0] op_sel_hi:[0,1,0]
	v_fma_mix_f32 v85, -v53, v48, v85 op_sel:[0,1,0] op_sel_hi:[0,1,0]
	v_fma_mix_f32 v86, -v53, v49, v86 op_sel:[0,0,0] op_sel_hi:[0,1,0]
	v_fma_mix_f32 v87, -v53, v49, v87 op_sel:[0,1,0] op_sel_hi:[0,1,0]
	v_fma_mix_f32 v41, v84, v42, 0 op_sel:[0,0,0] op_sel_hi:[0,1,0]
	v_add_u32_e32 v173, 16, v193
	v_fma_mix_f32 v41, v85, v42, v41 op_sel:[0,1,0] op_sel_hi:[0,1,0]
	ds_write_b32 v172, v173 offset:49216
	v_fma_mix_f32 v41, v86, v43, v41 op_sel:[0,0,0] op_sel_hi:[0,1,0]
	v_cndmask_b32_e64 v187, v57, v56, s[38:39]
	v_fma_mix_f32 v41, v87, v43, v41 op_sel:[0,1,0] op_sel_hi:[0,1,0]
	v_cndmask_b32_e64 v188, v56, v57, s[38:39]
	v_cndmask_b32_e64 v189, v41, v40, s[38:39]
	v_cndmask_b32_e64 v190, v40, v41, s[38:39]
	s_waitcnt lgkmcnt(1)
	v_fma_mix_f32 v98, v84, v6, 0 op_sel:[0,0,0] op_sel_hi:[0,1,0]
	v_fma_mix_f32 v98, v85, v6, v98 op_sel:[0,1,0] op_sel_hi:[0,1,0]
	v_add_f32_dpp v188, v188, v187 quad_perm:[1,0,3,2] row_mask:0xf bank_mask:0xf bound_ctrl:1
	v_add_f32_dpp v189, v190, v189 quad_perm:[1,0,3,2] row_mask:0xf bank_mask:0xf bound_ctrl:1
	v_fma_mix_f32 v98, v86, v7, v98 op_sel:[0,0,0] op_sel_hi:[0,1,0]
	v_fma_mix_f32 v98, v87, v7, v98 op_sel:[0,1,0] op_sel_hi:[0,1,0]
	v_cndmask_b32_e64 v191, v189, v188, s[40:41]
	v_cndmask_b32_e64 v192, v188, v189, s[40:41]
	v_fma_mix_f32 v100, v88, v14, 0 op_sel:[0,0,0] op_sel_hi:[1,1,0]
	v_fma_mix_f32 v101, v88, v14, 0 op_sel:[0,1,0] op_sel_hi:[1,1,0]
	v_add_f32_dpp v192, v192, v191 quad_perm:[2,3,0,1] row_mask:0xf bank_mask:0xf bound_ctrl:1
	v_add_f32_dpp v98, v98, v98 quad_perm:[1,0,3,2] row_mask:0xf bank_mask:0xf bound_ctrl:1
	v_fma_mix_f32 v102, v88, v15, 0 op_sel:[0,0,0] op_sel_hi:[1,1,0]
	v_add_f32_dpp v192, v192, v192 row_ror:4 row_mask:0xf bank_mask:0xf bound_ctrl:1
	v_fma_mix_f32 v103, v88, v15, 0 op_sel:[0,1,0] op_sel_hi:[1,1,0]
	v_add_f32_dpp v98, v98, v98 quad_perm:[2,3,0,1] row_mask:0xf bank_mask:0xf bound_ctrl:1
	v_add_f32_dpp v192, v192, v192 row_ror:8 row_mask:0xf bank_mask:0xf bound_ctrl:1
	v_cvt_f16_f32_e32 v192, v192
	global_store_short v83, v192, s[36:37]
	s_add_u32 s36, s36, s44
	s_addc_u32 s37, s37, s45
	ds_read_b128 v[56:59], v194 offset:5120
	ds_read_b128 v[72:75], v194 offset:3072
	ds_read_b128 v[64:67], v194 offset:3328
	ds_read_b128 v[76:79], v194 offset:4096
	ds_read_b128 v[68:71], v194 offset:4352
	ds_read_b128 v[40:43], v194 offset:5376
	ds_read_b128 v[52:55], v194 offset:3584
	ds_read_b128 v[44:47], v194 offset:3840
	ds_read_b128 v[60:63], v194 offset:4608
	ds_read_b128 v[48:51], v194 offset:4864
	ds_read_u16 v92, v196 offset:5632
	ds_read_u16 v93, v196 offset:5760
	ds_read_u16 v94, v196 offset:5888
	ds_read_u16 v95, v196 offset:6016
	s_add_i32 s33, s33, 16
	s_sub_i32 s35, s35, 16
	v_mov_b32_e32 v193, s33
	s_cmp_eq_u32 s33, 64
	s_cbranch_scc1 .Lc_fix
